# residual-update epilogues (down x2, w_o): the two column-group partial sums of a row are combined before the cross-lane reduction: half the LDS shuffles and half the row-stat atomics
# baseline (speedup 1.0000x reference)
.LBB0_1623:
	s_add_u32 s22, s20, 0x100
	s_addc_u32 s23, s21, 0
	s_add_i32 s46, 0, 0x10000
	ds_read_b128 v[128:131], v216
	ds_read_b128 v[132:135], v216 offset:1024
	ds_read_b128 v[136:139], v216 offset:2048
	ds_read_b128 v[140:143], v216 offset:3072
	s_cmp_eq_u32 s45, 40
	s_cselect_b32 s27, s7, s23
	s_cselect_b32 s26, s6, s22
	s_cselect_b32 s25, s9, s44
	s_cselect_b32 s24, s8, s33
	s_add_i32 m0, s34, 0xc000
	ds_read_b128 v[144:147], v198
	ds_read_b128 v[148:151], v198 offset:1024
	ds_read_b128 v[152:155], v198 offset:2048
	ds_read_b128 v[156:159], v198 offset:3072
	ds_read_b128 v[160:163], v198 offset:4096
	ds_read_b128 v[164:167], v198 offset:5120
	ds_read_b128 v[168:171], v198 offset:6144
	ds_read_b128 v[172:175], v198 offset:7168
	global_load_lds_dwordx4 v214, s[20:21]
	s_add_i32 m0, s34, 0xe000
	s_nop 0
	global_load_lds_dwordx4 v212, s[20:21]
	s_waitcnt lgkmcnt(8)
	s_barrier
	s_waitcnt lgkmcnt(0)
	v_mfma_f32_16x16x32_bf16 v[124:127], v[128:131], v[144:147], v[124:127]
	v_mfma_f32_16x16x32_bf16 v[120:123], v[136:139], v[144:147], v[120:123]
	v_mfma_f32_16x16x32_bf16 v[108:111], v[128:131], v[152:155], v[108:111]
	v_mfma_f32_16x16x32_bf16 v[104:107], v[136:139], v[152:155], v[104:107]
	v_mfma_f32_16x16x32_bf16 v[92:95], v[128:131], v[160:163], v[92:95]
	v_mfma_f32_16x16x32_bf16 v[88:91], v[136:139], v[160:163], v[88:91]
	v_mfma_f32_16x16x32_bf16 v[76:79], v[128:131], v[168:171], v[76:79]
	v_mfma_f32_16x16x32_bf16 v[72:75], v[136:139], v[168:171], v[72:75]
	v_mfma_f32_16x16x32_bf16 v[124:127], v[132:135], v[148:151], v[124:127]
	v_mfma_f32_16x16x32_bf16 v[120:123], v[140:143], v[148:151], v[120:123]
	v_mfma_f32_16x16x32_bf16 v[108:111], v[132:135], v[156:159], v[108:111]
	v_mfma_f32_16x16x32_bf16 v[104:107], v[140:143], v[156:159], v[104:107]
	v_mfma_f32_16x16x32_bf16 v[92:95], v[132:135], v[164:167], v[92:95]
	v_mfma_f32_16x16x32_bf16 v[88:91], v[140:143], v[164:167], v[88:91]
	v_mfma_f32_16x16x32_bf16 v[76:79], v[132:135], v[172:175], v[76:79]
	v_mfma_f32_16x16x32_bf16 v[72:75], v[140:143], v[172:175], v[72:75]
	s_barrier
	s_add_i32 s47, 0, 0x14000
	s_add_i32 s20, s46, s31
	s_mov_b32 m0, s20
	ds_read_b128 v[176:179], v217
	ds_read_b128 v[180:183], v217 offset:1024
	ds_read_b128 v[184:187], v217 offset:2048
	ds_read_b128 v[188:191], v217 offset:3072
	global_load_lds_dwordx4 v192, s[24:25]
	s_add_i32 m0, s20, 0x2000
	s_nop 0
	global_load_lds_dwordx4 v210, s[24:25]
	s_barrier
	s_waitcnt lgkmcnt(0)
	v_mfma_f32_16x16x32_bf16 v[116:119], v[176:179], v[144:147], v[116:119]
	v_mfma_f32_16x16x32_bf16 v[112:115], v[184:187], v[144:147], v[112:115]
	v_mfma_f32_16x16x32_bf16 v[100:103], v[176:179], v[152:155], v[100:103]
	v_mfma_f32_16x16x32_bf16 v[96:99], v[184:187], v[152:155], v[96:99]
	v_mfma_f32_16x16x32_bf16 v[84:87], v[176:179], v[160:163], v[84:87]
	v_mfma_f32_16x16x32_bf16 v[80:83], v[184:187], v[160:163], v[80:83]
	v_mfma_f32_16x16x32_bf16 v[68:71], v[176:179], v[168:171], v[68:71]
	v_mfma_f32_16x16x32_bf16 v[64:67], v[184:187], v[168:171], v[64:67]
	v_mfma_f32_16x16x32_bf16 v[116:119], v[180:183], v[148:151], v[116:119]
	v_mfma_f32_16x16x32_bf16 v[112:115], v[188:191], v[148:151], v[112:115]
	v_mfma_f32_16x16x32_bf16 v[100:103], v[180:183], v[156:159], v[100:103]
	v_mfma_f32_16x16x32_bf16 v[96:99], v[188:191], v[156:159], v[96:99]
	v_mfma_f32_16x16x32_bf16 v[84:87], v[180:183], v[164:167], v[84:87]
	v_mfma_f32_16x16x32_bf16 v[80:83], v[188:191], v[164:167], v[80:83]
	v_mfma_f32_16x16x32_bf16 v[68:71], v[180:183], v[172:175], v[68:71]
	v_mfma_f32_16x16x32_bf16 v[64:67], v[188:191], v[172:175], v[64:67]
	s_mov_b32 m0, s34
	s_add_u32 vcc_lo, s26, 0x80
	s_addc_u32 vcc_hi, s27, 0
	s_barrier
	ds_read_b128 v[144:147], v198 offset:16384
	ds_read_b128 v[148:151], v198 offset:17408
	ds_read_b128 v[152:155], v198 offset:18432
	ds_read_b128 v[156:159], v198 offset:19456
	ds_read_b128 v[160:163], v198 offset:20480
	ds_read_b128 v[164:167], v198 offset:21504
	ds_read_b128 v[168:171], v198 offset:22528
	ds_read_b128 v[172:175], v198 offset:23552
	global_load_lds_dwordx4 v206, s[26:27]
	s_mov_b32 m0, s35
	s_nop 0
	global_load_lds_dwordx4 v208, s[26:27]
	s_barrier
	s_waitcnt lgkmcnt(0)
	v_mfma_f32_16x16x32_bf16 v[60:63], v[128:131], v[144:147], v[60:63]
	v_mfma_f32_16x16x32_bf16 v[56:59], v[136:139], v[144:147], v[56:59]
	v_mfma_f32_16x16x32_bf16 v[44:47], v[128:131], v[152:155], v[44:47]
	v_mfma_f32_16x16x32_bf16 v[40:43], v[136:139], v[152:155], v[40:43]
	v_mfma_f32_16x16x32_bf16 v[28:31], v[128:131], v[160:163], v[28:31]
	v_mfma_f32_16x16x32_bf16 v[24:27], v[136:139], v[160:163], v[24:27]
	v_mfma_f32_16x16x32_bf16 v[12:15], v[128:131], v[168:171], v[12:15]
	v_mfma_f32_16x16x32_bf16 v[8:11], v[136:139], v[168:171], v[8:11]
	v_mfma_f32_16x16x32_bf16 v[60:63], v[132:135], v[148:151], v[60:63]
	v_mfma_f32_16x16x32_bf16 v[56:59], v[140:143], v[148:151], v[56:59]
	v_mfma_f32_16x16x32_bf16 v[44:47], v[132:135], v[156:159], v[44:47]
	v_mfma_f32_16x16x32_bf16 v[40:43], v[140:143], v[156:159], v[40:43]
	v_mfma_f32_16x16x32_bf16 v[28:31], v[132:135], v[164:167], v[28:31]
	v_mfma_f32_16x16x32_bf16 v[24:27], v[140:143], v[164:167], v[24:27]
	v_mfma_f32_16x16x32_bf16 v[12:15], v[132:135], v[172:175], v[12:15]
	v_mfma_f32_16x16x32_bf16 v[8:11], v[140:143], v[172:175], v[8:11]
	s_barrier
	s_add_u32 s20, s24, 0xb0000
	s_addc_u32 s21, s25, 0
	s_add_i32 s46, s47, s31
	s_mov_b32 m0, s46
	s_nop 0
	global_load_lds_dwordx4 v192, s[20:21]
	s_add_i32 m0, s46, 0x2000
	s_nop 0
	global_load_lds_dwordx4 v210, s[20:21]
	s_waitcnt vmcnt(6)
	s_barrier
	v_mfma_f32_16x16x32_bf16 v[52:55], v[176:179], v[144:147], v[52:55]
	v_mfma_f32_16x16x32_bf16 v[48:51], v[184:187], v[144:147], v[48:51]
	v_mfma_f32_16x16x32_bf16 v[36:39], v[176:179], v[152:155], v[36:39]
	v_mfma_f32_16x16x32_bf16 v[32:35], v[184:187], v[152:155], v[32:35]
	v_mfma_f32_16x16x32_bf16 v[20:23], v[176:179], v[160:163], v[20:23]
	v_mfma_f32_16x16x32_bf16 v[16:19], v[184:187], v[160:163], v[16:19]
	v_mfma_f32_16x16x32_bf16 v[4:7], v[176:179], v[168:171], v[4:7]
	v_mfma_f32_16x16x32_bf16 v[0:3], v[184:187], v[168:171], v[0:3]
	v_mfma_f32_16x16x32_bf16 v[52:55], v[180:183], v[148:151], v[52:55]
	v_mfma_f32_16x16x32_bf16 v[48:51], v[188:191], v[148:151], v[48:51]
	v_mfma_f32_16x16x32_bf16 v[36:39], v[180:183], v[156:159], v[36:39]
	v_mfma_f32_16x16x32_bf16 v[32:35], v[188:191], v[156:159], v[32:35]
	v_mfma_f32_16x16x32_bf16 v[20:23], v[180:183], v[164:167], v[20:23]
	v_mfma_f32_16x16x32_bf16 v[16:19], v[188:191], v[164:167], v[16:19]
	v_mfma_f32_16x16x32_bf16 v[4:7], v[180:183], v[172:175], v[4:7]
	v_mfma_f32_16x16x32_bf16 v[0:3], v[188:191], v[172:175], v[0:3]
	s_add_i32 s46, 0, 0x18000
	s_barrier
	ds_read_b128 v[128:131], v218
	ds_read_b128 v[132:135], v218 offset:1024
	ds_read_b128 v[136:139], v218 offset:2048
	ds_read_b128 v[140:143], v218 offset:3072
	s_add_u32 s20, s26, 0xb0000
	s_addc_u32 s21, s27, 0
	s_mov_b32 m0, s36
	ds_read_b128 v[144:147], v198 offset:32768
	ds_read_b128 v[148:151], v198 offset:33792
	ds_read_b128 v[152:155], v198 offset:34816
	ds_read_b128 v[156:159], v198 offset:35840
	ds_read_b128 v[160:163], v198 offset:36864
	ds_read_b128 v[164:167], v198 offset:37888
	ds_read_b128 v[168:171], v198 offset:38912
	ds_read_b128 v[172:175], v198 offset:39936
	global_load_lds_dwordx4 v206, s[20:21]
	s_mov_b32 m0, s37
	s_nop 0
	global_load_lds_dwordx4 v208, s[20:21]
	s_waitcnt lgkmcnt(8)
	s_barrier
	s_waitcnt lgkmcnt(0)
	v_mfma_f32_16x16x32_bf16 v[124:127], v[128:131], v[144:147], v[124:127]
	v_mfma_f32_16x16x32_bf16 v[120:123], v[136:139], v[144:147], v[120:123]
	v_mfma_f32_16x16x32_bf16 v[108:111], v[128:131], v[152:155], v[108:111]
	v_mfma_f32_16x16x32_bf16 v[104:107], v[136:139], v[152:155], v[104:107]
	v_mfma_f32_16x16x32_bf16 v[92:95], v[128:131], v[160:163], v[92:95]
	v_mfma_f32_16x16x32_bf16 v[88:91], v[136:139], v[160:163], v[88:91]
	v_mfma_f32_16x16x32_bf16 v[76:79], v[128:131], v[168:171], v[76:79]
	v_mfma_f32_16x16x32_bf16 v[72:75], v[136:139], v[168:171], v[72:75]
	v_mfma_f32_16x16x32_bf16 v[124:127], v[132:135], v[148:151], v[124:127]
	v_mfma_f32_16x16x32_bf16 v[120:123], v[140:143], v[148:151], v[120:123]
	v_mfma_f32_16x16x32_bf16 v[108:111], v[132:135], v[156:159], v[108:111]
	v_mfma_f32_16x16x32_bf16 v[104:107], v[140:143], v[156:159], v[104:107]
	v_mfma_f32_16x16x32_bf16 v[92:95], v[132:135], v[164:167], v[92:95]
	v_mfma_f32_16x16x32_bf16 v[88:91], v[140:143], v[164:167], v[88:91]
	v_mfma_f32_16x16x32_bf16 v[76:79], v[132:135], v[172:175], v[76:79]
	v_mfma_f32_16x16x32_bf16 v[72:75], v[140:143], v[172:175], v[72:75]
	s_barrier
	s_add_i32 s26, 0, 0x1c000
	s_add_i32 s20, s46, s31
	s_add_u32 s100, s24, 0x80
	s_addc_u32 s101, s25, 0
	s_mov_b32 m0, s20
	ds_read_b128 v[176:179], v219
	ds_read_b128 v[180:183], v219 offset:1024
	ds_read_b128 v[184:187], v219 offset:2048
	ds_read_b128 v[188:191], v219 offset:3072
	global_load_lds_dwordx4 v192, s[100:101]
	s_add_i32 m0, s20, 0x2000
	s_nop 0
	global_load_lds_dwordx4 v210, s[100:101]
	s_barrier
	s_waitcnt lgkmcnt(0)
	v_mfma_f32_16x16x32_bf16 v[116:119], v[176:179], v[144:147], v[116:119]
	v_mfma_f32_16x16x32_bf16 v[112:115], v[184:187], v[144:147], v[112:115]
	v_mfma_f32_16x16x32_bf16 v[100:103], v[176:179], v[152:155], v[100:103]
	v_mfma_f32_16x16x32_bf16 v[96:99], v[184:187], v[152:155], v[96:99]
	v_mfma_f32_16x16x32_bf16 v[84:87], v[176:179], v[160:163], v[84:87]
	v_mfma_f32_16x16x32_bf16 v[80:83], v[184:187], v[160:163], v[80:83]
	v_mfma_f32_16x16x32_bf16 v[68:71], v[176:179], v[168:171], v[68:71]
	v_mfma_f32_16x16x32_bf16 v[64:67], v[184:187], v[168:171], v[64:67]
	v_mfma_f32_16x16x32_bf16 v[116:119], v[180:183], v[148:151], v[116:119]
	v_mfma_f32_16x16x32_bf16 v[112:115], v[188:191], v[148:151], v[112:115]
	v_mfma_f32_16x16x32_bf16 v[100:103], v[180:183], v[156:159], v[100:103]
	v_mfma_f32_16x16x32_bf16 v[96:99], v[188:191], v[156:159], v[96:99]
	v_mfma_f32_16x16x32_bf16 v[84:87], v[180:183], v[164:167], v[84:87]
	v_mfma_f32_16x16x32_bf16 v[80:83], v[188:191], v[164:167], v[80:83]
	v_mfma_f32_16x16x32_bf16 v[68:71], v[180:183], v[172:175], v[68:71]
	v_mfma_f32_16x16x32_bf16 v[64:67], v[188:191], v[172:175], v[64:67]
	s_mov_b32 m0, s38
	s_barrier
	ds_read_b128 v[144:147], v198 offset:49152
	ds_read_b128 v[148:151], v198 offset:50176
	ds_read_b128 v[152:155], v198 offset:51200
	ds_read_b128 v[156:159], v198 offset:52224
	ds_read_b128 v[160:163], v198 offset:53248
	ds_read_b128 v[164:167], v198 offset:54272
	ds_read_b128 v[168:171], v198 offset:55296
	ds_read_b128 v[172:175], v198 offset:56320
	global_load_lds_dwordx4 v206, vcc
	s_mov_b32 m0, s39
	s_nop 0
	global_load_lds_dwordx4 v208, vcc
	s_barrier
	s_waitcnt lgkmcnt(0)
	v_mfma_f32_16x16x32_bf16 v[60:63], v[128:131], v[144:147], v[60:63]
	v_mfma_f32_16x16x32_bf16 v[56:59], v[136:139], v[144:147], v[56:59]
	v_mfma_f32_16x16x32_bf16 v[44:47], v[128:131], v[152:155], v[44:47]
	v_mfma_f32_16x16x32_bf16 v[40:43], v[136:139], v[152:155], v[40:43]
	v_mfma_f32_16x16x32_bf16 v[28:31], v[128:131], v[160:163], v[28:31]
	v_mfma_f32_16x16x32_bf16 v[24:27], v[136:139], v[160:163], v[24:27]
	v_mfma_f32_16x16x32_bf16 v[12:15], v[128:131], v[168:171], v[12:15]
	v_mfma_f32_16x16x32_bf16 v[8:11], v[136:139], v[168:171], v[8:11]
	v_mfma_f32_16x16x32_bf16 v[60:63], v[132:135], v[148:151], v[60:63]
	v_mfma_f32_16x16x32_bf16 v[56:59], v[140:143], v[148:151], v[56:59]
	v_mfma_f32_16x16x32_bf16 v[44:47], v[132:135], v[156:159], v[44:47]
	v_mfma_f32_16x16x32_bf16 v[40:43], v[140:143], v[156:159], v[40:43]
	v_mfma_f32_16x16x32_bf16 v[28:31], v[132:135], v[164:167], v[28:31]
	v_mfma_f32_16x16x32_bf16 v[24:27], v[140:143], v[164:167], v[24:27]
	v_mfma_f32_16x16x32_bf16 v[12:15], v[132:135], v[172:175], v[12:15]
	v_mfma_f32_16x16x32_bf16 v[8:11], v[140:143], v[172:175], v[8:11]
	s_barrier
	s_add_u32 s20, s24, 0xb0080
	s_addc_u32 s21, s25, 0
	s_add_i32 s24, s26, s31
	s_mov_b32 m0, s24
	s_nop 0
	global_load_lds_dwordx4 v192, s[20:21]
	s_add_i32 m0, s24, 0x2000
	s_nop 0
	global_load_lds_dwordx4 v210, s[20:21]
	s_waitcnt vmcnt(6)
	s_barrier
	v_mfma_f32_16x16x32_bf16 v[52:55], v[176:179], v[144:147], v[52:55]
	v_mfma_f32_16x16x32_bf16 v[48:51], v[184:187], v[144:147], v[48:51]
	v_mfma_f32_16x16x32_bf16 v[36:39], v[176:179], v[152:155], v[36:39]
	v_mfma_f32_16x16x32_bf16 v[32:35], v[184:187], v[152:155], v[32:35]
	v_mfma_f32_16x16x32_bf16 v[20:23], v[176:179], v[160:163], v[20:23]
	v_mfma_f32_16x16x32_bf16 v[16:19], v[184:187], v[160:163], v[16:19]
	v_mfma_f32_16x16x32_bf16 v[4:7], v[176:179], v[168:171], v[4:7]
	v_mfma_f32_16x16x32_bf16 v[0:3], v[184:187], v[168:171], v[0:3]
	v_mfma_f32_16x16x32_bf16 v[52:55], v[180:183], v[148:151], v[52:55]
	v_mfma_f32_16x16x32_bf16 v[48:51], v[188:191], v[148:151], v[48:51]
	v_mfma_f32_16x16x32_bf16 v[36:39], v[180:183], v[156:159], v[36:39]
	v_mfma_f32_16x16x32_bf16 v[32:35], v[188:191], v[156:159], v[32:35]
	v_mfma_f32_16x16x32_bf16 v[20:23], v[180:183], v[164:167], v[20:23]
	v_mfma_f32_16x16x32_bf16 v[16:19], v[188:191], v[164:167], v[16:19]
	v_mfma_f32_16x16x32_bf16 v[4:7], v[180:183], v[172:175], v[4:7]
	v_mfma_f32_16x16x32_bf16 v[0:3], v[188:191], v[172:175], v[0:3]
	s_add_i32 s45, s45, 2
	s_add_u32 s33, s33, 0x100
	s_addc_u32 s44, s44, 0
	s_cmp_gt_u32 s45, 41
	s_mov_b64 s[20:21], s[22:23]
	s_barrier
	s_cbranch_scc0 .LBB0_1623
	v_mov_b32_e32 v128, v252
	s_lshl_b32 s1, s1, 8
	v_readfirstlane_b32 s20, v128
	s_ashr_i32 s21, s20, 2
	s_andn2_b32 s21, s21, 63
	s_add_i32 s21, s21, s1
	s_lshr_b32 s1, s20, 1
	s_and_b32 s1, s1, 0x60
	s_lshl_b32 s0, s0, 8
	v_and_or_b32 v244, v128, 15, s21
	v_lshrrev_b32_e32 v128, 1, v128
	s_or_b32 s0, s1, s0
	v_and_b32_e32 v129, 64, v195
	v_and_or_b32 v216, v128, 24, s0
	v_xor_b32_e32 v128, 16, v195
	v_add_u32_e32 v129, 64, v129
	v_cmp_lt_i32_e32 vcc, v128, v129
	v_ashrrev_i32_e32 v245, 31, v244
	v_lshlrev_b64 v[220:221], 10, v[244:245]
	v_cndmask_b32_e32 v128, v195, v128, vcc
	v_lshlrev_b32_e32 v200, 2, v128
	v_xor_b32_e32 v128, 32, v195
	v_cmp_lt_i32_e32 vcc, v128, v129
	v_ashrrev_i32_e32 v217, 31, v216
	v_or_b32_e32 v218, 0x80, v216
	v_cndmask_b32_e32 v128, v195, v128, vcc
	v_lshlrev_b32_e32 v199, 2, v128
	v_lshl_add_u64 v[128:129], v[220:221], 0, v[216:217]
	v_lshlrev_b64 v[128:129], 1, v[128:129]
	v_lshl_add_u64 v[240:241], s[18:19], 0, v[128:129]
	v_lshl_add_u64 v[246:247], s[10:11], 0, v[128:129]
	global_load_dwordx4 v[188:191], v[240:241], off
	global_load_dwordx4 v[180:183], v[240:241], off offset:256
	global_load_dwordx4 v[184:187], v[246:247], off
	v_ashrrev_i32_e32 v219, 31, v218
	v_lshl_add_u64 v[128:129], v[220:221], 0, v[218:219]
	v_lshl_add_u64 v[242:243], v[128:129], 1, s[10:11]
	v_or_b32_e32 v128, 16, v244
	v_ashrrev_i32_e32 v129, 31, v128
	v_lshlrev_b64 v[128:129], 10, v[128:129]
	v_lshl_add_u64 v[130:131], v[128:129], 0, v[216:217]
	v_lshl_add_u64 v[128:129], v[128:129], 0, v[218:219]
	v_lshl_add_u64 v[236:237], v[128:129], 1, s[10:11]
	v_or_b32_e32 v128, 32, v244
	v_ashrrev_i32_e32 v129, 31, v128
	v_lshlrev_b64 v[130:131], 1, v[130:131]
	v_lshlrev_b64 v[128:129], 10, v[128:129]
	v_lshl_add_u64 v[234:235], s[18:19], 0, v[130:131]
	v_lshl_add_u64 v[238:239], s[10:11], 0, v[130:131]
	v_lshl_add_u64 v[130:131], v[128:129], 0, v[216:217]
	v_lshl_add_u64 v[128:129], v[128:129], 0, v[218:219]
	v_lshl_add_u64 v[230:231], v[128:129], 1, s[10:11]
	v_or_b32_e32 v128, 48, v244
	v_ashrrev_i32_e32 v129, 31, v128
	v_lshlrev_b64 v[130:131], 1, v[130:131]
	v_lshlrev_b64 v[128:129], 10, v[128:129]
	v_lshl_add_u64 v[226:227], s[18:19], 0, v[130:131]
	v_lshl_add_u64 v[232:233], s[10:11], 0, v[130:131]
	v_lshl_add_u64 v[130:131], v[128:129], 0, v[216:217]
	v_lshlrev_b64 v[130:131], 1, v[130:131]
	v_lshl_add_u64 v[132:133], v[128:129], 0, v[218:219]
	v_lshl_add_u64 v[222:223], s[18:19], 0, v[130:131]
	v_lshl_add_u64 v[228:229], s[10:11], 0, v[130:131]
	v_lshl_add_u64 v[224:225], v[132:133], 1, s[10:11]
	global_load_dwordx4 v[176:179], v[242:243], off
	global_load_dwordx4 v[172:175], v[234:235], off
	global_load_dwordx4 v[164:167], v[234:235], off offset:256
	global_load_dwordx4 v[168:171], v[238:239], off
	global_load_dwordx4 v[160:163], v[236:237], off
	global_load_dwordx4 v[156:159], v[226:227], off
	global_load_dwordx4 v[132:135], v[224:225], off
	global_load_dwordx4 v[152:155], v[232:233], off
	global_load_dwordx4 v[144:147], v[230:231], off
	global_load_dwordx4 v[148:151], v[226:227], off offset:256
	global_load_dwordx4 v[136:139], v[228:229], off
	global_load_dwordx4 v[140:143], v[222:223], off
	global_load_dwordx4 v[128:131], v[222:223], off offset:256
	v_cmp_gt_u32_e32 vcc, 16, v195
	s_waitcnt vmcnt(0)
	v_lshlrev_b32_e32 v248, 16, v188
	v_and_b32_e32 v249, 0xffff0000, v188
	v_lshlrev_b32_e32 v250, 16, v184
	v_and_b32_e32 v251, 0xffff0000, v184
	v_lshlrev_b32_e32 v188, 16, v189
	v_and_b32_e32 v189, 0xffff0000, v189
	v_lshlrev_b32_e32 v184, 16, v185
	v_and_b32_e32 v185, 0xffff0000, v185
	v_pk_add_f32 v[248:249], v[248:249], v[250:251]
	v_pk_add_f32 v[184:185], v[188:189], v[184:185]
	v_pk_fma_f32 v[188:189], v[124:125], 0.5, v[248:249] op_sel_hi:[1,0,1]
	v_pk_fma_f32 v[184:185], v[126:127], 0.5, v[184:185] op_sel_hi:[1,0,1]
	v_lshlrev_b32_e32 v124, 16, v190
	v_and_b32_e32 v125, 0xffff0000, v190
	v_lshlrev_b32_e32 v126, 16, v186
	v_and_b32_e32 v127, 0xffff0000, v186
	v_pk_add_f32 v[124:125], v[124:125], v[126:127]
	v_lshlrev_b32_e32 v126, 16, v191
	v_and_b32_e32 v127, 0xffff0000, v191
	v_lshlrev_b32_e32 v186, 16, v187
	v_and_b32_e32 v187, 0xffff0000, v187
	v_pk_add_f32 v[126:127], v[126:127], v[186:187]
	v_pk_fma_f32 v[190:191], v[120:121], 0.5, v[124:125] op_sel_hi:[1,0,1]
	v_cvt_pk_bf16_f32 v120, v188, v189
	v_pk_fma_f32 v[186:187], v[122:123], 0.5, v[126:127] op_sel_hi:[1,0,1]
	v_and_b32_e32 v123, 0xffff0000, v120
	v_lshlrev_b32_e32 v122, 16, v120
	v_pk_add_f32 v[122:123], v[188:189], v[122:123] neg_lo:[0,1] neg_hi:[0,1]
	v_cvt_pk_bf16_f32 v121, v184, v185
	v_cvt_pk_bf16_f32 v124, v122, v123
	v_and_b32_e32 v123, 0xffff0000, v121
	v_lshlrev_b32_e32 v122, 16, v121
	v_pk_add_f32 v[122:123], v[184:185], v[122:123] neg_lo:[0,1] neg_hi:[0,1]
	s_nop 0
	v_cvt_pk_bf16_f32 v125, v122, v123
	v_cvt_pk_bf16_f32 v122, v190, v191
	v_cvt_pk_bf16_f32 v123, v186, v187
	v_and_b32_e32 v127, 0xffff0000, v122
	v_lshlrev_b32_e32 v126, 16, v122
	v_and_b32_e32 v249, 0xffff0000, v123
	v_lshlrev_b32_e32 v248, 16, v123
	v_pk_add_f32 v[126:127], v[190:191], v[126:127] neg_lo:[0,1] neg_hi:[0,1]
	v_pk_add_f32 v[248:249], v[186:187], v[248:249] neg_lo:[0,1] neg_hi:[0,1]
	v_cvt_pk_bf16_f32 v126, v126, v127
	v_cvt_pk_bf16_f32 v127, v248, v249
	global_store_dwordx4 v[240:241], v[120:123], off
	global_store_dwordx4 v[246:247], v[124:127], off
	s_nop 0
	v_pk_mul_f32 v[122:123], v[190:191], v[190:191]
	v_pk_mul_f32 v[120:121], v[186:187], v[186:187]
	v_pk_fma_f32 v[122:123], v[188:189], v[188:189], v[122:123]
	v_pk_fma_f32 v[120:121], v[184:185], v[184:185], v[120:121]
	v_add_f32_e32 v122, v122, v123
	v_add_f32_e32 v120, v120, v122
	v_add_f32_e32 v120, v121, v120
	v_mov_b32_e32 v201, v120
	v_lshl_add_u64 v[184:185], v[244:245], 2, s[14:15]
	s_waitcnt lgkmcnt(0)
.LBB0_1626:
	v_lshlrev_b32_e32 v120, 16, v180
	s_waitcnt lgkmcnt(0)
	v_and_b32_e32 v121, 0xffff0000, v180
	v_lshlrev_b32_e32 v122, 16, v176
	v_and_b32_e32 v123, 0xffff0000, v176
	v_pk_add_f32 v[120:121], v[120:121], v[122:123]
	v_lshlrev_b32_e32 v122, 16, v181
	v_and_b32_e32 v123, 0xffff0000, v181
	v_lshlrev_b32_e32 v124, 16, v177
	v_and_b32_e32 v125, 0xffff0000, v177
	v_pk_add_f32 v[122:123], v[122:123], v[124:125]
	v_pk_fma_f32 v[120:121], v[116:117], 0.5, v[120:121] op_sel_hi:[1,0,1]
	v_pk_fma_f32 v[122:123], v[118:119], 0.5, v[122:123] op_sel_hi:[1,0,1]
	v_lshlrev_b32_e32 v116, 16, v182
	v_and_b32_e32 v117, 0xffff0000, v182
	v_lshlrev_b32_e32 v118, 16, v178
	v_and_b32_e32 v119, 0xffff0000, v178
	v_pk_add_f32 v[116:117], v[116:117], v[118:119]
	v_lshlrev_b32_e32 v118, 16, v183
	v_and_b32_e32 v119, 0xffff0000, v183
	v_lshlrev_b32_e32 v124, 16, v179
	v_and_b32_e32 v125, 0xffff0000, v179
	v_pk_add_f32 v[118:119], v[118:119], v[124:125]
	v_pk_fma_f32 v[112:113], v[112:113], 0.5, v[116:117] op_sel_hi:[1,0,1]
	v_pk_fma_f32 v[124:125], v[114:115], 0.5, v[118:119] op_sel_hi:[1,0,1]
	v_cvt_pk_bf16_f32 v114, v120, v121
	v_and_b32_e32 v117, 0xffff0000, v114
	v_lshlrev_b32_e32 v116, 16, v114
	v_pk_add_f32 v[116:117], v[120:121], v[116:117] neg_lo:[0,1] neg_hi:[0,1]
	v_cvt_pk_bf16_f32 v115, v122, v123
	v_cvt_pk_bf16_f32 v118, v116, v117
	v_and_b32_e32 v117, 0xffff0000, v115
	v_lshlrev_b32_e32 v116, 16, v115
	v_pk_add_f32 v[116:117], v[122:123], v[116:117] neg_lo:[0,1] neg_hi:[0,1]
	v_pk_mul_f32 v[176:177], v[124:125], v[124:125]
	v_cvt_pk_bf16_f32 v119, v116, v117
	v_cvt_pk_bf16_f32 v116, v112, v113
	v_and_b32_e32 v127, 0xffff0000, v116
	v_lshlrev_b32_e32 v126, 16, v116
	v_pk_add_f32 v[126:127], v[112:113], v[126:127] neg_lo:[0,1] neg_hi:[0,1]
	v_pk_mul_f32 v[112:113], v[112:113], v[112:113]
	v_pk_fma_f32 v[122:123], v[122:123], v[122:123], v[176:177]
	v_pk_fma_f32 v[112:113], v[120:121], v[120:121], v[112:113]
	v_cvt_pk_bf16_f32 v117, v124, v125
	v_add_f32_e32 v112, v112, v113
	v_add_f32_e32 v112, v122, v112
	v_add_f32_e32 v112, v123, v112
	v_add_f32_e32 v112, v201, v112
	ds_bpermute_b32 v113, v200, v112
	v_and_b32_e32 v123, 0xffff0000, v117
	v_lshlrev_b32_e32 v122, 16, v117
	v_pk_add_f32 v[122:123], v[124:125], v[122:123] neg_lo:[0,1] neg_hi:[0,1]
	v_cvt_pk_bf16_f32 v120, v126, v127
	s_waitcnt lgkmcnt(0)
	v_add_f32_e32 v112, v112, v113
	ds_bpermute_b32 v113, v199, v112
	v_cvt_pk_bf16_f32 v121, v122, v123
	global_store_dwordx4 v[240:241], v[114:117], off offset:256
	global_store_dwordx4 v[242:243], v[118:121], off
	s_and_saveexec_b64 s[20:21], vcc
	s_cbranch_execz .LBB0_1628
	s_waitcnt lgkmcnt(0)
	v_add_f32_e32 v112, v112, v113
	global_atomic_add_f32 v[184:185], v112, off
.LBB0_1628:
	s_or_b64 exec, exec, s[20:21]
	v_lshlrev_b32_e32 v112, 16, v172
	s_waitcnt lgkmcnt(0)
	v_and_b32_e32 v113, 0xffff0000, v172
	v_lshlrev_b32_e32 v114, 16, v168
	v_and_b32_e32 v115, 0xffff0000, v168
	v_pk_add_f32 v[112:113], v[112:113], v[114:115]
	v_lshlrev_b32_e32 v114, 16, v173
	v_and_b32_e32 v115, 0xffff0000, v173
	v_lshlrev_b32_e32 v116, 16, v169
	v_and_b32_e32 v117, 0xffff0000, v169
	v_pk_add_f32 v[114:115], v[114:115], v[116:117]
	v_pk_fma_f32 v[112:113], v[108:109], 0.5, v[112:113] op_sel_hi:[1,0,1]
	v_pk_fma_f32 v[114:115], v[110:111], 0.5, v[114:115] op_sel_hi:[1,0,1]
	v_lshlrev_b32_e32 v108, 16, v174
	v_and_b32_e32 v109, 0xffff0000, v174
	v_lshlrev_b32_e32 v110, 16, v170
	v_and_b32_e32 v111, 0xffff0000, v170
	v_pk_add_f32 v[108:109], v[108:109], v[110:111]
	v_lshlrev_b32_e32 v110, 16, v175
	v_and_b32_e32 v111, 0xffff0000, v175
	v_lshlrev_b32_e32 v116, 16, v171
	v_and_b32_e32 v117, 0xffff0000, v171
	v_pk_add_f32 v[110:111], v[110:111], v[116:117]
	v_pk_fma_f32 v[104:105], v[104:105], 0.5, v[108:109] op_sel_hi:[1,0,1]
	v_pk_fma_f32 v[116:117], v[106:107], 0.5, v[110:111] op_sel_hi:[1,0,1]
	v_cvt_pk_bf16_f32 v106, v112, v113
	v_and_b32_e32 v109, 0xffff0000, v106
	v_lshlrev_b32_e32 v108, 16, v106
	v_pk_add_f32 v[108:109], v[112:113], v[108:109] neg_lo:[0,1] neg_hi:[0,1]
	v_cvt_pk_bf16_f32 v107, v114, v115
	v_cvt_pk_bf16_f32 v110, v108, v109
	v_and_b32_e32 v109, 0xffff0000, v107
	v_lshlrev_b32_e32 v108, 16, v107
	v_pk_add_f32 v[108:109], v[114:115], v[108:109] neg_lo:[0,1] neg_hi:[0,1]
	v_pk_mul_f32 v[120:121], v[116:117], v[116:117]
	v_cvt_pk_bf16_f32 v111, v108, v109
	v_cvt_pk_bf16_f32 v108, v104, v105
	v_and_b32_e32 v119, 0xffff0000, v108
	v_lshlrev_b32_e32 v118, 16, v108
	v_pk_add_f32 v[118:119], v[104:105], v[118:119] neg_lo:[0,1] neg_hi:[0,1]
	v_pk_mul_f32 v[104:105], v[104:105], v[104:105]
	v_pk_fma_f32 v[114:115], v[114:115], v[114:115], v[120:121]
	v_pk_fma_f32 v[104:105], v[112:113], v[112:113], v[104:105]
	v_cvt_pk_bf16_f32 v109, v116, v117
	v_add_f32_e32 v104, v104, v105
	v_add_f32_e32 v104, v114, v104
	v_add_f32_e32 v104, v115, v104
	v_mov_b32_e32 v201, v104
	v_and_b32_e32 v115, 0xffff0000, v109
	v_lshlrev_b32_e32 v114, 16, v109
	v_pk_add_f32 v[114:115], v[116:117], v[114:115] neg_lo:[0,1] neg_hi:[0,1]
	v_cvt_pk_bf16_f32 v112, v118, v119
	s_waitcnt lgkmcnt(0)
	v_cvt_pk_bf16_f32 v113, v114, v115
	global_store_dwordx4 v[234:235], v[106:109], off
	global_store_dwordx4 v[238:239], v[110:113], off
.LBB0_1630:
	v_lshlrev_b32_e32 v104, 16, v164
	s_waitcnt lgkmcnt(0)
	v_and_b32_e32 v105, 0xffff0000, v164
	v_lshlrev_b32_e32 v106, 16, v160
	v_and_b32_e32 v107, 0xffff0000, v160
	v_pk_add_f32 v[104:105], v[104:105], v[106:107]
	v_lshlrev_b32_e32 v106, 16, v165
	v_and_b32_e32 v107, 0xffff0000, v165
	v_lshlrev_b32_e32 v108, 16, v161
	v_and_b32_e32 v109, 0xffff0000, v161
	v_pk_add_f32 v[106:107], v[106:107], v[108:109]
	v_pk_fma_f32 v[104:105], v[100:101], 0.5, v[104:105] op_sel_hi:[1,0,1]
	v_pk_fma_f32 v[106:107], v[102:103], 0.5, v[106:107] op_sel_hi:[1,0,1]
	v_lshlrev_b32_e32 v100, 16, v166
	v_and_b32_e32 v101, 0xffff0000, v166
	v_lshlrev_b32_e32 v102, 16, v162
	v_and_b32_e32 v103, 0xffff0000, v162
	v_pk_add_f32 v[100:101], v[100:101], v[102:103]
	v_lshlrev_b32_e32 v102, 16, v167
	v_and_b32_e32 v103, 0xffff0000, v167
	v_lshlrev_b32_e32 v108, 16, v163
	v_and_b32_e32 v109, 0xffff0000, v163
	v_pk_add_f32 v[102:103], v[102:103], v[108:109]
	v_pk_fma_f32 v[96:97], v[96:97], 0.5, v[100:101] op_sel_hi:[1,0,1]
	v_pk_fma_f32 v[108:109], v[98:99], 0.5, v[102:103] op_sel_hi:[1,0,1]
	v_cvt_pk_bf16_f32 v98, v104, v105
	v_and_b32_e32 v101, 0xffff0000, v98
	v_lshlrev_b32_e32 v100, 16, v98
	v_pk_add_f32 v[100:101], v[104:105], v[100:101] neg_lo:[0,1] neg_hi:[0,1]
	v_cvt_pk_bf16_f32 v99, v106, v107
	v_cvt_pk_bf16_f32 v102, v100, v101
	v_and_b32_e32 v101, 0xffff0000, v99
	v_lshlrev_b32_e32 v100, 16, v99
	v_pk_add_f32 v[100:101], v[106:107], v[100:101] neg_lo:[0,1] neg_hi:[0,1]
	v_pk_mul_f32 v[112:113], v[108:109], v[108:109]
	v_cvt_pk_bf16_f32 v103, v100, v101
	v_cvt_pk_bf16_f32 v100, v96, v97
	v_and_b32_e32 v111, 0xffff0000, v100
	v_lshlrev_b32_e32 v110, 16, v100
	v_pk_add_f32 v[110:111], v[96:97], v[110:111] neg_lo:[0,1] neg_hi:[0,1]
	v_pk_mul_f32 v[96:97], v[96:97], v[96:97]
	v_pk_fma_f32 v[106:107], v[106:107], v[106:107], v[112:113]
	v_pk_fma_f32 v[96:97], v[104:105], v[104:105], v[96:97]
	v_cvt_pk_bf16_f32 v101, v108, v109
	v_add_f32_e32 v96, v96, v97
	v_add_f32_e32 v96, v106, v96
	v_add_f32_e32 v96, v107, v96
	v_add_f32_e32 v96, v201, v96
	ds_bpermute_b32 v97, v200, v96
	v_and_b32_e32 v107, 0xffff0000, v101
	v_lshlrev_b32_e32 v106, 16, v101
	v_pk_add_f32 v[106:107], v[108:109], v[106:107] neg_lo:[0,1] neg_hi:[0,1]
	v_cvt_pk_bf16_f32 v104, v110, v111
	s_waitcnt lgkmcnt(0)
	v_add_f32_e32 v96, v96, v97
	ds_bpermute_b32 v97, v199, v96
	v_cvt_pk_bf16_f32 v105, v106, v107
	global_store_dwordx4 v[234:235], v[98:101], off offset:256
	global_store_dwordx4 v[236:237], v[102:105], off
	s_and_saveexec_b64 s[20:21], vcc
	s_cbranch_execz .LBB0_1632
	s_waitcnt lgkmcnt(0)
	v_add_f32_e32 v96, v96, v97
	global_atomic_add_f32 v[184:185], v96, off offset:64
.LBB0_1632:
	s_or_b64 exec, exec, s[20:21]
	v_lshlrev_b32_e32 v96, 16, v156
	s_waitcnt lgkmcnt(0)
	v_and_b32_e32 v97, 0xffff0000, v156
	v_lshlrev_b32_e32 v98, 16, v152
	v_and_b32_e32 v99, 0xffff0000, v152
	v_pk_add_f32 v[96:97], v[96:97], v[98:99]
	v_lshlrev_b32_e32 v98, 16, v157
	v_and_b32_e32 v99, 0xffff0000, v157
	v_lshlrev_b32_e32 v100, 16, v153
	v_and_b32_e32 v101, 0xffff0000, v153
	v_pk_add_f32 v[98:99], v[98:99], v[100:101]
	v_pk_fma_f32 v[96:97], v[92:93], 0.5, v[96:97] op_sel_hi:[1,0,1]
	v_pk_fma_f32 v[98:99], v[94:95], 0.5, v[98:99] op_sel_hi:[1,0,1]
	v_lshlrev_b32_e32 v92, 16, v158
	v_and_b32_e32 v93, 0xffff0000, v158
	v_lshlrev_b32_e32 v94, 16, v154
	v_and_b32_e32 v95, 0xffff0000, v154
	v_pk_add_f32 v[92:93], v[92:93], v[94:95]
	v_lshlrev_b32_e32 v94, 16, v159
	v_and_b32_e32 v95, 0xffff0000, v159
	v_lshlrev_b32_e32 v100, 16, v155
	v_and_b32_e32 v101, 0xffff0000, v155
	v_pk_add_f32 v[94:95], v[94:95], v[100:101]
	v_pk_fma_f32 v[88:89], v[88:89], 0.5, v[92:93] op_sel_hi:[1,0,1]
	v_pk_fma_f32 v[100:101], v[90:91], 0.5, v[94:95] op_sel_hi:[1,0,1]
	v_cvt_pk_bf16_f32 v90, v96, v97
	v_and_b32_e32 v93, 0xffff0000, v90
	v_lshlrev_b32_e32 v92, 16, v90
	v_pk_add_f32 v[92:93], v[96:97], v[92:93] neg_lo:[0,1] neg_hi:[0,1]
	v_cvt_pk_bf16_f32 v91, v98, v99
	v_cvt_pk_bf16_f32 v94, v92, v93
	v_and_b32_e32 v93, 0xffff0000, v91
	v_lshlrev_b32_e32 v92, 16, v91
	v_pk_add_f32 v[92:93], v[98:99], v[92:93] neg_lo:[0,1] neg_hi:[0,1]
	v_pk_mul_f32 v[104:105], v[100:101], v[100:101]
	v_cvt_pk_bf16_f32 v95, v92, v93
	v_cvt_pk_bf16_f32 v92, v88, v89
	v_and_b32_e32 v103, 0xffff0000, v92
	v_lshlrev_b32_e32 v102, 16, v92
	v_pk_add_f32 v[102:103], v[88:89], v[102:103] neg_lo:[0,1] neg_hi:[0,1]
	v_pk_mul_f32 v[88:89], v[88:89], v[88:89]
	v_pk_fma_f32 v[98:99], v[98:99], v[98:99], v[104:105]
	v_pk_fma_f32 v[88:89], v[96:97], v[96:97], v[88:89]
	v_cvt_pk_bf16_f32 v93, v100, v101
	v_add_f32_e32 v88, v88, v89
	v_add_f32_e32 v88, v98, v88
	v_add_f32_e32 v88, v99, v88
	v_mov_b32_e32 v201, v88
	v_and_b32_e32 v99, 0xffff0000, v93
	v_lshlrev_b32_e32 v98, 16, v93
	v_pk_add_f32 v[98:99], v[100:101], v[98:99] neg_lo:[0,1] neg_hi:[0,1]
	v_cvt_pk_bf16_f32 v96, v102, v103
	s_waitcnt lgkmcnt(0)
	v_cvt_pk_bf16_f32 v97, v98, v99
	global_store_dwordx4 v[226:227], v[90:93], off
	global_store_dwordx4 v[232:233], v[94:97], off
.LBB0_1634:
	v_lshlrev_b32_e32 v88, 16, v148
	s_waitcnt lgkmcnt(0)
	v_and_b32_e32 v89, 0xffff0000, v148
	v_lshlrev_b32_e32 v90, 16, v144
	v_and_b32_e32 v91, 0xffff0000, v144
	v_pk_add_f32 v[88:89], v[88:89], v[90:91]
	v_lshlrev_b32_e32 v90, 16, v149
	v_and_b32_e32 v91, 0xffff0000, v149
	v_lshlrev_b32_e32 v92, 16, v145
	v_and_b32_e32 v93, 0xffff0000, v145
	v_pk_add_f32 v[90:91], v[90:91], v[92:93]
	v_pk_fma_f32 v[88:89], v[84:85], 0.5, v[88:89] op_sel_hi:[1,0,1]
	v_pk_fma_f32 v[90:91], v[86:87], 0.5, v[90:91] op_sel_hi:[1,0,1]
	v_lshlrev_b32_e32 v84, 16, v150
	v_and_b32_e32 v85, 0xffff0000, v150
	v_lshlrev_b32_e32 v86, 16, v146
	v_and_b32_e32 v87, 0xffff0000, v146
	v_pk_add_f32 v[84:85], v[84:85], v[86:87]
	v_lshlrev_b32_e32 v86, 16, v151
	v_and_b32_e32 v87, 0xffff0000, v151
	v_lshlrev_b32_e32 v92, 16, v147
	v_and_b32_e32 v93, 0xffff0000, v147
	v_pk_add_f32 v[86:87], v[86:87], v[92:93]
	v_pk_fma_f32 v[80:81], v[80:81], 0.5, v[84:85] op_sel_hi:[1,0,1]
	v_pk_fma_f32 v[92:93], v[82:83], 0.5, v[86:87] op_sel_hi:[1,0,1]
	v_cvt_pk_bf16_f32 v82, v88, v89
	v_and_b32_e32 v85, 0xffff0000, v82
	v_lshlrev_b32_e32 v84, 16, v82
	v_pk_add_f32 v[84:85], v[88:89], v[84:85] neg_lo:[0,1] neg_hi:[0,1]
	v_cvt_pk_bf16_f32 v83, v90, v91
	v_cvt_pk_bf16_f32 v86, v84, v85
	v_and_b32_e32 v85, 0xffff0000, v83
	v_lshlrev_b32_e32 v84, 16, v83
	v_pk_add_f32 v[84:85], v[90:91], v[84:85] neg_lo:[0,1] neg_hi:[0,1]
	v_pk_mul_f32 v[96:97], v[92:93], v[92:93]
	v_cvt_pk_bf16_f32 v87, v84, v85
	v_cvt_pk_bf16_f32 v84, v80, v81
	v_and_b32_e32 v95, 0xffff0000, v84
	v_lshlrev_b32_e32 v94, 16, v84
	v_pk_add_f32 v[94:95], v[80:81], v[94:95] neg_lo:[0,1] neg_hi:[0,1]
	v_pk_mul_f32 v[80:81], v[80:81], v[80:81]
	v_pk_fma_f32 v[90:91], v[90:91], v[90:91], v[96:97]
	v_pk_fma_f32 v[80:81], v[88:89], v[88:89], v[80:81]
	v_cvt_pk_bf16_f32 v85, v92, v93
	v_add_f32_e32 v80, v80, v81
	v_add_f32_e32 v80, v90, v80
	v_add_f32_e32 v80, v91, v80
	v_add_f32_e32 v80, v201, v80
	ds_bpermute_b32 v81, v200, v80
	v_and_b32_e32 v91, 0xffff0000, v85
	v_lshlrev_b32_e32 v90, 16, v85
	v_pk_add_f32 v[90:91], v[92:93], v[90:91] neg_lo:[0,1] neg_hi:[0,1]
	v_cvt_pk_bf16_f32 v88, v94, v95
	s_waitcnt lgkmcnt(0)
	v_add_f32_e32 v80, v80, v81
	ds_bpermute_b32 v81, v199, v80
	v_cvt_pk_bf16_f32 v89, v90, v91
	global_store_dwordx4 v[226:227], v[82:85], off offset:256
	global_store_dwordx4 v[230:231], v[86:89], off
	s_and_saveexec_b64 s[20:21], vcc
	s_cbranch_execz .LBB0_1636
	s_waitcnt lgkmcnt(0)
	v_add_f32_e32 v80, v80, v81
	global_atomic_add_f32 v[184:185], v80, off offset:128
.LBB0_1636:
	s_or_b64 exec, exec, s[20:21]
	v_lshlrev_b32_e32 v80, 16, v140
	s_waitcnt lgkmcnt(0)
	v_and_b32_e32 v81, 0xffff0000, v140
	v_lshlrev_b32_e32 v82, 16, v136
	v_and_b32_e32 v83, 0xffff0000, v136
	v_pk_add_f32 v[80:81], v[80:81], v[82:83]
	v_lshlrev_b32_e32 v82, 16, v141
	v_and_b32_e32 v83, 0xffff0000, v141
	v_lshlrev_b32_e32 v84, 16, v137
	v_and_b32_e32 v85, 0xffff0000, v137
	v_pk_add_f32 v[82:83], v[82:83], v[84:85]
	v_pk_fma_f32 v[80:81], v[76:77], 0.5, v[80:81] op_sel_hi:[1,0,1]
	v_pk_fma_f32 v[82:83], v[78:79], 0.5, v[82:83] op_sel_hi:[1,0,1]
	v_lshlrev_b32_e32 v76, 16, v142
	v_and_b32_e32 v77, 0xffff0000, v142
	v_lshlrev_b32_e32 v78, 16, v138
	v_and_b32_e32 v79, 0xffff0000, v138
	v_pk_add_f32 v[76:77], v[76:77], v[78:79]
	v_lshlrev_b32_e32 v78, 16, v143
	v_and_b32_e32 v79, 0xffff0000, v143
	v_lshlrev_b32_e32 v84, 16, v139
	v_and_b32_e32 v85, 0xffff0000, v139
	v_pk_add_f32 v[78:79], v[78:79], v[84:85]
	v_pk_fma_f32 v[72:73], v[72:73], 0.5, v[76:77] op_sel_hi:[1,0,1]
	v_pk_fma_f32 v[84:85], v[74:75], 0.5, v[78:79] op_sel_hi:[1,0,1]
	v_cvt_pk_bf16_f32 v74, v80, v81
	v_and_b32_e32 v77, 0xffff0000, v74
	v_lshlrev_b32_e32 v76, 16, v74
	v_pk_add_f32 v[76:77], v[80:81], v[76:77] neg_lo:[0,1] neg_hi:[0,1]
	v_cvt_pk_bf16_f32 v75, v82, v83
	v_cvt_pk_bf16_f32 v78, v76, v77
	v_and_b32_e32 v77, 0xffff0000, v75
	v_lshlrev_b32_e32 v76, 16, v75
	v_pk_add_f32 v[76:77], v[82:83], v[76:77] neg_lo:[0,1] neg_hi:[0,1]
	v_pk_mul_f32 v[88:89], v[84:85], v[84:85]
	v_cvt_pk_bf16_f32 v79, v76, v77
	v_cvt_pk_bf16_f32 v76, v72, v73
	v_and_b32_e32 v87, 0xffff0000, v76
	v_lshlrev_b32_e32 v86, 16, v76
	v_pk_add_f32 v[86:87], v[72:73], v[86:87] neg_lo:[0,1] neg_hi:[0,1]
	v_pk_mul_f32 v[72:73], v[72:73], v[72:73]
	v_pk_fma_f32 v[82:83], v[82:83], v[82:83], v[88:89]
	v_pk_fma_f32 v[72:73], v[80:81], v[80:81], v[72:73]
	v_cvt_pk_bf16_f32 v77, v84, v85
	v_add_f32_e32 v72, v72, v73
	v_add_f32_e32 v72, v82, v72
	v_add_f32_e32 v72, v83, v72
	v_mov_b32_e32 v201, v72
	v_and_b32_e32 v83, 0xffff0000, v77
	v_lshlrev_b32_e32 v82, 16, v77
	v_pk_add_f32 v[82:83], v[84:85], v[82:83] neg_lo:[0,1] neg_hi:[0,1]
	v_cvt_pk_bf16_f32 v80, v86, v87
	s_waitcnt lgkmcnt(0)
	v_cvt_pk_bf16_f32 v81, v82, v83
	global_store_dwordx4 v[222:223], v[74:77], off
	global_store_dwordx4 v[228:229], v[78:81], off
.LBB0_1638:
	v_lshlrev_b32_e32 v72, 16, v128
	s_waitcnt lgkmcnt(0)
	v_and_b32_e32 v73, 0xffff0000, v128
	v_lshlrev_b32_e32 v74, 16, v132
	v_and_b32_e32 v75, 0xffff0000, v132
	v_pk_add_f32 v[72:73], v[72:73], v[74:75]
	v_lshlrev_b32_e32 v74, 16, v129
	v_and_b32_e32 v75, 0xffff0000, v129
	v_lshlrev_b32_e32 v76, 16, v133
	v_and_b32_e32 v77, 0xffff0000, v133
	v_pk_add_f32 v[74:75], v[74:75], v[76:77]
	v_pk_fma_f32 v[72:73], v[68:69], 0.5, v[72:73] op_sel_hi:[1,0,1]
	v_pk_fma_f32 v[74:75], v[70:71], 0.5, v[74:75] op_sel_hi:[1,0,1]
	v_lshlrev_b32_e32 v68, 16, v130
	v_and_b32_e32 v69, 0xffff0000, v130
	v_lshlrev_b32_e32 v70, 16, v134
	v_and_b32_e32 v71, 0xffff0000, v134
	v_pk_add_f32 v[68:69], v[68:69], v[70:71]
	v_lshlrev_b32_e32 v70, 16, v131
	v_and_b32_e32 v71, 0xffff0000, v131
	v_lshlrev_b32_e32 v76, 16, v135
	v_and_b32_e32 v77, 0xffff0000, v135
	v_pk_add_f32 v[70:71], v[70:71], v[76:77]
	v_pk_fma_f32 v[64:65], v[64:65], 0.5, v[68:69] op_sel_hi:[1,0,1]
	v_pk_fma_f32 v[76:77], v[66:67], 0.5, v[70:71] op_sel_hi:[1,0,1]
	v_cvt_pk_bf16_f32 v66, v72, v73
	v_and_b32_e32 v69, 0xffff0000, v66
	v_lshlrev_b32_e32 v68, 16, v66
	v_pk_add_f32 v[68:69], v[72:73], v[68:69] neg_lo:[0,1] neg_hi:[0,1]
	v_cvt_pk_bf16_f32 v67, v74, v75
	v_cvt_pk_bf16_f32 v70, v68, v69
	v_and_b32_e32 v69, 0xffff0000, v67
	v_lshlrev_b32_e32 v68, 16, v67
	v_pk_add_f32 v[68:69], v[74:75], v[68:69] neg_lo:[0,1] neg_hi:[0,1]
	v_pk_mul_f32 v[80:81], v[76:77], v[76:77]
	v_cvt_pk_bf16_f32 v71, v68, v69
	v_cvt_pk_bf16_f32 v68, v64, v65
	v_and_b32_e32 v79, 0xffff0000, v68
	v_lshlrev_b32_e32 v78, 16, v68
	v_pk_add_f32 v[78:79], v[64:65], v[78:79] neg_lo:[0,1] neg_hi:[0,1]
	v_pk_mul_f32 v[64:65], v[64:65], v[64:65]
	v_pk_fma_f32 v[74:75], v[74:75], v[74:75], v[80:81]
	v_pk_fma_f32 v[64:65], v[72:73], v[72:73], v[64:65]
	v_cvt_pk_bf16_f32 v69, v76, v77
	v_add_f32_e32 v64, v64, v65
	v_add_f32_e32 v64, v74, v64
	v_add_f32_e32 v64, v75, v64
	v_add_f32_e32 v64, v201, v64
	ds_bpermute_b32 v65, v200, v64
	v_and_b32_e32 v75, 0xffff0000, v69
	v_lshlrev_b32_e32 v74, 16, v69
	v_pk_add_f32 v[74:75], v[76:77], v[74:75] neg_lo:[0,1] neg_hi:[0,1]
	v_cvt_pk_bf16_f32 v72, v78, v79
	s_waitcnt lgkmcnt(0)
	v_add_f32_e32 v64, v64, v65
	ds_bpermute_b32 v65, v199, v64
	v_cvt_pk_bf16_f32 v73, v74, v75
	global_store_dwordx4 v[222:223], v[66:69], off offset:256
	global_store_dwordx4 v[224:225], v[70:73], off
	s_and_saveexec_b64 s[20:21], vcc
	s_cbranch_execz .LBB0_1640
	s_waitcnt lgkmcnt(0)
	v_add_f32_e32 v64, v64, v65
	global_atomic_add_f32 v[184:185], v64, off offset:192
.LBB0_1640:
	s_or_b64 exec, exec, s[20:21]
	s_mov_b64 s[0:1], 0x20000
	s_waitcnt lgkmcnt(0)
	v_lshl_add_u64 v[64:65], v[220:221], 0, s[0:1]
	v_lshl_add_u64 v[66:67], v[64:65], 0, v[216:217]
	v_lshlrev_b64 v[66:67], 1, v[66:67]
	v_lshl_add_u64 v[146:147], s[18:19], 0, v[66:67]
	v_lshl_add_u64 v[150:151], s[10:11], 0, v[66:67]
	global_load_dwordx4 v[124:127], v[146:147], off
	global_load_dwordx4 v[116:119], v[146:147], off offset:256
	global_load_dwordx4 v[120:123], v[150:151], off
	v_lshl_add_u64 v[64:65], v[64:65], 0, v[218:219]
	s_mov_b64 s[0:1], 0x24000
	v_lshl_add_u64 v[148:149], v[64:65], 1, s[10:11]
	v_lshl_add_u64 v[64:65], v[220:221], 0, s[0:1]
	v_lshl_add_u64 v[66:67], v[64:65], 0, v[216:217]
	v_lshl_add_u64 v[64:65], v[64:65], 0, v[218:219]
	s_mov_b64 s[0:1], 0x28000
	v_lshlrev_b64 v[66:67], 1, v[66:67]
	v_lshl_add_u64 v[142:143], v[64:65], 1, s[10:11]
	v_lshl_add_u64 v[64:65], v[220:221], 0, s[0:1]
	v_lshl_add_u64 v[140:141], s[18:19], 0, v[66:67]
	v_lshl_add_u64 v[144:145], s[10:11], 0, v[66:67]
	v_lshl_add_u64 v[66:67], v[64:65], 0, v[216:217]
	v_lshl_add_u64 v[64:65], v[64:65], 0, v[218:219]
	s_mov_b64 s[0:1], 0x2c000
	v_lshlrev_b64 v[66:67], 1, v[66:67]
	v_lshl_add_u64 v[136:137], v[64:65], 1, s[10:11]
	v_lshl_add_u64 v[64:65], v[220:221], 0, s[0:1]
	v_lshl_add_u64 v[134:135], s[18:19], 0, v[66:67]
	v_lshl_add_u64 v[138:139], s[10:11], 0, v[66:67]
	v_lshl_add_u64 v[66:67], v[64:65], 0, v[216:217]
	v_lshlrev_b64 v[66:67], 1, v[66:67]
	v_lshl_add_u64 v[76:77], v[64:65], 0, v[218:219]
	v_lshl_add_u64 v[128:129], s[18:19], 0, v[66:67]
	v_lshl_add_u64 v[132:133], s[10:11], 0, v[66:67]
	v_lshl_add_u64 v[130:131], v[76:77], 1, s[10:11]
	global_load_dwordx4 v[112:115], v[148:149], off
	global_load_dwordx4 v[108:111], v[140:141], off
	global_load_dwordx4 v[100:103], v[140:141], off offset:256
	global_load_dwordx4 v[104:107], v[144:145], off
	global_load_dwordx4 v[96:99], v[142:143], off
	global_load_dwordx4 v[92:95], v[134:135], off
	global_load_dwordx4 v[84:87], v[134:135], off offset:256
	global_load_dwordx4 v[88:91], v[138:139], off
	global_load_dwordx4 v[80:83], v[136:137], off
	global_load_dwordx4 v[72:75], v[128:129], off
	global_load_dwordx4 v[64:67], v[128:129], off offset:256
	global_load_dwordx4 v[68:71], v[132:133], off
	global_load_dwordx4 v[76:79], v[130:131], off
	s_waitcnt vmcnt(15)
	v_lshlrev_b32_e32 v152, 16, v124
	v_and_b32_e32 v153, 0xffff0000, v124
	s_waitcnt vmcnt(13)
	v_lshlrev_b32_e32 v154, 16, v120
	v_and_b32_e32 v155, 0xffff0000, v120
	v_lshlrev_b32_e32 v124, 16, v125
	v_and_b32_e32 v125, 0xffff0000, v125
	v_lshlrev_b32_e32 v120, 16, v121
	v_and_b32_e32 v121, 0xffff0000, v121
	v_pk_add_f32 v[152:153], v[152:153], v[154:155]
	v_pk_add_f32 v[120:121], v[124:125], v[120:121]
	v_pk_fma_f32 v[124:125], v[60:61], 0.5, v[152:153] op_sel_hi:[1,0,1]
	v_pk_fma_f32 v[120:121], v[62:63], 0.5, v[120:121] op_sel_hi:[1,0,1]
	v_lshlrev_b32_e32 v60, 16, v126
	v_and_b32_e32 v61, 0xffff0000, v126
	v_lshlrev_b32_e32 v62, 16, v122
	v_and_b32_e32 v63, 0xffff0000, v122
	v_pk_add_f32 v[60:61], v[60:61], v[62:63]
	v_lshlrev_b32_e32 v62, 16, v127
	v_and_b32_e32 v63, 0xffff0000, v127
	v_lshlrev_b32_e32 v122, 16, v123
	v_and_b32_e32 v123, 0xffff0000, v123
	v_pk_add_f32 v[62:63], v[62:63], v[122:123]
	v_pk_fma_f32 v[126:127], v[56:57], 0.5, v[60:61] op_sel_hi:[1,0,1]
	v_cvt_pk_bf16_f32 v56, v124, v125
	v_pk_fma_f32 v[122:123], v[58:59], 0.5, v[62:63] op_sel_hi:[1,0,1]
	v_and_b32_e32 v59, 0xffff0000, v56
	v_lshlrev_b32_e32 v58, 16, v56
	v_pk_add_f32 v[58:59], v[124:125], v[58:59] neg_lo:[0,1] neg_hi:[0,1]
	v_cvt_pk_bf16_f32 v57, v120, v121
	v_cvt_pk_bf16_f32 v60, v58, v59
	v_and_b32_e32 v59, 0xffff0000, v57
	v_lshlrev_b32_e32 v58, 16, v57
	v_pk_add_f32 v[58:59], v[120:121], v[58:59] neg_lo:[0,1] neg_hi:[0,1]
	s_nop 0
	v_cvt_pk_bf16_f32 v61, v58, v59
	v_cvt_pk_bf16_f32 v58, v126, v127
	v_cvt_pk_bf16_f32 v59, v122, v123
	v_and_b32_e32 v63, 0xffff0000, v58
	v_lshlrev_b32_e32 v62, 16, v58
	v_and_b32_e32 v153, 0xffff0000, v59
	v_lshlrev_b32_e32 v152, 16, v59
	v_pk_add_f32 v[62:63], v[126:127], v[62:63] neg_lo:[0,1] neg_hi:[0,1]
	v_pk_add_f32 v[152:153], v[122:123], v[152:153] neg_lo:[0,1] neg_hi:[0,1]
	v_cvt_pk_bf16_f32 v62, v62, v63
	v_cvt_pk_bf16_f32 v63, v152, v153
	global_store_dwordx4 v[146:147], v[56:59], off
	global_store_dwordx4 v[150:151], v[60:63], off
	s_nop 0
	v_pk_mul_f32 v[56:57], v[126:127], v[126:127]
	v_pk_mul_f32 v[58:59], v[122:123], v[122:123]
	v_pk_fma_f32 v[56:57], v[124:125], v[124:125], v[56:57]
	v_pk_fma_f32 v[58:59], v[120:121], v[120:121], v[58:59]
	v_add_f32_e32 v56, v56, v57
	v_add_f32_e32 v56, v58, v56
	v_add_f32_e32 v56, v59, v56
	v_mov_b32_e32 v201, v56
	s_waitcnt lgkmcnt(0)
.LBB0_1642:
	v_lshlrev_b32_e32 v56, 16, v116
	s_waitcnt lgkmcnt(0)
	v_and_b32_e32 v57, 0xffff0000, v116
	s_waitcnt vmcnt(13)
	v_lshlrev_b32_e32 v58, 16, v112
	v_and_b32_e32 v59, 0xffff0000, v112
	v_pk_add_f32 v[56:57], v[56:57], v[58:59]
	v_lshlrev_b32_e32 v58, 16, v117
	v_and_b32_e32 v59, 0xffff0000, v117
	v_lshlrev_b32_e32 v60, 16, v113
	v_and_b32_e32 v61, 0xffff0000, v113
	v_pk_add_f32 v[58:59], v[58:59], v[60:61]
	v_pk_fma_f32 v[56:57], v[52:53], 0.5, v[56:57] op_sel_hi:[1,0,1]
	v_pk_fma_f32 v[58:59], v[54:55], 0.5, v[58:59] op_sel_hi:[1,0,1]
	v_lshlrev_b32_e32 v52, 16, v118
	v_and_b32_e32 v53, 0xffff0000, v118
	v_lshlrev_b32_e32 v54, 16, v114
	v_and_b32_e32 v55, 0xffff0000, v114
	v_pk_add_f32 v[52:53], v[52:53], v[54:55]
	v_lshlrev_b32_e32 v54, 16, v119
	v_and_b32_e32 v55, 0xffff0000, v119
	v_lshlrev_b32_e32 v60, 16, v115
	v_and_b32_e32 v61, 0xffff0000, v115
	v_pk_add_f32 v[54:55], v[54:55], v[60:61]
	v_pk_fma_f32 v[48:49], v[48:49], 0.5, v[52:53] op_sel_hi:[1,0,1]
	v_pk_fma_f32 v[60:61], v[50:51], 0.5, v[54:55] op_sel_hi:[1,0,1]
	v_cvt_pk_bf16_f32 v50, v56, v57
	v_and_b32_e32 v53, 0xffff0000, v50
	v_lshlrev_b32_e32 v52, 16, v50
	v_pk_add_f32 v[52:53], v[56:57], v[52:53] neg_lo:[0,1] neg_hi:[0,1]
	v_cvt_pk_bf16_f32 v51, v58, v59
	v_cvt_pk_bf16_f32 v54, v52, v53
	v_and_b32_e32 v53, 0xffff0000, v51
	v_lshlrev_b32_e32 v52, 16, v51
	v_pk_add_f32 v[52:53], v[58:59], v[52:53] neg_lo:[0,1] neg_hi:[0,1]
	v_pk_mul_f32 v[112:113], v[60:61], v[60:61]
	v_cvt_pk_bf16_f32 v55, v52, v53
	v_cvt_pk_bf16_f32 v52, v48, v49
	v_and_b32_e32 v63, 0xffff0000, v52
	v_lshlrev_b32_e32 v62, 16, v52
	v_pk_add_f32 v[62:63], v[48:49], v[62:63] neg_lo:[0,1] neg_hi:[0,1]
	v_pk_mul_f32 v[48:49], v[48:49], v[48:49]
	v_pk_fma_f32 v[58:59], v[58:59], v[58:59], v[112:113]
	v_pk_fma_f32 v[48:49], v[56:57], v[56:57], v[48:49]
	v_cvt_pk_bf16_f32 v53, v60, v61
	v_add_f32_e32 v48, v48, v49
	v_add_f32_e32 v48, v58, v48
	v_add_f32_e32 v48, v59, v48
	v_add_f32_e32 v48, v201, v48
	ds_bpermute_b32 v49, v200, v48
	v_and_b32_e32 v59, 0xffff0000, v53
	v_lshlrev_b32_e32 v58, 16, v53
	v_pk_add_f32 v[58:59], v[60:61], v[58:59] neg_lo:[0,1] neg_hi:[0,1]
	v_cvt_pk_bf16_f32 v56, v62, v63
	s_waitcnt lgkmcnt(0)
	v_add_f32_e32 v48, v48, v49
	ds_bpermute_b32 v49, v199, v48
	v_cvt_pk_bf16_f32 v57, v58, v59
	global_store_dwordx4 v[146:147], v[50:53], off offset:256
	global_store_dwordx4 v[148:149], v[54:57], off
	s_and_saveexec_b64 s[20:21], vcc
	s_cbranch_execz .LBB0_1644
	s_waitcnt lgkmcnt(0)
	v_add_f32_e32 v48, v48, v49
	global_atomic_add_f32 v[184:185], v48, off offset:512
.LBB0_1644:
	s_or_b64 exec, exec, s[20:21]
	s_waitcnt vmcnt(14)
	v_lshlrev_b32_e32 v48, 16, v108
	s_waitcnt lgkmcnt(0)
	v_and_b32_e32 v49, 0xffff0000, v108
	s_waitcnt vmcnt(12)
	v_lshlrev_b32_e32 v50, 16, v104
	v_and_b32_e32 v51, 0xffff0000, v104
	v_pk_add_f32 v[48:49], v[48:49], v[50:51]
	v_lshlrev_b32_e32 v50, 16, v109
	v_and_b32_e32 v51, 0xffff0000, v109
	v_lshlrev_b32_e32 v52, 16, v105
	v_and_b32_e32 v53, 0xffff0000, v105
	v_pk_add_f32 v[50:51], v[50:51], v[52:53]
	v_pk_fma_f32 v[48:49], v[44:45], 0.5, v[48:49] op_sel_hi:[1,0,1]
	v_pk_fma_f32 v[50:51], v[46:47], 0.5, v[50:51] op_sel_hi:[1,0,1]
	v_lshlrev_b32_e32 v44, 16, v110
	v_and_b32_e32 v45, 0xffff0000, v110
	v_lshlrev_b32_e32 v46, 16, v106
	v_and_b32_e32 v47, 0xffff0000, v106
	v_pk_add_f32 v[44:45], v[44:45], v[46:47]
	v_lshlrev_b32_e32 v46, 16, v111
	v_and_b32_e32 v47, 0xffff0000, v111
	v_lshlrev_b32_e32 v52, 16, v107
	v_and_b32_e32 v53, 0xffff0000, v107
	v_pk_add_f32 v[46:47], v[46:47], v[52:53]
	v_pk_fma_f32 v[40:41], v[40:41], 0.5, v[44:45] op_sel_hi:[1,0,1]
	v_pk_fma_f32 v[52:53], v[42:43], 0.5, v[46:47] op_sel_hi:[1,0,1]
	v_cvt_pk_bf16_f32 v42, v48, v49
	v_and_b32_e32 v45, 0xffff0000, v42
	v_lshlrev_b32_e32 v44, 16, v42
	v_pk_add_f32 v[44:45], v[48:49], v[44:45] neg_lo:[0,1] neg_hi:[0,1]
	v_cvt_pk_bf16_f32 v43, v50, v51
	v_cvt_pk_bf16_f32 v46, v44, v45
	v_and_b32_e32 v45, 0xffff0000, v43
	v_lshlrev_b32_e32 v44, 16, v43
	v_pk_add_f32 v[44:45], v[50:51], v[44:45] neg_lo:[0,1] neg_hi:[0,1]
	v_pk_mul_f32 v[56:57], v[52:53], v[52:53]
	v_cvt_pk_bf16_f32 v47, v44, v45
	v_cvt_pk_bf16_f32 v44, v40, v41
	v_and_b32_e32 v55, 0xffff0000, v44
	v_lshlrev_b32_e32 v54, 16, v44
	v_pk_add_f32 v[54:55], v[40:41], v[54:55] neg_lo:[0,1] neg_hi:[0,1]
	v_pk_mul_f32 v[40:41], v[40:41], v[40:41]
	v_pk_fma_f32 v[50:51], v[50:51], v[50:51], v[56:57]
	v_pk_fma_f32 v[40:41], v[48:49], v[48:49], v[40:41]
	v_cvt_pk_bf16_f32 v45, v52, v53
	v_add_f32_e32 v40, v40, v41
	v_add_f32_e32 v40, v50, v40
	v_add_f32_e32 v40, v51, v40
	v_mov_b32_e32 v201, v40
	v_and_b32_e32 v51, 0xffff0000, v45
	v_lshlrev_b32_e32 v50, 16, v45
	v_pk_add_f32 v[50:51], v[52:53], v[50:51] neg_lo:[0,1] neg_hi:[0,1]
	v_cvt_pk_bf16_f32 v48, v54, v55
	s_waitcnt lgkmcnt(0)
	v_cvt_pk_bf16_f32 v49, v50, v51
	global_store_dwordx4 v[140:141], v[42:45], off
	global_store_dwordx4 v[144:145], v[46:49], off
.LBB0_1646:
	v_lshlrev_b32_e32 v40, 16, v100
	s_waitcnt lgkmcnt(0)
	v_and_b32_e32 v41, 0xffff0000, v100
	s_waitcnt vmcnt(12)
	v_lshlrev_b32_e32 v42, 16, v96
	v_and_b32_e32 v43, 0xffff0000, v96
	v_pk_add_f32 v[40:41], v[40:41], v[42:43]
	v_lshlrev_b32_e32 v42, 16, v101
	v_and_b32_e32 v43, 0xffff0000, v101
	v_lshlrev_b32_e32 v44, 16, v97
	v_and_b32_e32 v45, 0xffff0000, v97
	v_pk_add_f32 v[42:43], v[42:43], v[44:45]
	v_pk_fma_f32 v[40:41], v[36:37], 0.5, v[40:41] op_sel_hi:[1,0,1]
	v_pk_fma_f32 v[42:43], v[38:39], 0.5, v[42:43] op_sel_hi:[1,0,1]
	v_lshlrev_b32_e32 v36, 16, v102
	v_and_b32_e32 v37, 0xffff0000, v102
	v_lshlrev_b32_e32 v38, 16, v98
	v_and_b32_e32 v39, 0xffff0000, v98
	v_pk_add_f32 v[36:37], v[36:37], v[38:39]
	v_lshlrev_b32_e32 v38, 16, v103
	v_and_b32_e32 v39, 0xffff0000, v103
	v_lshlrev_b32_e32 v44, 16, v99
	v_and_b32_e32 v45, 0xffff0000, v99
	v_pk_add_f32 v[38:39], v[38:39], v[44:45]
	v_pk_fma_f32 v[32:33], v[32:33], 0.5, v[36:37] op_sel_hi:[1,0,1]
	v_pk_fma_f32 v[44:45], v[34:35], 0.5, v[38:39] op_sel_hi:[1,0,1]
	v_cvt_pk_bf16_f32 v34, v40, v41
	v_and_b32_e32 v37, 0xffff0000, v34
	v_lshlrev_b32_e32 v36, 16, v34
	v_pk_add_f32 v[36:37], v[40:41], v[36:37] neg_lo:[0,1] neg_hi:[0,1]
	v_cvt_pk_bf16_f32 v35, v42, v43
	v_cvt_pk_bf16_f32 v38, v36, v37
	v_and_b32_e32 v37, 0xffff0000, v35
	v_lshlrev_b32_e32 v36, 16, v35
	v_pk_add_f32 v[36:37], v[42:43], v[36:37] neg_lo:[0,1] neg_hi:[0,1]
	v_pk_mul_f32 v[48:49], v[44:45], v[44:45]
	v_cvt_pk_bf16_f32 v39, v36, v37
	v_cvt_pk_bf16_f32 v36, v32, v33
	v_and_b32_e32 v47, 0xffff0000, v36
	v_lshlrev_b32_e32 v46, 16, v36
	v_pk_add_f32 v[46:47], v[32:33], v[46:47] neg_lo:[0,1] neg_hi:[0,1]
	v_pk_mul_f32 v[32:33], v[32:33], v[32:33]
	v_pk_fma_f32 v[42:43], v[42:43], v[42:43], v[48:49]
	v_pk_fma_f32 v[32:33], v[40:41], v[40:41], v[32:33]
	v_cvt_pk_bf16_f32 v37, v44, v45
	v_add_f32_e32 v32, v32, v33
	v_add_f32_e32 v32, v42, v32
	v_add_f32_e32 v32, v43, v32
	v_add_f32_e32 v32, v201, v32
	ds_bpermute_b32 v33, v200, v32
	v_and_b32_e32 v43, 0xffff0000, v37
	v_lshlrev_b32_e32 v42, 16, v37
	v_pk_add_f32 v[42:43], v[44:45], v[42:43] neg_lo:[0,1] neg_hi:[0,1]
	v_cvt_pk_bf16_f32 v40, v46, v47
	s_waitcnt lgkmcnt(0)
	v_add_f32_e32 v32, v32, v33
	ds_bpermute_b32 v33, v199, v32
	v_cvt_pk_bf16_f32 v41, v42, v43
	global_store_dwordx4 v[140:141], v[34:37], off offset:256
	global_store_dwordx4 v[142:143], v[38:41], off
	s_and_saveexec_b64 s[20:21], vcc
	s_cbranch_execz .LBB0_1648
	s_waitcnt lgkmcnt(0)
	v_add_f32_e32 v32, v32, v33
	global_atomic_add_f32 v[184:185], v32, off offset:576
.LBB0_1648:
	s_or_b64 exec, exec, s[20:21]
	s_waitcnt vmcnt(13)
	v_lshlrev_b32_e32 v32, 16, v92
	s_waitcnt lgkmcnt(0)
	v_and_b32_e32 v33, 0xffff0000, v92
	s_waitcnt vmcnt(11)
	v_lshlrev_b32_e32 v34, 16, v88
	v_and_b32_e32 v35, 0xffff0000, v88
	v_pk_add_f32 v[32:33], v[32:33], v[34:35]
	v_lshlrev_b32_e32 v34, 16, v93
	v_and_b32_e32 v35, 0xffff0000, v93
	v_lshlrev_b32_e32 v36, 16, v89
	v_and_b32_e32 v37, 0xffff0000, v89
	v_pk_add_f32 v[34:35], v[34:35], v[36:37]
	v_pk_fma_f32 v[32:33], v[28:29], 0.5, v[32:33] op_sel_hi:[1,0,1]
	v_pk_fma_f32 v[34:35], v[30:31], 0.5, v[34:35] op_sel_hi:[1,0,1]
	v_lshlrev_b32_e32 v28, 16, v94
	v_and_b32_e32 v29, 0xffff0000, v94
	v_lshlrev_b32_e32 v30, 16, v90
	v_and_b32_e32 v31, 0xffff0000, v90
	v_pk_add_f32 v[28:29], v[28:29], v[30:31]
	v_lshlrev_b32_e32 v30, 16, v95
	v_and_b32_e32 v31, 0xffff0000, v95
	v_lshlrev_b32_e32 v36, 16, v91
	v_and_b32_e32 v37, 0xffff0000, v91
	v_pk_add_f32 v[30:31], v[30:31], v[36:37]
	v_pk_fma_f32 v[24:25], v[24:25], 0.5, v[28:29] op_sel_hi:[1,0,1]
	v_pk_fma_f32 v[36:37], v[26:27], 0.5, v[30:31] op_sel_hi:[1,0,1]
	v_cvt_pk_bf16_f32 v26, v32, v33
	v_and_b32_e32 v29, 0xffff0000, v26
	v_lshlrev_b32_e32 v28, 16, v26
	v_pk_add_f32 v[28:29], v[32:33], v[28:29] neg_lo:[0,1] neg_hi:[0,1]
	v_cvt_pk_bf16_f32 v27, v34, v35
	v_cvt_pk_bf16_f32 v30, v28, v29
	v_and_b32_e32 v29, 0xffff0000, v27
	v_lshlrev_b32_e32 v28, 16, v27
	v_pk_add_f32 v[28:29], v[34:35], v[28:29] neg_lo:[0,1] neg_hi:[0,1]
	v_pk_mul_f32 v[40:41], v[36:37], v[36:37]
	v_cvt_pk_bf16_f32 v31, v28, v29
	v_cvt_pk_bf16_f32 v28, v24, v25
	v_and_b32_e32 v39, 0xffff0000, v28
	v_lshlrev_b32_e32 v38, 16, v28
	v_pk_add_f32 v[38:39], v[24:25], v[38:39] neg_lo:[0,1] neg_hi:[0,1]
	v_pk_mul_f32 v[24:25], v[24:25], v[24:25]
	v_pk_fma_f32 v[34:35], v[34:35], v[34:35], v[40:41]
	v_pk_fma_f32 v[24:25], v[32:33], v[32:33], v[24:25]
	v_cvt_pk_bf16_f32 v29, v36, v37
	v_add_f32_e32 v24, v24, v25
	v_add_f32_e32 v24, v34, v24
	v_add_f32_e32 v24, v35, v24
	v_mov_b32_e32 v201, v24
	v_and_b32_e32 v35, 0xffff0000, v29
	v_lshlrev_b32_e32 v34, 16, v29
	v_pk_add_f32 v[34:35], v[36:37], v[34:35] neg_lo:[0,1] neg_hi:[0,1]
	v_cvt_pk_bf16_f32 v32, v38, v39
	s_waitcnt lgkmcnt(0)
	v_cvt_pk_bf16_f32 v33, v34, v35
	global_store_dwordx4 v[134:135], v[26:29], off
	global_store_dwordx4 v[138:139], v[30:33], off
.LBB0_1650:
	v_lshlrev_b32_e32 v24, 16, v84
	s_waitcnt lgkmcnt(0)
	v_and_b32_e32 v25, 0xffff0000, v84
	s_waitcnt vmcnt(11)
	v_lshlrev_b32_e32 v26, 16, v80
	v_and_b32_e32 v27, 0xffff0000, v80
	v_pk_add_f32 v[24:25], v[24:25], v[26:27]
	v_lshlrev_b32_e32 v26, 16, v85
	v_and_b32_e32 v27, 0xffff0000, v85
	v_lshlrev_b32_e32 v28, 16, v81
	v_and_b32_e32 v29, 0xffff0000, v81
	v_pk_add_f32 v[26:27], v[26:27], v[28:29]
	v_pk_fma_f32 v[24:25], v[20:21], 0.5, v[24:25] op_sel_hi:[1,0,1]
	v_pk_fma_f32 v[26:27], v[22:23], 0.5, v[26:27] op_sel_hi:[1,0,1]
	v_lshlrev_b32_e32 v20, 16, v86
	v_and_b32_e32 v21, 0xffff0000, v86
	v_lshlrev_b32_e32 v22, 16, v82
	v_and_b32_e32 v23, 0xffff0000, v82
	v_pk_add_f32 v[20:21], v[20:21], v[22:23]
	v_lshlrev_b32_e32 v22, 16, v87
	v_and_b32_e32 v23, 0xffff0000, v87
	v_lshlrev_b32_e32 v28, 16, v83
	v_and_b32_e32 v29, 0xffff0000, v83
	v_pk_add_f32 v[22:23], v[22:23], v[28:29]
	v_pk_fma_f32 v[16:17], v[16:17], 0.5, v[20:21] op_sel_hi:[1,0,1]
	v_pk_fma_f32 v[28:29], v[18:19], 0.5, v[22:23] op_sel_hi:[1,0,1]
	v_cvt_pk_bf16_f32 v18, v24, v25
	v_and_b32_e32 v21, 0xffff0000, v18
	v_lshlrev_b32_e32 v20, 16, v18
	v_pk_add_f32 v[20:21], v[24:25], v[20:21] neg_lo:[0,1] neg_hi:[0,1]
	v_cvt_pk_bf16_f32 v19, v26, v27
	v_cvt_pk_bf16_f32 v22, v20, v21
	v_and_b32_e32 v21, 0xffff0000, v19
	v_lshlrev_b32_e32 v20, 16, v19
	v_pk_add_f32 v[20:21], v[26:27], v[20:21] neg_lo:[0,1] neg_hi:[0,1]
	v_pk_mul_f32 v[32:33], v[28:29], v[28:29]
	v_cvt_pk_bf16_f32 v23, v20, v21
	v_cvt_pk_bf16_f32 v20, v16, v17
	v_and_b32_e32 v31, 0xffff0000, v20
	v_lshlrev_b32_e32 v30, 16, v20
	v_pk_add_f32 v[30:31], v[16:17], v[30:31] neg_lo:[0,1] neg_hi:[0,1]
	v_pk_mul_f32 v[16:17], v[16:17], v[16:17]
	v_pk_fma_f32 v[26:27], v[26:27], v[26:27], v[32:33]
	v_pk_fma_f32 v[16:17], v[24:25], v[24:25], v[16:17]
	v_cvt_pk_bf16_f32 v21, v28, v29
	v_add_f32_e32 v16, v16, v17
	v_add_f32_e32 v16, v26, v16
	v_add_f32_e32 v16, v27, v16
	v_add_f32_e32 v16, v201, v16
	ds_bpermute_b32 v17, v200, v16
	v_and_b32_e32 v27, 0xffff0000, v21
	v_lshlrev_b32_e32 v26, 16, v21
	v_pk_add_f32 v[26:27], v[28:29], v[26:27] neg_lo:[0,1] neg_hi:[0,1]
	v_cvt_pk_bf16_f32 v24, v30, v31
	s_waitcnt lgkmcnt(0)
	v_add_f32_e32 v16, v16, v17
	ds_bpermute_b32 v17, v199, v16
	v_cvt_pk_bf16_f32 v25, v26, v27
	global_store_dwordx4 v[134:135], v[18:21], off offset:256
	global_store_dwordx4 v[136:137], v[22:25], off
	s_and_saveexec_b64 s[20:21], vcc
	s_cbranch_execz .LBB0_1652
	s_waitcnt lgkmcnt(0)
	v_add_f32_e32 v16, v16, v17
	global_atomic_add_f32 v[184:185], v16, off offset:640
.LBB0_1652:
	s_or_b64 exec, exec, s[20:21]
	s_waitcnt vmcnt(12)
	v_lshlrev_b32_e32 v16, 16, v72
	s_waitcnt lgkmcnt(0)
	v_and_b32_e32 v17, 0xffff0000, v72
	s_waitcnt vmcnt(10)
	v_lshlrev_b32_e32 v18, 16, v68
	v_and_b32_e32 v19, 0xffff0000, v68
	v_pk_add_f32 v[16:17], v[16:17], v[18:19]
	v_lshlrev_b32_e32 v18, 16, v73
	v_and_b32_e32 v19, 0xffff0000, v73
	v_lshlrev_b32_e32 v20, 16, v69
	v_and_b32_e32 v21, 0xffff0000, v69
	v_pk_add_f32 v[18:19], v[18:19], v[20:21]
	v_pk_fma_f32 v[16:17], v[12:13], 0.5, v[16:17] op_sel_hi:[1,0,1]
	v_pk_fma_f32 v[18:19], v[14:15], 0.5, v[18:19] op_sel_hi:[1,0,1]
	v_lshlrev_b32_e32 v12, 16, v74
	v_and_b32_e32 v13, 0xffff0000, v74
	v_lshlrev_b32_e32 v14, 16, v70
	v_and_b32_e32 v15, 0xffff0000, v70
	v_pk_add_f32 v[12:13], v[12:13], v[14:15]
	v_lshlrev_b32_e32 v14, 16, v75
	v_and_b32_e32 v15, 0xffff0000, v75
	v_lshlrev_b32_e32 v20, 16, v71
	v_and_b32_e32 v21, 0xffff0000, v71
	v_pk_add_f32 v[14:15], v[14:15], v[20:21]
	v_pk_fma_f32 v[8:9], v[8:9], 0.5, v[12:13] op_sel_hi:[1,0,1]
	v_pk_fma_f32 v[20:21], v[10:11], 0.5, v[14:15] op_sel_hi:[1,0,1]
	v_cvt_pk_bf16_f32 v10, v16, v17
	v_and_b32_e32 v13, 0xffff0000, v10
	v_lshlrev_b32_e32 v12, 16, v10
	v_pk_add_f32 v[12:13], v[16:17], v[12:13] neg_lo:[0,1] neg_hi:[0,1]
	v_cvt_pk_bf16_f32 v11, v18, v19
	v_cvt_pk_bf16_f32 v14, v12, v13
	v_and_b32_e32 v13, 0xffff0000, v11
	v_lshlrev_b32_e32 v12, 16, v11
	v_pk_add_f32 v[12:13], v[18:19], v[12:13] neg_lo:[0,1] neg_hi:[0,1]
	v_pk_mul_f32 v[24:25], v[20:21], v[20:21]
	v_cvt_pk_bf16_f32 v15, v12, v13
	v_cvt_pk_bf16_f32 v12, v8, v9
	v_and_b32_e32 v23, 0xffff0000, v12
	v_lshlrev_b32_e32 v22, 16, v12
	v_pk_add_f32 v[22:23], v[8:9], v[22:23] neg_lo:[0,1] neg_hi:[0,1]
	v_pk_mul_f32 v[8:9], v[8:9], v[8:9]
	v_pk_fma_f32 v[18:19], v[18:19], v[18:19], v[24:25]
	v_pk_fma_f32 v[8:9], v[16:17], v[16:17], v[8:9]
	v_cvt_pk_bf16_f32 v13, v20, v21
	v_add_f32_e32 v8, v8, v9
	v_add_f32_e32 v8, v18, v8
	v_add_f32_e32 v8, v19, v8
	v_mov_b32_e32 v201, v8
	v_and_b32_e32 v19, 0xffff0000, v13
	v_lshlrev_b32_e32 v18, 16, v13
	v_pk_add_f32 v[18:19], v[20:21], v[18:19] neg_lo:[0,1] neg_hi:[0,1]
	v_cvt_pk_bf16_f32 v16, v22, v23
	s_waitcnt lgkmcnt(0)
	v_cvt_pk_bf16_f32 v17, v18, v19
	global_store_dwordx4 v[128:129], v[10:13], off
	global_store_dwordx4 v[132:133], v[14:17], off
.LBB0_1654:
	v_lshlrev_b32_e32 v8, 16, v64
	s_waitcnt lgkmcnt(0)
	v_and_b32_e32 v9, 0xffff0000, v64
	s_waitcnt vmcnt(10)
	v_lshlrev_b32_e32 v10, 16, v76
	v_and_b32_e32 v11, 0xffff0000, v76
	v_pk_add_f32 v[8:9], v[8:9], v[10:11]
	v_lshlrev_b32_e32 v10, 16, v65
	v_and_b32_e32 v11, 0xffff0000, v65
	v_lshlrev_b32_e32 v12, 16, v77
	v_and_b32_e32 v13, 0xffff0000, v77
	v_pk_add_f32 v[10:11], v[10:11], v[12:13]
	v_pk_fma_f32 v[8:9], v[4:5], 0.5, v[8:9] op_sel_hi:[1,0,1]
	v_pk_fma_f32 v[10:11], v[6:7], 0.5, v[10:11] op_sel_hi:[1,0,1]
	v_lshlrev_b32_e32 v4, 16, v66
	v_and_b32_e32 v5, 0xffff0000, v66
	v_lshlrev_b32_e32 v6, 16, v78
	v_and_b32_e32 v7, 0xffff0000, v78
	v_pk_add_f32 v[4:5], v[4:5], v[6:7]
	v_lshlrev_b32_e32 v6, 16, v67
	v_and_b32_e32 v7, 0xffff0000, v67
	v_lshlrev_b32_e32 v12, 16, v79
	v_and_b32_e32 v13, 0xffff0000, v79
	v_pk_add_f32 v[6:7], v[6:7], v[12:13]
	v_pk_fma_f32 v[0:1], v[0:1], 0.5, v[4:5] op_sel_hi:[1,0,1]
	v_pk_fma_f32 v[12:13], v[2:3], 0.5, v[6:7] op_sel_hi:[1,0,1]
	v_cvt_pk_bf16_f32 v2, v8, v9
	v_and_b32_e32 v5, 0xffff0000, v2
	v_lshlrev_b32_e32 v4, 16, v2
	v_pk_add_f32 v[4:5], v[8:9], v[4:5] neg_lo:[0,1] neg_hi:[0,1]
	v_cvt_pk_bf16_f32 v3, v10, v11
	v_cvt_pk_bf16_f32 v6, v4, v5
	v_and_b32_e32 v5, 0xffff0000, v3
	v_lshlrev_b32_e32 v4, 16, v3
	v_pk_add_f32 v[4:5], v[10:11], v[4:5] neg_lo:[0,1] neg_hi:[0,1]
	v_pk_mul_f32 v[16:17], v[12:13], v[12:13]
	v_cvt_pk_bf16_f32 v7, v4, v5
	v_cvt_pk_bf16_f32 v4, v0, v1
	v_and_b32_e32 v15, 0xffff0000, v4
	v_lshlrev_b32_e32 v14, 16, v4
	v_pk_add_f32 v[14:15], v[0:1], v[14:15] neg_lo:[0,1] neg_hi:[0,1]
	v_pk_mul_f32 v[0:1], v[0:1], v[0:1]
	v_pk_fma_f32 v[10:11], v[10:11], v[10:11], v[16:17]
	v_pk_fma_f32 v[0:1], v[8:9], v[8:9], v[0:1]
	v_cvt_pk_bf16_f32 v5, v12, v13
	v_add_f32_e32 v0, v0, v1
	v_add_f32_e32 v0, v10, v0
	v_add_f32_e32 v0, v11, v0
	v_add_f32_e32 v0, v201, v0
	ds_bpermute_b32 v1, v200, v0
	v_and_b32_e32 v11, 0xffff0000, v5
	v_lshlrev_b32_e32 v10, 16, v5
	v_pk_add_f32 v[10:11], v[12:13], v[10:11] neg_lo:[0,1] neg_hi:[0,1]
	v_cvt_pk_bf16_f32 v8, v14, v15
	s_waitcnt lgkmcnt(0)
	v_add_f32_e32 v0, v0, v1
	ds_bpermute_b32 v1, v199, v0
	v_cvt_pk_bf16_f32 v9, v10, v11
	global_store_dwordx4 v[128:129], v[2:5], off offset:256
	global_store_dwordx4 v[130:131], v[6:9], off
	s_and_saveexec_b64 s[20:21], vcc
	s_cbranch_execz .LBB0_1615
	s_waitcnt lgkmcnt(0)
	v_add_f32_e32 v0, v0, v1
	global_atomic_add_f32 v[184:185], v0, off offset:704
	s_branch .LBB0_1615

.LBB0_2484:
	s_add_u32 s34, s30, 0xfffe0080
	s_addc_u32 s35, s31, -1
	s_add_i32 s53, 0, 0x10000
	v_add_u32_e32 v140, s53, v196
	ds_read_b128 v[128:131], v140
	ds_read_b128 v[132:135], v140 offset:1024
	ds_read_b128 v[136:139], v140 offset:2048
	ds_read_b128 v[140:143], v140 offset:3072
	s_cmp_eq_u32 s52, 4
	s_cselect_b32 s37, s0, s35
	s_cselect_b32 s36, s1, s34
	s_cselect_b32 s35, s15, s33
	s_cselect_b32 s34, s21, s27
	s_add_i32 m0, s29, 0xc000
	ds_read_b128 v[144:147], v198
	ds_read_b128 v[148:151], v198 offset:1024
	ds_read_b128 v[152:155], v198 offset:2048
	ds_read_b128 v[156:159], v198 offset:3072
	ds_read_b128 v[160:163], v198 offset:4096
	ds_read_b128 v[164:167], v198 offset:5120
	ds_read_b128 v[168:171], v198 offset:6144
	ds_read_b128 v[172:175], v198 offset:7168
	global_load_lds_dwordx4 v212, s[30:31]
	s_add_i32 m0, s29, 0xe000
	s_nop 0
	global_load_lds_dwordx4 v214, s[30:31]
	s_waitcnt lgkmcnt(8)
	s_barrier
	s_waitcnt lgkmcnt(0)
	v_mfma_f32_16x16x32_bf16 v[124:127], v[128:131], v[144:147], v[124:127]
	v_mfma_f32_16x16x32_bf16 v[120:123], v[136:139], v[144:147], v[120:123]
	v_mfma_f32_16x16x32_bf16 v[108:111], v[128:131], v[152:155], v[108:111]
	v_mfma_f32_16x16x32_bf16 v[104:107], v[136:139], v[152:155], v[104:107]
	v_mfma_f32_16x16x32_bf16 v[92:95], v[128:131], v[160:163], v[92:95]
	v_mfma_f32_16x16x32_bf16 v[88:91], v[136:139], v[160:163], v[88:91]
	v_mfma_f32_16x16x32_bf16 v[76:79], v[128:131], v[168:171], v[76:79]
	v_mfma_f32_16x16x32_bf16 v[72:75], v[136:139], v[168:171], v[72:75]
	v_mfma_f32_16x16x32_bf16 v[124:127], v[132:135], v[148:151], v[124:127]
	v_mfma_f32_16x16x32_bf16 v[120:123], v[140:143], v[148:151], v[120:123]
	v_mfma_f32_16x16x32_bf16 v[108:111], v[132:135], v[156:159], v[108:111]
	v_mfma_f32_16x16x32_bf16 v[104:107], v[140:143], v[156:159], v[104:107]
	v_mfma_f32_16x16x32_bf16 v[92:95], v[132:135], v[164:167], v[92:95]
	v_mfma_f32_16x16x32_bf16 v[88:91], v[140:143], v[164:167], v[88:91]
	v_mfma_f32_16x16x32_bf16 v[76:79], v[132:135], v[172:175], v[76:79]
	v_mfma_f32_16x16x32_bf16 v[72:75], v[140:143], v[172:175], v[72:75]
	s_barrier
	s_add_i32 s56, 0, 0x14000
	s_add_i32 s53, s53, s45
	v_add_u32_e32 v188, s56, v196
	s_mov_b32 m0, s53
	ds_read_b128 v[176:179], v188
	ds_read_b128 v[180:183], v188 offset:1024
	ds_read_b128 v[184:187], v188 offset:2048
	ds_read_b128 v[188:191], v188 offset:3072
	global_load_lds_dwordx4 v192, s[34:35]
	s_add_i32 m0, s53, 0x2000
	s_nop 0
	global_load_lds_dwordx4 v210, s[34:35]
	s_barrier
	s_waitcnt lgkmcnt(0)
	v_mfma_f32_16x16x32_bf16 v[116:119], v[176:179], v[144:147], v[116:119]
	v_mfma_f32_16x16x32_bf16 v[112:115], v[184:187], v[144:147], v[112:115]
	v_mfma_f32_16x16x32_bf16 v[100:103], v[176:179], v[152:155], v[100:103]
	v_mfma_f32_16x16x32_bf16 v[96:99], v[184:187], v[152:155], v[96:99]
	v_mfma_f32_16x16x32_bf16 v[84:87], v[176:179], v[160:163], v[84:87]
	v_mfma_f32_16x16x32_bf16 v[80:83], v[184:187], v[160:163], v[80:83]
	v_mfma_f32_16x16x32_bf16 v[68:71], v[176:179], v[168:171], v[68:71]
	v_mfma_f32_16x16x32_bf16 v[64:67], v[184:187], v[168:171], v[64:67]
	v_mfma_f32_16x16x32_bf16 v[116:119], v[180:183], v[148:151], v[116:119]
	v_mfma_f32_16x16x32_bf16 v[112:115], v[188:191], v[148:151], v[112:115]
	v_mfma_f32_16x16x32_bf16 v[100:103], v[180:183], v[156:159], v[100:103]
	v_mfma_f32_16x16x32_bf16 v[96:99], v[188:191], v[156:159], v[96:99]
	v_mfma_f32_16x16x32_bf16 v[84:87], v[180:183], v[164:167], v[84:87]
	v_mfma_f32_16x16x32_bf16 v[80:83], v[188:191], v[164:167], v[80:83]
	v_mfma_f32_16x16x32_bf16 v[68:71], v[180:183], v[172:175], v[68:71]
	v_mfma_f32_16x16x32_bf16 v[64:67], v[188:191], v[172:175], v[64:67]
	s_mov_b32 m0, s29
	s_add_u32 vcc_lo, s36, 0x80
	s_addc_u32 vcc_hi, s37, 0
	s_barrier
	ds_read_b128 v[144:147], v198 offset:16384
	ds_read_b128 v[148:151], v198 offset:17408
	ds_read_b128 v[152:155], v198 offset:18432
	ds_read_b128 v[156:159], v198 offset:19456
	ds_read_b128 v[160:163], v198 offset:20480
	ds_read_b128 v[164:167], v198 offset:21504
	ds_read_b128 v[168:171], v198 offset:22528
	ds_read_b128 v[172:175], v198 offset:23552
	global_load_lds_dwordx4 v206, s[36:37]
	s_mov_b32 m0, s46
	s_nop 0
	global_load_lds_dwordx4 v208, s[36:37]
	s_barrier
	s_waitcnt lgkmcnt(0)
	v_mfma_f32_16x16x32_bf16 v[60:63], v[128:131], v[144:147], v[60:63]
	v_mfma_f32_16x16x32_bf16 v[56:59], v[136:139], v[144:147], v[56:59]
	v_mfma_f32_16x16x32_bf16 v[44:47], v[128:131], v[152:155], v[44:47]
	v_mfma_f32_16x16x32_bf16 v[40:43], v[136:139], v[152:155], v[40:43]
	v_mfma_f32_16x16x32_bf16 v[28:31], v[128:131], v[160:163], v[28:31]
	v_mfma_f32_16x16x32_bf16 v[24:27], v[136:139], v[160:163], v[24:27]
	v_mfma_f32_16x16x32_bf16 v[12:15], v[128:131], v[168:171], v[12:15]
	v_mfma_f32_16x16x32_bf16 v[8:11], v[136:139], v[168:171], v[8:11]
	v_mfma_f32_16x16x32_bf16 v[60:63], v[132:135], v[148:151], v[60:63]
	v_mfma_f32_16x16x32_bf16 v[56:59], v[140:143], v[148:151], v[56:59]
	v_mfma_f32_16x16x32_bf16 v[44:47], v[132:135], v[156:159], v[44:47]
	v_mfma_f32_16x16x32_bf16 v[40:43], v[140:143], v[156:159], v[40:43]
	v_mfma_f32_16x16x32_bf16 v[28:31], v[132:135], v[164:167], v[28:31]
	v_mfma_f32_16x16x32_bf16 v[24:27], v[140:143], v[164:167], v[24:27]
	v_mfma_f32_16x16x32_bf16 v[12:15], v[132:135], v[172:175], v[12:15]
	v_mfma_f32_16x16x32_bf16 v[8:11], v[140:143], v[172:175], v[8:11]
	s_barrier
	s_add_u32 s54, s34, 0x20000
	s_addc_u32 s55, s35, 0
	s_add_i32 s53, s56, s45
	s_mov_b32 m0, s53
	s_nop 0
	global_load_lds_dwordx4 v192, s[54:55]
	s_add_i32 m0, s53, 0x2000
	s_nop 0
	global_load_lds_dwordx4 v210, s[54:55]
	s_waitcnt vmcnt(6)
	s_barrier
	v_mfma_f32_16x16x32_bf16 v[52:55], v[176:179], v[144:147], v[52:55]
	v_mfma_f32_16x16x32_bf16 v[48:51], v[184:187], v[144:147], v[48:51]
	v_mfma_f32_16x16x32_bf16 v[36:39], v[176:179], v[152:155], v[36:39]
	v_mfma_f32_16x16x32_bf16 v[32:35], v[184:187], v[152:155], v[32:35]
	v_mfma_f32_16x16x32_bf16 v[20:23], v[176:179], v[160:163], v[20:23]
	v_mfma_f32_16x16x32_bf16 v[16:19], v[184:187], v[160:163], v[16:19]
	v_mfma_f32_16x16x32_bf16 v[4:7], v[176:179], v[168:171], v[4:7]
	v_mfma_f32_16x16x32_bf16 v[0:3], v[184:187], v[168:171], v[0:3]
	v_mfma_f32_16x16x32_bf16 v[52:55], v[180:183], v[148:151], v[52:55]
	v_mfma_f32_16x16x32_bf16 v[48:51], v[188:191], v[148:151], v[48:51]
	v_mfma_f32_16x16x32_bf16 v[36:39], v[180:183], v[156:159], v[36:39]
	v_mfma_f32_16x16x32_bf16 v[32:35], v[188:191], v[156:159], v[32:35]
	v_mfma_f32_16x16x32_bf16 v[20:23], v[180:183], v[164:167], v[20:23]
	v_mfma_f32_16x16x32_bf16 v[16:19], v[188:191], v[164:167], v[16:19]
	v_mfma_f32_16x16x32_bf16 v[4:7], v[180:183], v[172:175], v[4:7]
	v_mfma_f32_16x16x32_bf16 v[0:3], v[188:191], v[172:175], v[0:3]
	s_add_i32 s53, 0, 0x18000
	v_add_u32_e32 v140, s53, v196
	s_barrier
	ds_read_b128 v[128:131], v140
	ds_read_b128 v[132:135], v140 offset:1024
	ds_read_b128 v[136:139], v140 offset:2048
	ds_read_b128 v[140:143], v140 offset:3072
	s_add_u32 s36, s36, 0x20000
	s_addc_u32 s37, s37, 0
	s_mov_b32 m0, s47
	ds_read_b128 v[144:147], v198 offset:32768
	ds_read_b128 v[148:151], v198 offset:33792
	ds_read_b128 v[152:155], v198 offset:34816
	ds_read_b128 v[156:159], v198 offset:35840
	ds_read_b128 v[160:163], v198 offset:36864
	ds_read_b128 v[164:167], v198 offset:37888
	ds_read_b128 v[168:171], v198 offset:38912
	ds_read_b128 v[172:175], v198 offset:39936
	global_load_lds_dwordx4 v206, s[36:37]
	s_mov_b32 m0, s48
	s_nop 0
	global_load_lds_dwordx4 v208, s[36:37]
	s_waitcnt lgkmcnt(8)
	s_barrier
	s_waitcnt lgkmcnt(0)
	v_mfma_f32_16x16x32_bf16 v[124:127], v[128:131], v[144:147], v[124:127]
	v_mfma_f32_16x16x32_bf16 v[120:123], v[136:139], v[144:147], v[120:123]
	v_mfma_f32_16x16x32_bf16 v[108:111], v[128:131], v[152:155], v[108:111]
	v_mfma_f32_16x16x32_bf16 v[104:107], v[136:139], v[152:155], v[104:107]
	v_mfma_f32_16x16x32_bf16 v[92:95], v[128:131], v[160:163], v[92:95]
	v_mfma_f32_16x16x32_bf16 v[88:91], v[136:139], v[160:163], v[88:91]
	v_mfma_f32_16x16x32_bf16 v[76:79], v[128:131], v[168:171], v[76:79]
	v_mfma_f32_16x16x32_bf16 v[72:75], v[136:139], v[168:171], v[72:75]
	v_mfma_f32_16x16x32_bf16 v[124:127], v[132:135], v[148:151], v[124:127]
	v_mfma_f32_16x16x32_bf16 v[120:123], v[140:143], v[148:151], v[120:123]
	v_mfma_f32_16x16x32_bf16 v[108:111], v[132:135], v[156:159], v[108:111]
	v_mfma_f32_16x16x32_bf16 v[104:107], v[140:143], v[156:159], v[104:107]
	v_mfma_f32_16x16x32_bf16 v[92:95], v[132:135], v[164:167], v[92:95]
	v_mfma_f32_16x16x32_bf16 v[88:91], v[140:143], v[164:167], v[88:91]
	v_mfma_f32_16x16x32_bf16 v[76:79], v[132:135], v[172:175], v[76:79]
	v_mfma_f32_16x16x32_bf16 v[72:75], v[140:143], v[172:175], v[72:75]
	s_barrier
	s_add_i32 s36, 0, 0x1c000
	s_add_i32 s37, s53, s45
	v_add_u32_e32 v188, s36, v196
	s_add_u32 s100, s34, 0x80
	s_addc_u32 s101, s35, 0
	s_mov_b32 m0, s37
	ds_read_b128 v[176:179], v188
	ds_read_b128 v[180:183], v188 offset:1024
	ds_read_b128 v[184:187], v188 offset:2048
	ds_read_b128 v[188:191], v188 offset:3072
	global_load_lds_dwordx4 v192, s[100:101]
	s_add_i32 m0, s37, 0x2000
	s_nop 0
	global_load_lds_dwordx4 v210, s[100:101]
	s_barrier
	s_waitcnt lgkmcnt(0)
	v_mfma_f32_16x16x32_bf16 v[116:119], v[176:179], v[144:147], v[116:119]
	v_mfma_f32_16x16x32_bf16 v[112:115], v[184:187], v[144:147], v[112:115]
	v_mfma_f32_16x16x32_bf16 v[100:103], v[176:179], v[152:155], v[100:103]
	v_mfma_f32_16x16x32_bf16 v[96:99], v[184:187], v[152:155], v[96:99]
	v_mfma_f32_16x16x32_bf16 v[84:87], v[176:179], v[160:163], v[84:87]
	v_mfma_f32_16x16x32_bf16 v[80:83], v[184:187], v[160:163], v[80:83]
	v_mfma_f32_16x16x32_bf16 v[68:71], v[176:179], v[168:171], v[68:71]
	v_mfma_f32_16x16x32_bf16 v[64:67], v[184:187], v[168:171], v[64:67]
	v_mfma_f32_16x16x32_bf16 v[116:119], v[180:183], v[148:151], v[116:119]
	v_mfma_f32_16x16x32_bf16 v[112:115], v[188:191], v[148:151], v[112:115]
	v_mfma_f32_16x16x32_bf16 v[100:103], v[180:183], v[156:159], v[100:103]
	v_mfma_f32_16x16x32_bf16 v[96:99], v[188:191], v[156:159], v[96:99]
	v_mfma_f32_16x16x32_bf16 v[84:87], v[180:183], v[164:167], v[84:87]
	v_mfma_f32_16x16x32_bf16 v[80:83], v[188:191], v[164:167], v[80:83]
	v_mfma_f32_16x16x32_bf16 v[68:71], v[180:183], v[172:175], v[68:71]
	v_mfma_f32_16x16x32_bf16 v[64:67], v[188:191], v[172:175], v[64:67]
	s_mov_b32 m0, s49
	s_barrier
	ds_read_b128 v[144:147], v198 offset:49152
	ds_read_b128 v[148:151], v198 offset:50176
	ds_read_b128 v[152:155], v198 offset:51200
	ds_read_b128 v[156:159], v198 offset:52224
	ds_read_b128 v[160:163], v198 offset:53248
	ds_read_b128 v[164:167], v198 offset:54272
	ds_read_b128 v[168:171], v198 offset:55296
	ds_read_b128 v[172:175], v198 offset:56320
	global_load_lds_dwordx4 v206, vcc
	s_mov_b32 m0, s50
	s_nop 0
	global_load_lds_dwordx4 v208, vcc
	s_barrier
	s_waitcnt lgkmcnt(0)
	v_mfma_f32_16x16x32_bf16 v[60:63], v[128:131], v[144:147], v[60:63]
	v_mfma_f32_16x16x32_bf16 v[56:59], v[136:139], v[144:147], v[56:59]
	v_mfma_f32_16x16x32_bf16 v[44:47], v[128:131], v[152:155], v[44:47]
	v_mfma_f32_16x16x32_bf16 v[40:43], v[136:139], v[152:155], v[40:43]
	v_mfma_f32_16x16x32_bf16 v[28:31], v[128:131], v[160:163], v[28:31]
	v_mfma_f32_16x16x32_bf16 v[24:27], v[136:139], v[160:163], v[24:27]
	v_mfma_f32_16x16x32_bf16 v[12:15], v[128:131], v[168:171], v[12:15]
	v_mfma_f32_16x16x32_bf16 v[8:11], v[136:139], v[168:171], v[8:11]
	v_mfma_f32_16x16x32_bf16 v[60:63], v[132:135], v[148:151], v[60:63]
	v_mfma_f32_16x16x32_bf16 v[56:59], v[140:143], v[148:151], v[56:59]
	v_mfma_f32_16x16x32_bf16 v[44:47], v[132:135], v[156:159], v[44:47]
	v_mfma_f32_16x16x32_bf16 v[40:43], v[140:143], v[156:159], v[40:43]
	v_mfma_f32_16x16x32_bf16 v[28:31], v[132:135], v[164:167], v[28:31]
	v_mfma_f32_16x16x32_bf16 v[24:27], v[140:143], v[164:167], v[24:27]
	v_mfma_f32_16x16x32_bf16 v[12:15], v[132:135], v[172:175], v[12:15]
	v_mfma_f32_16x16x32_bf16 v[8:11], v[140:143], v[172:175], v[8:11]
	s_barrier
	s_add_u32 s34, s34, 0x20080
	s_addc_u32 s35, s35, 0
	s_add_i32 s36, s36, s45
	s_mov_b32 m0, s36
	s_nop 0
	global_load_lds_dwordx4 v192, s[34:35]
	s_add_i32 m0, s36, 0x2000
	s_nop 0
	global_load_lds_dwordx4 v210, s[34:35]
	s_waitcnt vmcnt(6)
	s_barrier
	v_mfma_f32_16x16x32_bf16 v[52:55], v[176:179], v[144:147], v[52:55]
	v_mfma_f32_16x16x32_bf16 v[48:51], v[184:187], v[144:147], v[48:51]
	v_mfma_f32_16x16x32_bf16 v[36:39], v[176:179], v[152:155], v[36:39]
	v_mfma_f32_16x16x32_bf16 v[32:35], v[184:187], v[152:155], v[32:35]
	v_mfma_f32_16x16x32_bf16 v[20:23], v[176:179], v[160:163], v[20:23]
	v_mfma_f32_16x16x32_bf16 v[16:19], v[184:187], v[160:163], v[16:19]
	v_mfma_f32_16x16x32_bf16 v[4:7], v[176:179], v[168:171], v[4:7]
	v_mfma_f32_16x16x32_bf16 v[0:3], v[184:187], v[168:171], v[0:3]
	v_mfma_f32_16x16x32_bf16 v[52:55], v[180:183], v[148:151], v[52:55]
	v_mfma_f32_16x16x32_bf16 v[48:51], v[188:191], v[148:151], v[48:51]
	v_mfma_f32_16x16x32_bf16 v[36:39], v[180:183], v[156:159], v[36:39]
	v_mfma_f32_16x16x32_bf16 v[32:35], v[188:191], v[156:159], v[32:35]
	v_mfma_f32_16x16x32_bf16 v[20:23], v[180:183], v[164:167], v[20:23]
	v_mfma_f32_16x16x32_bf16 v[16:19], v[188:191], v[164:167], v[16:19]
	v_mfma_f32_16x16x32_bf16 v[4:7], v[180:183], v[172:175], v[4:7]
	v_mfma_f32_16x16x32_bf16 v[0:3], v[188:191], v[172:175], v[0:3]
	s_add_i32 s52, s52, 2
	s_add_u32 s30, s30, 0x100
	s_addc_u32 s31, s31, 0
	s_add_u32 s27, s27, 0x100
	s_addc_u32 s33, s33, 0
	s_cmp_gt_u32 s52, 5
	s_barrier
	s_cbranch_scc0 .LBB0_2484
	v_mov_b32_e32 v128, v252
	s_lshl_b32 s1, s28, 8
	v_readfirstlane_b32 s0, v128
	s_ashr_i32 s15, s0, 2
	s_andn2_b32 s15, s15, 63
	s_lshr_b32 s0, s0, 1
	s_add_i32 s15, s15, s1
	s_and_b32 s0, s0, 0x60
	s_lshl_b32 s1, s26, 8
	v_and_or_b32 v218, v128, 15, s15
	v_lshrrev_b32_e32 v128, 1, v128
	s_or_b32 s0, s0, s1
	v_and_b32_e32 v129, 64, v195
	v_and_or_b32 v216, v128, 24, s0
	v_xor_b32_e32 v128, 16, v195
	v_add_u32_e32 v129, 64, v129
	v_cmp_lt_i32_e32 vcc, v128, v129
	v_ashrrev_i32_e32 v219, 31, v218
	v_ashrrev_i32_e32 v217, 31, v216
	v_cndmask_b32_e32 v128, v195, v128, vcc
	v_lshlrev_b32_e32 v200, 2, v128
	v_xor_b32_e32 v128, 32, v195
	v_cmp_lt_i32_e32 vcc, v128, v129
	v_or_b32_e32 v220, 0x80, v216
	v_ashrrev_i32_e32 v221, 31, v220
	v_cndmask_b32_e32 v128, v195, v128, vcc
	v_lshlrev_b32_e32 v199, 2, v128
	v_lshlrev_b64 v[128:129], 10, v[218:219]
	v_lshl_add_u64 v[130:131], v[128:129], 0, v[216:217]
	v_lshlrev_b64 v[130:131], 1, v[130:131]
	v_lshl_add_u64 v[246:247], s[8:9], 0, v[130:131]
	v_lshl_add_u64 v[250:251], s[10:11], 0, v[130:131]
	global_load_dwordx4 v[188:191], v[246:247], off
	global_load_dwordx4 v[180:183], v[246:247], off offset:256
	global_load_dwordx4 v[184:187], v[250:251], off
	v_or_b32_e32 v242, 16, v218
	v_lshl_add_u64 v[128:129], v[128:129], 0, v[220:221]
	v_ashrrev_i32_e32 v243, 31, v242
	v_lshl_add_u64 v[248:249], v[128:129], 1, s[10:11]
	v_lshlrev_b64 v[128:129], 10, v[242:243]
	v_or_b32_e32 v234, 32, v218
	v_lshl_add_u64 v[130:131], v[128:129], 0, v[216:217]
	v_lshl_add_u64 v[128:129], v[128:129], 0, v[220:221]
	v_ashrrev_i32_e32 v235, 31, v234
	v_lshlrev_b64 v[130:131], 1, v[130:131]
	v_lshl_add_u64 v[240:241], v[128:129], 1, s[10:11]
	v_lshlrev_b64 v[128:129], 10, v[234:235]
	v_or_b32_e32 v226, 48, v218
	v_lshl_add_u64 v[238:239], s[8:9], 0, v[130:131]
	v_lshl_add_u64 v[244:245], s[10:11], 0, v[130:131]
	v_lshl_add_u64 v[130:131], v[128:129], 0, v[216:217]
	v_lshl_add_u64 v[128:129], v[128:129], 0, v[220:221]
	v_ashrrev_i32_e32 v227, 31, v226
	v_lshlrev_b64 v[130:131], 1, v[130:131]
	v_lshl_add_u64 v[232:233], v[128:129], 1, s[10:11]
	v_lshlrev_b64 v[128:129], 10, v[226:227]
	v_lshl_add_u64 v[228:229], s[8:9], 0, v[130:131]
	v_lshl_add_u64 v[236:237], s[10:11], 0, v[130:131]
	v_lshl_add_u64 v[130:131], v[128:129], 0, v[216:217]
	v_lshlrev_b64 v[130:131], 1, v[130:131]
	v_lshl_add_u64 v[132:133], v[128:129], 0, v[220:221]
	v_lshl_add_u64 v[222:223], s[8:9], 0, v[130:131]
	v_lshl_add_u64 v[230:231], s[10:11], 0, v[130:131]
	v_lshl_add_u64 v[224:225], v[132:133], 1, s[10:11]
	global_load_dwordx4 v[176:179], v[248:249], off
	global_load_dwordx4 v[172:175], v[238:239], off
	global_load_dwordx4 v[164:167], v[238:239], off offset:256
	global_load_dwordx4 v[168:171], v[244:245], off
	global_load_dwordx4 v[160:163], v[240:241], off
	global_load_dwordx4 v[156:159], v[228:229], off
	global_load_dwordx4 v[132:135], v[224:225], off
	global_load_dwordx4 v[152:155], v[236:237], off
	global_load_dwordx4 v[144:147], v[232:233], off
	global_load_dwordx4 v[148:151], v[228:229], off offset:256
	global_load_dwordx4 v[136:139], v[230:231], off
	global_load_dwordx4 v[140:143], v[222:223], off
	global_load_dwordx4 v[128:131], v[222:223], off offset:256
	v_cmp_gt_u32_e32 vcc, 16, v195
	s_waitcnt vmcnt(0)
	v_lshlrev_b32_e32 v202, 16, v188
	v_and_b32_e32 v203, 0xffff0000, v188
	v_lshlrev_b32_e32 v204, 16, v184
	v_and_b32_e32 v205, 0xffff0000, v184
	v_lshlrev_b32_e32 v188, 16, v189
	v_and_b32_e32 v189, 0xffff0000, v189
	v_lshlrev_b32_e32 v184, 16, v185
	v_and_b32_e32 v185, 0xffff0000, v185
	v_pk_add_f32 v[202:203], v[202:203], v[204:205]
	v_pk_add_f32 v[184:185], v[188:189], v[184:185]
	v_pk_add_f32 v[188:189], v[124:125], v[202:203]
	v_pk_add_f32 v[184:185], v[126:127], v[184:185]
	v_lshlrev_b32_e32 v124, 16, v190
	v_and_b32_e32 v125, 0xffff0000, v190
	v_lshlrev_b32_e32 v126, 16, v186
	v_and_b32_e32 v127, 0xffff0000, v186
	v_pk_add_f32 v[124:125], v[124:125], v[126:127]
	v_lshlrev_b32_e32 v126, 16, v191
	v_and_b32_e32 v127, 0xffff0000, v191
	v_lshlrev_b32_e32 v186, 16, v187
	v_and_b32_e32 v187, 0xffff0000, v187
	v_pk_add_f32 v[126:127], v[126:127], v[186:187]
	v_pk_add_f32 v[190:191], v[120:121], v[124:125]
	v_cvt_pk_bf16_f32 v120, v188, v189
	v_pk_add_f32 v[186:187], v[122:123], v[126:127]
	v_and_b32_e32 v123, 0xffff0000, v120
	v_lshlrev_b32_e32 v122, 16, v120
	v_pk_add_f32 v[122:123], v[188:189], v[122:123] neg_lo:[0,1] neg_hi:[0,1]
	v_cvt_pk_bf16_f32 v121, v184, v185
	v_cvt_pk_bf16_f32 v124, v122, v123
	v_and_b32_e32 v123, 0xffff0000, v121
	v_lshlrev_b32_e32 v122, 16, v121
	v_pk_add_f32 v[122:123], v[184:185], v[122:123] neg_lo:[0,1] neg_hi:[0,1]
	s_nop 0
	v_cvt_pk_bf16_f32 v125, v122, v123
	v_cvt_pk_bf16_f32 v122, v190, v191
	v_cvt_pk_bf16_f32 v123, v186, v187
	v_and_b32_e32 v127, 0xffff0000, v122
	v_lshlrev_b32_e32 v126, 16, v122
	v_and_b32_e32 v203, 0xffff0000, v123
	v_lshlrev_b32_e32 v202, 16, v123
	v_pk_add_f32 v[126:127], v[190:191], v[126:127] neg_lo:[0,1] neg_hi:[0,1]
	v_pk_add_f32 v[202:203], v[186:187], v[202:203] neg_lo:[0,1] neg_hi:[0,1]
	v_cvt_pk_bf16_f32 v126, v126, v127
	v_cvt_pk_bf16_f32 v127, v202, v203
	global_store_dwordx4 v[246:247], v[120:123], off
	global_store_dwordx4 v[250:251], v[124:127], off
	s_nop 0
	v_pk_mul_f32 v[122:123], v[190:191], v[190:191]
	v_pk_mul_f32 v[120:121], v[186:187], v[186:187]
	v_pk_fma_f32 v[122:123], v[188:189], v[188:189], v[122:123]
	v_pk_fma_f32 v[120:121], v[184:185], v[184:185], v[120:121]
	v_add_f32_e32 v122, v122, v123
	v_add_f32_e32 v120, v120, v122
	v_add_f32_e32 v120, v121, v120
	v_mov_b32_e32 v201, v120
	s_waitcnt lgkmcnt(0)
	v_lshl_add_u64 v[120:121], v[218:219], 2, s[12:13]
.LBB0_2487:
	v_lshlrev_b32_e32 v122, 16, v180
	s_waitcnt lgkmcnt(0)
	v_and_b32_e32 v123, 0xffff0000, v180
	v_lshlrev_b32_e32 v124, 16, v176
	v_and_b32_e32 v125, 0xffff0000, v176
	v_pk_add_f32 v[122:123], v[122:123], v[124:125]
	v_lshlrev_b32_e32 v124, 16, v181
	v_and_b32_e32 v125, 0xffff0000, v181
	v_lshlrev_b32_e32 v126, 16, v177
	v_and_b32_e32 v127, 0xffff0000, v177
	v_pk_add_f32 v[124:125], v[124:125], v[126:127]
	v_lshlrev_b32_e32 v126, 16, v179
	v_pk_add_f32 v[118:119], v[118:119], v[124:125]
	v_pk_add_f32 v[124:125], v[116:117], v[122:123]
	v_lshlrev_b32_e32 v116, 16, v182
	v_and_b32_e32 v117, 0xffff0000, v182
	v_lshlrev_b32_e32 v122, 16, v178
	v_and_b32_e32 v123, 0xffff0000, v178
	v_pk_add_f32 v[116:117], v[116:117], v[122:123]
	v_lshlrev_b32_e32 v122, 16, v183
	v_and_b32_e32 v123, 0xffff0000, v183
	v_and_b32_e32 v127, 0xffff0000, v179
	v_pk_add_f32 v[122:123], v[122:123], v[126:127]
	v_pk_add_f32 v[112:113], v[112:113], v[116:117]
	v_pk_add_f32 v[126:127], v[114:115], v[122:123]
	v_cvt_pk_bf16_f32 v114, v124, v125
	v_and_b32_e32 v117, 0xffff0000, v114
	v_lshlrev_b32_e32 v116, 16, v114
	v_pk_add_f32 v[116:117], v[124:125], v[116:117] neg_lo:[0,1] neg_hi:[0,1]
	v_cvt_pk_bf16_f32 v115, v118, v119
	v_cvt_pk_bf16_f32 v122, v116, v117
	v_and_b32_e32 v117, 0xffff0000, v115
	v_lshlrev_b32_e32 v116, 16, v115
	v_pk_add_f32 v[116:117], v[118:119], v[116:117] neg_lo:[0,1] neg_hi:[0,1]
	v_pk_mul_f32 v[178:179], v[126:127], v[126:127]
	v_cvt_pk_bf16_f32 v123, v116, v117
	v_cvt_pk_bf16_f32 v116, v112, v113
	v_and_b32_e32 v177, 0xffff0000, v116
	v_lshlrev_b32_e32 v176, 16, v116
	v_pk_add_f32 v[176:177], v[112:113], v[176:177] neg_lo:[0,1] neg_hi:[0,1]
	v_pk_mul_f32 v[112:113], v[112:113], v[112:113]
	v_pk_fma_f32 v[118:119], v[118:119], v[118:119], v[178:179]
	v_pk_fma_f32 v[112:113], v[124:125], v[124:125], v[112:113]
	v_cvt_pk_bf16_f32 v117, v126, v127
	v_add_f32_e32 v112, v112, v113
	v_add_f32_e32 v112, v118, v112
	v_add_f32_e32 v112, v119, v112
	v_add_f32_e32 v112, v201, v112
	ds_bpermute_b32 v113, v200, v112
	v_and_b32_e32 v119, 0xffff0000, v117
	v_lshlrev_b32_e32 v118, 16, v117
	v_pk_add_f32 v[118:119], v[126:127], v[118:119] neg_lo:[0,1] neg_hi:[0,1]
	v_cvt_pk_bf16_f32 v124, v176, v177
	s_waitcnt lgkmcnt(0)
	v_add_f32_e32 v112, v112, v113
	ds_bpermute_b32 v113, v199, v112
	v_cvt_pk_bf16_f32 v125, v118, v119
	global_store_dwordx4 v[246:247], v[114:117], off offset:256
	global_store_dwordx4 v[248:249], v[122:125], off
	s_and_saveexec_b64 s[26:27], vcc
	s_cbranch_execz .LBB0_2489
	s_waitcnt lgkmcnt(0)
	v_add_f32_e32 v112, v112, v113
	global_atomic_add_f32 v[120:121], v112, off
.LBB0_2489:
	s_or_b64 exec, exec, s[26:27]
	v_lshlrev_b32_e32 v112, 16, v172
	s_waitcnt lgkmcnt(0)
	v_and_b32_e32 v113, 0xffff0000, v172
	v_lshlrev_b32_e32 v114, 16, v168
	v_and_b32_e32 v115, 0xffff0000, v168
	v_pk_add_f32 v[112:113], v[112:113], v[114:115]
	v_lshlrev_b32_e32 v114, 16, v173
	v_and_b32_e32 v115, 0xffff0000, v173
	v_lshlrev_b32_e32 v116, 16, v169
	v_and_b32_e32 v117, 0xffff0000, v169
	v_pk_add_f32 v[114:115], v[114:115], v[116:117]
	v_pk_add_f32 v[118:119], v[108:109], v[112:113]
	v_pk_add_f32 v[116:117], v[110:111], v[114:115]
	v_lshlrev_b32_e32 v108, 16, v174
	v_and_b32_e32 v109, 0xffff0000, v174
	v_lshlrev_b32_e32 v110, 16, v170
	v_and_b32_e32 v111, 0xffff0000, v170
	v_pk_add_f32 v[108:109], v[108:109], v[110:111]
	v_lshlrev_b32_e32 v110, 16, v175
	v_and_b32_e32 v111, 0xffff0000, v175
	v_lshlrev_b32_e32 v112, 16, v171
	v_and_b32_e32 v113, 0xffff0000, v171
	v_pk_add_f32 v[110:111], v[110:111], v[112:113]
	v_pk_add_f32 v[104:105], v[104:105], v[108:109]
	v_cvt_pk_bf16_f32 v108, v118, v119
	v_pk_add_f32 v[106:107], v[106:107], v[110:111]
	v_and_b32_e32 v111, 0xffff0000, v108
	v_lshlrev_b32_e32 v110, 16, v108
	v_pk_add_f32 v[110:111], v[118:119], v[110:111] neg_lo:[0,1] neg_hi:[0,1]
	v_cvt_pk_bf16_f32 v109, v116, v117
	v_cvt_pk_bf16_f32 v112, v110, v111
	v_and_b32_e32 v111, 0xffff0000, v109
	v_lshlrev_b32_e32 v110, 16, v109
	v_pk_add_f32 v[110:111], v[116:117], v[110:111] neg_lo:[0,1] neg_hi:[0,1]
	v_pk_mul_f32 v[120:121], v[106:107], v[106:107]
	v_cvt_pk_bf16_f32 v113, v110, v111
	v_cvt_pk_bf16_f32 v110, v104, v105
	v_and_b32_e32 v115, 0xffff0000, v110
	v_lshlrev_b32_e32 v114, 16, v110
	v_pk_add_f32 v[114:115], v[104:105], v[114:115] neg_lo:[0,1] neg_hi:[0,1]
	v_pk_mul_f32 v[104:105], v[104:105], v[104:105]
	v_pk_fma_f32 v[116:117], v[116:117], v[116:117], v[120:121]
	v_pk_fma_f32 v[104:105], v[118:119], v[118:119], v[104:105]
	v_cvt_pk_bf16_f32 v114, v114, v115
	v_add_f32_e32 v104, v104, v105
	v_add_f32_e32 v104, v116, v104
	v_add_f32_e32 v115, v117, v104
	v_mov_b32_e32 v201, v115
	v_cvt_pk_bf16_f32 v111, v106, v107
	v_and_b32_e32 v105, 0xffff0000, v111
	v_lshlrev_b32_e32 v104, 16, v111
	v_pk_add_f32 v[104:105], v[106:107], v[104:105] neg_lo:[0,1] neg_hi:[0,1]
	s_waitcnt lgkmcnt(0)
	v_cvt_pk_bf16_f32 v115, v104, v105
	v_lshl_add_u64 v[104:105], v[242:243], 2, s[12:13]
	global_store_dwordx4 v[238:239], v[108:111], off
	global_store_dwordx4 v[244:245], v[112:115], off
.LBB0_2491:
	v_lshlrev_b32_e32 v106, 16, v164
	s_waitcnt lgkmcnt(0)
	v_and_b32_e32 v107, 0xffff0000, v164
	v_lshlrev_b32_e32 v108, 16, v160
	v_and_b32_e32 v109, 0xffff0000, v160
	v_pk_add_f32 v[106:107], v[106:107], v[108:109]
	v_lshlrev_b32_e32 v108, 16, v165
	v_and_b32_e32 v109, 0xffff0000, v165
	v_lshlrev_b32_e32 v110, 16, v161
	v_and_b32_e32 v111, 0xffff0000, v161
	v_pk_add_f32 v[108:109], v[108:109], v[110:111]
	v_lshlrev_b32_e32 v110, 16, v163
	v_pk_add_f32 v[102:103], v[102:103], v[108:109]
	v_pk_add_f32 v[108:109], v[100:101], v[106:107]
	v_lshlrev_b32_e32 v100, 16, v166
	v_and_b32_e32 v101, 0xffff0000, v166
	v_lshlrev_b32_e32 v106, 16, v162
	v_and_b32_e32 v107, 0xffff0000, v162
	v_pk_add_f32 v[100:101], v[100:101], v[106:107]
	v_lshlrev_b32_e32 v106, 16, v167
	v_and_b32_e32 v107, 0xffff0000, v167
	v_and_b32_e32 v111, 0xffff0000, v163
	v_pk_add_f32 v[106:107], v[106:107], v[110:111]
	v_pk_add_f32 v[96:97], v[96:97], v[100:101]
	v_pk_add_f32 v[110:111], v[98:99], v[106:107]
	v_cvt_pk_bf16_f32 v98, v108, v109
	v_and_b32_e32 v101, 0xffff0000, v98
	v_lshlrev_b32_e32 v100, 16, v98
	v_pk_add_f32 v[100:101], v[108:109], v[100:101] neg_lo:[0,1] neg_hi:[0,1]
	v_cvt_pk_bf16_f32 v99, v102, v103
	v_cvt_pk_bf16_f32 v106, v100, v101
	v_and_b32_e32 v101, 0xffff0000, v99
	v_lshlrev_b32_e32 v100, 16, v99
	v_pk_add_f32 v[100:101], v[102:103], v[100:101] neg_lo:[0,1] neg_hi:[0,1]
	v_pk_mul_f32 v[114:115], v[110:111], v[110:111]
	v_cvt_pk_bf16_f32 v107, v100, v101
	v_cvt_pk_bf16_f32 v100, v96, v97
	v_and_b32_e32 v113, 0xffff0000, v100
	v_lshlrev_b32_e32 v112, 16, v100
	v_pk_add_f32 v[112:113], v[96:97], v[112:113] neg_lo:[0,1] neg_hi:[0,1]
	v_pk_mul_f32 v[96:97], v[96:97], v[96:97]
	v_pk_fma_f32 v[102:103], v[102:103], v[102:103], v[114:115]
	v_pk_fma_f32 v[96:97], v[108:109], v[108:109], v[96:97]
	v_cvt_pk_bf16_f32 v101, v110, v111
	v_add_f32_e32 v96, v96, v97
	v_add_f32_e32 v96, v102, v96
	v_add_f32_e32 v96, v103, v96
	v_add_f32_e32 v96, v201, v96
	ds_bpermute_b32 v97, v200, v96
	v_and_b32_e32 v103, 0xffff0000, v101
	v_lshlrev_b32_e32 v102, 16, v101
	v_pk_add_f32 v[102:103], v[110:111], v[102:103] neg_lo:[0,1] neg_hi:[0,1]
	v_cvt_pk_bf16_f32 v108, v112, v113
	s_waitcnt lgkmcnt(0)
	v_add_f32_e32 v96, v96, v97
	ds_bpermute_b32 v97, v199, v96
	v_cvt_pk_bf16_f32 v109, v102, v103
	global_store_dwordx4 v[238:239], v[98:101], off offset:256
	global_store_dwordx4 v[240:241], v[106:109], off
	s_and_saveexec_b64 s[26:27], vcc
	s_cbranch_execz .LBB0_2493
	s_waitcnt lgkmcnt(0)
	v_add_f32_e32 v96, v96, v97
	global_atomic_add_f32 v[104:105], v96, off
.LBB0_2493:
	s_or_b64 exec, exec, s[26:27]
	v_lshlrev_b32_e32 v96, 16, v156
	s_waitcnt lgkmcnt(0)
	v_and_b32_e32 v97, 0xffff0000, v156
	v_lshlrev_b32_e32 v98, 16, v152
	v_and_b32_e32 v99, 0xffff0000, v152
	v_pk_add_f32 v[96:97], v[96:97], v[98:99]
	v_lshlrev_b32_e32 v98, 16, v157
	v_and_b32_e32 v99, 0xffff0000, v157
	v_lshlrev_b32_e32 v100, 16, v153
	v_and_b32_e32 v101, 0xffff0000, v153
	v_pk_add_f32 v[98:99], v[98:99], v[100:101]
	v_pk_add_f32 v[102:103], v[92:93], v[96:97]
	v_pk_add_f32 v[100:101], v[94:95], v[98:99]
	v_lshlrev_b32_e32 v92, 16, v158
	v_and_b32_e32 v93, 0xffff0000, v158
	v_lshlrev_b32_e32 v94, 16, v154
	v_and_b32_e32 v95, 0xffff0000, v154
	v_pk_add_f32 v[92:93], v[92:93], v[94:95]
	v_lshlrev_b32_e32 v94, 16, v159
	v_and_b32_e32 v95, 0xffff0000, v159
	v_lshlrev_b32_e32 v96, 16, v155
	v_and_b32_e32 v97, 0xffff0000, v155
	v_pk_add_f32 v[94:95], v[94:95], v[96:97]
	v_pk_add_f32 v[88:89], v[88:89], v[92:93]
	v_cvt_pk_bf16_f32 v92, v102, v103
	v_pk_add_f32 v[90:91], v[90:91], v[94:95]
	v_and_b32_e32 v95, 0xffff0000, v92
	v_lshlrev_b32_e32 v94, 16, v92
	v_pk_add_f32 v[94:95], v[102:103], v[94:95] neg_lo:[0,1] neg_hi:[0,1]
	v_cvt_pk_bf16_f32 v93, v100, v101
	v_cvt_pk_bf16_f32 v96, v94, v95
	v_and_b32_e32 v95, 0xffff0000, v93
	v_lshlrev_b32_e32 v94, 16, v93
	v_pk_add_f32 v[94:95], v[100:101], v[94:95] neg_lo:[0,1] neg_hi:[0,1]
	v_pk_mul_f32 v[104:105], v[90:91], v[90:91]
	v_cvt_pk_bf16_f32 v97, v94, v95
	v_cvt_pk_bf16_f32 v94, v88, v89
	v_and_b32_e32 v99, 0xffff0000, v94
	v_lshlrev_b32_e32 v98, 16, v94
	v_pk_add_f32 v[98:99], v[88:89], v[98:99] neg_lo:[0,1] neg_hi:[0,1]
	v_pk_mul_f32 v[88:89], v[88:89], v[88:89]
	v_pk_fma_f32 v[100:101], v[100:101], v[100:101], v[104:105]
	v_pk_fma_f32 v[88:89], v[102:103], v[102:103], v[88:89]
	v_cvt_pk_bf16_f32 v98, v98, v99
	v_add_f32_e32 v88, v88, v89
	v_add_f32_e32 v88, v100, v88
	v_add_f32_e32 v99, v101, v88
	v_mov_b32_e32 v201, v99
	v_cvt_pk_bf16_f32 v95, v90, v91
	v_and_b32_e32 v89, 0xffff0000, v95
	v_lshlrev_b32_e32 v88, 16, v95
	v_pk_add_f32 v[88:89], v[90:91], v[88:89] neg_lo:[0,1] neg_hi:[0,1]
	s_waitcnt lgkmcnt(0)
	v_cvt_pk_bf16_f32 v99, v88, v89
	v_lshl_add_u64 v[88:89], v[234:235], 2, s[12:13]
	global_store_dwordx4 v[228:229], v[92:95], off
	global_store_dwordx4 v[236:237], v[96:99], off
.LBB0_2495:
	v_lshlrev_b32_e32 v90, 16, v148
	s_waitcnt lgkmcnt(0)
	v_and_b32_e32 v91, 0xffff0000, v148
	v_lshlrev_b32_e32 v92, 16, v144
	v_and_b32_e32 v93, 0xffff0000, v144
	v_pk_add_f32 v[90:91], v[90:91], v[92:93]
	v_lshlrev_b32_e32 v92, 16, v149
	v_and_b32_e32 v93, 0xffff0000, v149
	v_lshlrev_b32_e32 v94, 16, v145
	v_and_b32_e32 v95, 0xffff0000, v145
	v_pk_add_f32 v[92:93], v[92:93], v[94:95]
	v_lshlrev_b32_e32 v94, 16, v147
	v_pk_add_f32 v[86:87], v[86:87], v[92:93]
	v_pk_add_f32 v[92:93], v[84:85], v[90:91]
	v_lshlrev_b32_e32 v84, 16, v150
	v_and_b32_e32 v85, 0xffff0000, v150
	v_lshlrev_b32_e32 v90, 16, v146
	v_and_b32_e32 v91, 0xffff0000, v146
	v_pk_add_f32 v[84:85], v[84:85], v[90:91]
	v_lshlrev_b32_e32 v90, 16, v151
	v_and_b32_e32 v91, 0xffff0000, v151
	v_and_b32_e32 v95, 0xffff0000, v147
	v_pk_add_f32 v[90:91], v[90:91], v[94:95]
	v_pk_add_f32 v[80:81], v[80:81], v[84:85]
	v_pk_add_f32 v[94:95], v[82:83], v[90:91]
	v_cvt_pk_bf16_f32 v82, v92, v93
	v_and_b32_e32 v85, 0xffff0000, v82
	v_lshlrev_b32_e32 v84, 16, v82
	v_pk_add_f32 v[84:85], v[92:93], v[84:85] neg_lo:[0,1] neg_hi:[0,1]
	v_cvt_pk_bf16_f32 v83, v86, v87
	v_cvt_pk_bf16_f32 v90, v84, v85
	v_and_b32_e32 v85, 0xffff0000, v83
	v_lshlrev_b32_e32 v84, 16, v83
	v_pk_add_f32 v[84:85], v[86:87], v[84:85] neg_lo:[0,1] neg_hi:[0,1]
	v_pk_mul_f32 v[98:99], v[94:95], v[94:95]
	v_cvt_pk_bf16_f32 v91, v84, v85
	v_cvt_pk_bf16_f32 v84, v80, v81
	v_and_b32_e32 v97, 0xffff0000, v84
	v_lshlrev_b32_e32 v96, 16, v84
	v_pk_add_f32 v[96:97], v[80:81], v[96:97] neg_lo:[0,1] neg_hi:[0,1]
	v_pk_mul_f32 v[80:81], v[80:81], v[80:81]
	v_pk_fma_f32 v[86:87], v[86:87], v[86:87], v[98:99]
	v_pk_fma_f32 v[80:81], v[92:93], v[92:93], v[80:81]
	v_cvt_pk_bf16_f32 v85, v94, v95
	v_add_f32_e32 v80, v80, v81
	v_add_f32_e32 v80, v86, v80
	v_add_f32_e32 v80, v87, v80
	v_add_f32_e32 v80, v201, v80
	ds_bpermute_b32 v81, v200, v80
	v_and_b32_e32 v87, 0xffff0000, v85
	v_lshlrev_b32_e32 v86, 16, v85
	v_pk_add_f32 v[86:87], v[94:95], v[86:87] neg_lo:[0,1] neg_hi:[0,1]
	v_cvt_pk_bf16_f32 v92, v96, v97
	s_waitcnt lgkmcnt(0)
	v_add_f32_e32 v80, v80, v81
	ds_bpermute_b32 v81, v199, v80
	v_cvt_pk_bf16_f32 v93, v86, v87
	global_store_dwordx4 v[228:229], v[82:85], off offset:256
	global_store_dwordx4 v[232:233], v[90:93], off
	s_and_saveexec_b64 s[26:27], vcc
	s_cbranch_execz .LBB0_2497
	s_waitcnt lgkmcnt(0)
	v_add_f32_e32 v80, v80, v81
	global_atomic_add_f32 v[88:89], v80, off
.LBB0_2497:
	s_or_b64 exec, exec, s[26:27]
	v_lshlrev_b32_e32 v80, 16, v140
	s_waitcnt lgkmcnt(0)
	v_and_b32_e32 v81, 0xffff0000, v140
	v_lshlrev_b32_e32 v82, 16, v136
	v_and_b32_e32 v83, 0xffff0000, v136
	v_pk_add_f32 v[80:81], v[80:81], v[82:83]
	v_lshlrev_b32_e32 v82, 16, v141
	v_and_b32_e32 v83, 0xffff0000, v141
	v_lshlrev_b32_e32 v84, 16, v137
	v_and_b32_e32 v85, 0xffff0000, v137
	v_pk_add_f32 v[82:83], v[82:83], v[84:85]
	v_pk_add_f32 v[86:87], v[76:77], v[80:81]
	v_pk_add_f32 v[84:85], v[78:79], v[82:83]
	v_lshlrev_b32_e32 v76, 16, v142
	v_and_b32_e32 v77, 0xffff0000, v142
	v_lshlrev_b32_e32 v78, 16, v138
	v_and_b32_e32 v79, 0xffff0000, v138
	v_pk_add_f32 v[76:77], v[76:77], v[78:79]
	v_lshlrev_b32_e32 v78, 16, v143
	v_and_b32_e32 v79, 0xffff0000, v143
	v_lshlrev_b32_e32 v80, 16, v139
	v_and_b32_e32 v81, 0xffff0000, v139
	v_pk_add_f32 v[78:79], v[78:79], v[80:81]
	v_pk_add_f32 v[72:73], v[72:73], v[76:77]
	v_cvt_pk_bf16_f32 v76, v86, v87
	v_pk_add_f32 v[74:75], v[74:75], v[78:79]
	v_and_b32_e32 v79, 0xffff0000, v76
	v_lshlrev_b32_e32 v78, 16, v76
	v_pk_add_f32 v[78:79], v[86:87], v[78:79] neg_lo:[0,1] neg_hi:[0,1]
	v_cvt_pk_bf16_f32 v77, v84, v85
	v_cvt_pk_bf16_f32 v80, v78, v79
	v_and_b32_e32 v79, 0xffff0000, v77
	v_lshlrev_b32_e32 v78, 16, v77
	v_pk_add_f32 v[78:79], v[84:85], v[78:79] neg_lo:[0,1] neg_hi:[0,1]
	v_pk_mul_f32 v[88:89], v[74:75], v[74:75]
	v_cvt_pk_bf16_f32 v81, v78, v79
	v_cvt_pk_bf16_f32 v78, v72, v73
	v_and_b32_e32 v83, 0xffff0000, v78
	v_lshlrev_b32_e32 v82, 16, v78
	v_pk_add_f32 v[82:83], v[72:73], v[82:83] neg_lo:[0,1] neg_hi:[0,1]
	v_pk_mul_f32 v[72:73], v[72:73], v[72:73]
	v_pk_fma_f32 v[84:85], v[84:85], v[84:85], v[88:89]
	v_pk_fma_f32 v[72:73], v[86:87], v[86:87], v[72:73]
	v_cvt_pk_bf16_f32 v82, v82, v83
	v_add_f32_e32 v72, v72, v73
	v_add_f32_e32 v72, v84, v72
	v_add_f32_e32 v83, v85, v72
	v_mov_b32_e32 v201, v83
	v_cvt_pk_bf16_f32 v79, v74, v75
	v_and_b32_e32 v73, 0xffff0000, v79
	v_lshlrev_b32_e32 v72, 16, v79
	v_pk_add_f32 v[72:73], v[74:75], v[72:73] neg_lo:[0,1] neg_hi:[0,1]
	s_waitcnt lgkmcnt(0)
	v_cvt_pk_bf16_f32 v83, v72, v73
	v_lshl_add_u64 v[72:73], v[226:227], 2, s[12:13]
	global_store_dwordx4 v[222:223], v[76:79], off
	global_store_dwordx4 v[230:231], v[80:83], off
.LBB0_2499:
	v_lshlrev_b32_e32 v74, 16, v128
	s_waitcnt lgkmcnt(0)
	v_and_b32_e32 v75, 0xffff0000, v128
	v_lshlrev_b32_e32 v76, 16, v132
	v_and_b32_e32 v77, 0xffff0000, v132
	v_pk_add_f32 v[74:75], v[74:75], v[76:77]
	v_lshlrev_b32_e32 v76, 16, v129
	v_and_b32_e32 v77, 0xffff0000, v129
	v_lshlrev_b32_e32 v78, 16, v133
	v_and_b32_e32 v79, 0xffff0000, v133
	v_pk_add_f32 v[76:77], v[76:77], v[78:79]
	v_lshlrev_b32_e32 v78, 16, v135
	v_pk_add_f32 v[70:71], v[70:71], v[76:77]
	v_pk_add_f32 v[76:77], v[68:69], v[74:75]
	v_lshlrev_b32_e32 v68, 16, v130
	v_and_b32_e32 v69, 0xffff0000, v130
	v_lshlrev_b32_e32 v74, 16, v134
	v_and_b32_e32 v75, 0xffff0000, v134
	v_pk_add_f32 v[68:69], v[68:69], v[74:75]
	v_lshlrev_b32_e32 v74, 16, v131
	v_and_b32_e32 v75, 0xffff0000, v131
	v_and_b32_e32 v79, 0xffff0000, v135
	v_pk_add_f32 v[74:75], v[74:75], v[78:79]
	v_pk_add_f32 v[64:65], v[64:65], v[68:69]
	v_pk_add_f32 v[78:79], v[66:67], v[74:75]
	v_cvt_pk_bf16_f32 v66, v76, v77
	v_and_b32_e32 v69, 0xffff0000, v66
	v_lshlrev_b32_e32 v68, 16, v66
	v_pk_add_f32 v[68:69], v[76:77], v[68:69] neg_lo:[0,1] neg_hi:[0,1]
	v_cvt_pk_bf16_f32 v67, v70, v71
	v_cvt_pk_bf16_f32 v74, v68, v69
	v_and_b32_e32 v69, 0xffff0000, v67
	v_lshlrev_b32_e32 v68, 16, v67
	v_pk_add_f32 v[68:69], v[70:71], v[68:69] neg_lo:[0,1] neg_hi:[0,1]
	v_pk_mul_f32 v[82:83], v[78:79], v[78:79]
	v_cvt_pk_bf16_f32 v75, v68, v69
	v_cvt_pk_bf16_f32 v68, v64, v65
	v_and_b32_e32 v81, 0xffff0000, v68
	v_lshlrev_b32_e32 v80, 16, v68
	v_pk_add_f32 v[80:81], v[64:65], v[80:81] neg_lo:[0,1] neg_hi:[0,1]
	v_pk_mul_f32 v[64:65], v[64:65], v[64:65]
	v_pk_fma_f32 v[70:71], v[70:71], v[70:71], v[82:83]
	v_pk_fma_f32 v[64:65], v[76:77], v[76:77], v[64:65]
	v_cvt_pk_bf16_f32 v69, v78, v79
	v_add_f32_e32 v64, v64, v65
	v_add_f32_e32 v64, v70, v64
	v_add_f32_e32 v64, v71, v64
	v_add_f32_e32 v64, v201, v64
	ds_bpermute_b32 v65, v200, v64
	v_and_b32_e32 v71, 0xffff0000, v69
	v_lshlrev_b32_e32 v70, 16, v69
	v_pk_add_f32 v[70:71], v[78:79], v[70:71] neg_lo:[0,1] neg_hi:[0,1]
	v_cvt_pk_bf16_f32 v76, v80, v81
	s_waitcnt lgkmcnt(0)
	v_add_f32_e32 v64, v64, v65
	ds_bpermute_b32 v65, v199, v64
	v_cvt_pk_bf16_f32 v77, v70, v71
	global_store_dwordx4 v[222:223], v[66:69], off offset:256
	global_store_dwordx4 v[224:225], v[74:77], off
	s_and_saveexec_b64 s[26:27], vcc
	s_cbranch_execz .LBB0_2501
	s_waitcnt lgkmcnt(0)
	v_add_f32_e32 v64, v64, v65
	global_atomic_add_f32 v[72:73], v64, off
.LBB0_2501:
	s_or_b64 exec, exec, s[26:27]
	v_add_u32_e32 v156, 0x80, v218
	v_ashrrev_i32_e32 v157, 31, v156
	s_waitcnt lgkmcnt(0)
	v_lshlrev_b64 v[64:65], 10, v[156:157]
	v_lshl_add_u64 v[66:67], v[64:65], 0, v[216:217]
	v_lshlrev_b64 v[66:67], 1, v[66:67]
	v_lshl_add_u64 v[152:153], s[8:9], 0, v[66:67]
	v_lshl_add_u64 v[158:159], s[10:11], 0, v[66:67]
	global_load_dwordx4 v[124:127], v[152:153], off
	global_load_dwordx4 v[116:119], v[152:153], off offset:256
	global_load_dwordx4 v[120:123], v[158:159], off
	v_add_u32_e32 v148, 0x90, v218
	v_lshl_add_u64 v[64:65], v[64:65], 0, v[220:221]
	v_ashrrev_i32_e32 v149, 31, v148
	v_lshl_add_u64 v[154:155], v[64:65], 1, s[10:11]
	v_lshlrev_b64 v[64:65], 10, v[148:149]
	v_add_u32_e32 v140, 0xa0, v218
	v_lshl_add_u64 v[66:67], v[64:65], 0, v[216:217]
	v_lshl_add_u64 v[64:65], v[64:65], 0, v[220:221]
	v_ashrrev_i32_e32 v141, 31, v140
	v_lshlrev_b64 v[66:67], 1, v[66:67]
	v_lshl_add_u64 v[146:147], v[64:65], 1, s[10:11]
	v_lshlrev_b64 v[64:65], 10, v[140:141]
	v_add_u32_e32 v132, 0xb0, v218
	v_lshl_add_u64 v[144:145], s[8:9], 0, v[66:67]
	v_lshl_add_u64 v[150:151], s[10:11], 0, v[66:67]
	v_lshl_add_u64 v[66:67], v[64:65], 0, v[216:217]
	v_lshl_add_u64 v[64:65], v[64:65], 0, v[220:221]
	v_ashrrev_i32_e32 v133, 31, v132
	v_lshlrev_b64 v[66:67], 1, v[66:67]
	v_lshl_add_u64 v[138:139], v[64:65], 1, s[10:11]
	v_lshlrev_b64 v[64:65], 10, v[132:133]
	v_lshl_add_u64 v[136:137], s[8:9], 0, v[66:67]
	v_lshl_add_u64 v[142:143], s[10:11], 0, v[66:67]
	v_lshl_add_u64 v[66:67], v[64:65], 0, v[216:217]
	v_lshlrev_b64 v[66:67], 1, v[66:67]
	v_lshl_add_u64 v[76:77], v[64:65], 0, v[220:221]
	v_lshl_add_u64 v[128:129], s[8:9], 0, v[66:67]
	v_lshl_add_u64 v[134:135], s[10:11], 0, v[66:67]
	v_lshl_add_u64 v[130:131], v[76:77], 1, s[10:11]
	global_load_dwordx4 v[112:115], v[154:155], off
	global_load_dwordx4 v[108:111], v[144:145], off
	global_load_dwordx4 v[100:103], v[144:145], off offset:256
	global_load_dwordx4 v[104:107], v[150:151], off
	global_load_dwordx4 v[96:99], v[146:147], off
	global_load_dwordx4 v[92:95], v[136:137], off
	global_load_dwordx4 v[84:87], v[136:137], off offset:256
	global_load_dwordx4 v[88:91], v[142:143], off
	global_load_dwordx4 v[80:83], v[138:139], off
	global_load_dwordx4 v[72:75], v[128:129], off
	global_load_dwordx4 v[64:67], v[128:129], off offset:256
	global_load_dwordx4 v[68:71], v[134:135], off
	global_load_dwordx4 v[76:79], v[130:131], off
	s_waitcnt vmcnt(15)
	v_lshlrev_b32_e32 v160, 16, v124
	v_and_b32_e32 v161, 0xffff0000, v124
	s_waitcnt vmcnt(13)
	v_lshlrev_b32_e32 v162, 16, v120
	v_and_b32_e32 v163, 0xffff0000, v120
	v_lshlrev_b32_e32 v124, 16, v125
	v_and_b32_e32 v125, 0xffff0000, v125
	v_lshlrev_b32_e32 v120, 16, v121
	v_and_b32_e32 v121, 0xffff0000, v121
	v_pk_add_f32 v[160:161], v[160:161], v[162:163]
	v_pk_add_f32 v[120:121], v[124:125], v[120:121]
	v_pk_add_f32 v[124:125], v[60:61], v[160:161]
	v_pk_add_f32 v[120:121], v[62:63], v[120:121]
	v_lshlrev_b32_e32 v60, 16, v126
	v_and_b32_e32 v61, 0xffff0000, v126
	v_lshlrev_b32_e32 v62, 16, v122
	v_and_b32_e32 v63, 0xffff0000, v122
	v_pk_add_f32 v[60:61], v[60:61], v[62:63]
	v_lshlrev_b32_e32 v62, 16, v127
	v_and_b32_e32 v63, 0xffff0000, v127
	v_lshlrev_b32_e32 v122, 16, v123
	v_and_b32_e32 v123, 0xffff0000, v123
	v_pk_add_f32 v[62:63], v[62:63], v[122:123]
	v_pk_add_f32 v[126:127], v[56:57], v[60:61]
	v_cvt_pk_bf16_f32 v56, v124, v125
	v_pk_add_f32 v[122:123], v[58:59], v[62:63]
	v_and_b32_e32 v59, 0xffff0000, v56
	v_lshlrev_b32_e32 v58, 16, v56
	v_pk_add_f32 v[58:59], v[124:125], v[58:59] neg_lo:[0,1] neg_hi:[0,1]
	v_cvt_pk_bf16_f32 v57, v120, v121
	v_cvt_pk_bf16_f32 v60, v58, v59
	v_and_b32_e32 v59, 0xffff0000, v57
	v_lshlrev_b32_e32 v58, 16, v57
	v_pk_add_f32 v[58:59], v[120:121], v[58:59] neg_lo:[0,1] neg_hi:[0,1]
	s_nop 0
	v_cvt_pk_bf16_f32 v61, v58, v59
	v_cvt_pk_bf16_f32 v58, v126, v127
	v_cvt_pk_bf16_f32 v59, v122, v123
	v_and_b32_e32 v63, 0xffff0000, v58
	v_lshlrev_b32_e32 v62, 16, v58
	v_and_b32_e32 v161, 0xffff0000, v59
	v_lshlrev_b32_e32 v160, 16, v59
	v_pk_add_f32 v[62:63], v[126:127], v[62:63] neg_lo:[0,1] neg_hi:[0,1]
	v_pk_add_f32 v[160:161], v[122:123], v[160:161] neg_lo:[0,1] neg_hi:[0,1]
	v_cvt_pk_bf16_f32 v62, v62, v63
	v_cvt_pk_bf16_f32 v63, v160, v161
	global_store_dwordx4 v[152:153], v[56:59], off
	global_store_dwordx4 v[158:159], v[60:63], off
	s_nop 0
	v_pk_mul_f32 v[58:59], v[126:127], v[126:127]
	v_pk_mul_f32 v[56:57], v[122:123], v[122:123]
	v_pk_fma_f32 v[58:59], v[124:125], v[124:125], v[58:59]
	v_pk_fma_f32 v[56:57], v[120:121], v[120:121], v[56:57]
	v_add_f32_e32 v58, v58, v59
	v_add_f32_e32 v56, v56, v58
	v_add_f32_e32 v56, v57, v56
	v_mov_b32_e32 v201, v56
	s_waitcnt lgkmcnt(0)
	v_lshl_add_u64 v[56:57], v[156:157], 2, s[12:13]
.LBB0_2503:
	v_lshlrev_b32_e32 v58, 16, v116
	s_waitcnt lgkmcnt(0)
	v_and_b32_e32 v59, 0xffff0000, v116
	s_waitcnt vmcnt(13)
	v_lshlrev_b32_e32 v60, 16, v112
	v_and_b32_e32 v61, 0xffff0000, v112
	v_pk_add_f32 v[58:59], v[58:59], v[60:61]
	v_lshlrev_b32_e32 v60, 16, v117
	v_and_b32_e32 v61, 0xffff0000, v117
	v_lshlrev_b32_e32 v62, 16, v113
	v_and_b32_e32 v63, 0xffff0000, v113
	v_pk_add_f32 v[60:61], v[60:61], v[62:63]
	v_lshlrev_b32_e32 v62, 16, v115
	v_pk_add_f32 v[54:55], v[54:55], v[60:61]
	v_pk_add_f32 v[60:61], v[52:53], v[58:59]
	v_lshlrev_b32_e32 v52, 16, v118
	v_and_b32_e32 v53, 0xffff0000, v118
	v_lshlrev_b32_e32 v58, 16, v114
	v_and_b32_e32 v59, 0xffff0000, v114
	v_pk_add_f32 v[52:53], v[52:53], v[58:59]
	v_lshlrev_b32_e32 v58, 16, v119
	v_and_b32_e32 v59, 0xffff0000, v119
	v_and_b32_e32 v63, 0xffff0000, v115
	v_pk_add_f32 v[58:59], v[58:59], v[62:63]
	v_pk_add_f32 v[48:49], v[48:49], v[52:53]
	v_pk_add_f32 v[62:63], v[50:51], v[58:59]
	v_cvt_pk_bf16_f32 v50, v60, v61
	v_and_b32_e32 v53, 0xffff0000, v50
	v_lshlrev_b32_e32 v52, 16, v50
	v_pk_add_f32 v[52:53], v[60:61], v[52:53] neg_lo:[0,1] neg_hi:[0,1]
	v_cvt_pk_bf16_f32 v51, v54, v55
	v_cvt_pk_bf16_f32 v58, v52, v53
	v_and_b32_e32 v53, 0xffff0000, v51
	v_lshlrev_b32_e32 v52, 16, v51
	v_pk_add_f32 v[52:53], v[54:55], v[52:53] neg_lo:[0,1] neg_hi:[0,1]
	v_pk_mul_f32 v[114:115], v[62:63], v[62:63]
	v_cvt_pk_bf16_f32 v59, v52, v53
	v_cvt_pk_bf16_f32 v52, v48, v49
	v_and_b32_e32 v113, 0xffff0000, v52
	v_lshlrev_b32_e32 v112, 16, v52
	v_pk_add_f32 v[112:113], v[48:49], v[112:113] neg_lo:[0,1] neg_hi:[0,1]
	v_pk_mul_f32 v[48:49], v[48:49], v[48:49]
	v_pk_fma_f32 v[54:55], v[54:55], v[54:55], v[114:115]
	v_pk_fma_f32 v[48:49], v[60:61], v[60:61], v[48:49]
	v_cvt_pk_bf16_f32 v53, v62, v63
	v_add_f32_e32 v48, v48, v49
	v_add_f32_e32 v48, v54, v48
	v_add_f32_e32 v48, v55, v48
	v_add_f32_e32 v48, v201, v48
	ds_bpermute_b32 v49, v200, v48
	v_and_b32_e32 v55, 0xffff0000, v53
	v_lshlrev_b32_e32 v54, 16, v53
	v_pk_add_f32 v[54:55], v[62:63], v[54:55] neg_lo:[0,1] neg_hi:[0,1]
	v_cvt_pk_bf16_f32 v60, v112, v113
	s_waitcnt lgkmcnt(0)
	v_add_f32_e32 v48, v48, v49
	ds_bpermute_b32 v49, v199, v48
	v_cvt_pk_bf16_f32 v61, v54, v55
	global_store_dwordx4 v[152:153], v[50:53], off offset:256
	global_store_dwordx4 v[154:155], v[58:61], off
	s_and_saveexec_b64 s[26:27], vcc
	s_cbranch_execz .LBB0_2505
	s_waitcnt lgkmcnt(0)
	v_add_f32_e32 v48, v48, v49
	global_atomic_add_f32 v[56:57], v48, off
.LBB0_2505:
	s_or_b64 exec, exec, s[26:27]
	s_waitcnt vmcnt(14)
	v_lshlrev_b32_e32 v48, 16, v108
	s_waitcnt lgkmcnt(0)
	v_and_b32_e32 v49, 0xffff0000, v108
	s_waitcnt vmcnt(12)
	v_lshlrev_b32_e32 v50, 16, v104
	v_and_b32_e32 v51, 0xffff0000, v104
	v_pk_add_f32 v[48:49], v[48:49], v[50:51]
	v_lshlrev_b32_e32 v50, 16, v109
	v_and_b32_e32 v51, 0xffff0000, v109
	v_lshlrev_b32_e32 v52, 16, v105
	v_and_b32_e32 v53, 0xffff0000, v105
	v_pk_add_f32 v[50:51], v[50:51], v[52:53]
	v_pk_add_f32 v[54:55], v[44:45], v[48:49]
	v_pk_add_f32 v[52:53], v[46:47], v[50:51]
	v_lshlrev_b32_e32 v44, 16, v110
	v_and_b32_e32 v45, 0xffff0000, v110
	v_lshlrev_b32_e32 v46, 16, v106
	v_and_b32_e32 v47, 0xffff0000, v106
	v_pk_add_f32 v[44:45], v[44:45], v[46:47]
	v_lshlrev_b32_e32 v46, 16, v111
	v_and_b32_e32 v47, 0xffff0000, v111
	v_lshlrev_b32_e32 v48, 16, v107
	v_and_b32_e32 v49, 0xffff0000, v107
	v_pk_add_f32 v[46:47], v[46:47], v[48:49]
	v_pk_add_f32 v[40:41], v[40:41], v[44:45]
	v_cvt_pk_bf16_f32 v44, v54, v55
	v_pk_add_f32 v[42:43], v[42:43], v[46:47]
	v_and_b32_e32 v47, 0xffff0000, v44
	v_lshlrev_b32_e32 v46, 16, v44
	v_pk_add_f32 v[46:47], v[54:55], v[46:47] neg_lo:[0,1] neg_hi:[0,1]
	v_cvt_pk_bf16_f32 v45, v52, v53
	v_cvt_pk_bf16_f32 v48, v46, v47
	v_and_b32_e32 v47, 0xffff0000, v45
	v_lshlrev_b32_e32 v46, 16, v45
	v_pk_add_f32 v[46:47], v[52:53], v[46:47] neg_lo:[0,1] neg_hi:[0,1]
	v_pk_mul_f32 v[56:57], v[42:43], v[42:43]
	v_cvt_pk_bf16_f32 v49, v46, v47
	v_cvt_pk_bf16_f32 v46, v40, v41
	v_and_b32_e32 v51, 0xffff0000, v46
	v_lshlrev_b32_e32 v50, 16, v46
	v_pk_add_f32 v[50:51], v[40:41], v[50:51] neg_lo:[0,1] neg_hi:[0,1]
	v_pk_mul_f32 v[40:41], v[40:41], v[40:41]
	v_pk_fma_f32 v[52:53], v[52:53], v[52:53], v[56:57]
	v_pk_fma_f32 v[40:41], v[54:55], v[54:55], v[40:41]
	v_cvt_pk_bf16_f32 v50, v50, v51
	v_add_f32_e32 v40, v40, v41
	v_add_f32_e32 v40, v52, v40
	v_add_f32_e32 v51, v53, v40
	v_mov_b32_e32 v201, v51
	v_cvt_pk_bf16_f32 v47, v42, v43
	v_and_b32_e32 v41, 0xffff0000, v47
	v_lshlrev_b32_e32 v40, 16, v47
	v_pk_add_f32 v[40:41], v[42:43], v[40:41] neg_lo:[0,1] neg_hi:[0,1]
	s_waitcnt lgkmcnt(0)
	v_cvt_pk_bf16_f32 v51, v40, v41
	v_lshl_add_u64 v[40:41], v[148:149], 2, s[12:13]
	global_store_dwordx4 v[144:145], v[44:47], off
	global_store_dwordx4 v[150:151], v[48:51], off
.LBB0_2507:
	v_lshlrev_b32_e32 v42, 16, v100
	s_waitcnt lgkmcnt(0)
	v_and_b32_e32 v43, 0xffff0000, v100
	s_waitcnt vmcnt(12)
	v_lshlrev_b32_e32 v44, 16, v96
	v_and_b32_e32 v45, 0xffff0000, v96
	v_pk_add_f32 v[42:43], v[42:43], v[44:45]
	v_lshlrev_b32_e32 v44, 16, v101
	v_and_b32_e32 v45, 0xffff0000, v101
	v_lshlrev_b32_e32 v46, 16, v97
	v_and_b32_e32 v47, 0xffff0000, v97
	v_pk_add_f32 v[44:45], v[44:45], v[46:47]
	v_lshlrev_b32_e32 v46, 16, v99
	v_pk_add_f32 v[38:39], v[38:39], v[44:45]
	v_pk_add_f32 v[44:45], v[36:37], v[42:43]
	v_lshlrev_b32_e32 v36, 16, v102
	v_and_b32_e32 v37, 0xffff0000, v102
	v_lshlrev_b32_e32 v42, 16, v98
	v_and_b32_e32 v43, 0xffff0000, v98
	v_pk_add_f32 v[36:37], v[36:37], v[42:43]
	v_lshlrev_b32_e32 v42, 16, v103
	v_and_b32_e32 v43, 0xffff0000, v103
	v_and_b32_e32 v47, 0xffff0000, v99
	v_pk_add_f32 v[42:43], v[42:43], v[46:47]
	v_pk_add_f32 v[32:33], v[32:33], v[36:37]
	v_pk_add_f32 v[46:47], v[34:35], v[42:43]
	v_cvt_pk_bf16_f32 v34, v44, v45
	v_and_b32_e32 v37, 0xffff0000, v34
	v_lshlrev_b32_e32 v36, 16, v34
	v_pk_add_f32 v[36:37], v[44:45], v[36:37] neg_lo:[0,1] neg_hi:[0,1]
	v_cvt_pk_bf16_f32 v35, v38, v39
	v_cvt_pk_bf16_f32 v42, v36, v37
	v_and_b32_e32 v37, 0xffff0000, v35
	v_lshlrev_b32_e32 v36, 16, v35
	v_pk_add_f32 v[36:37], v[38:39], v[36:37] neg_lo:[0,1] neg_hi:[0,1]
	v_pk_mul_f32 v[50:51], v[46:47], v[46:47]
	v_cvt_pk_bf16_f32 v43, v36, v37
	v_cvt_pk_bf16_f32 v36, v32, v33
	v_and_b32_e32 v49, 0xffff0000, v36
	v_lshlrev_b32_e32 v48, 16, v36
	v_pk_add_f32 v[48:49], v[32:33], v[48:49] neg_lo:[0,1] neg_hi:[0,1]
	v_pk_mul_f32 v[32:33], v[32:33], v[32:33]
	v_pk_fma_f32 v[38:39], v[38:39], v[38:39], v[50:51]
	v_pk_fma_f32 v[32:33], v[44:45], v[44:45], v[32:33]
	v_cvt_pk_bf16_f32 v37, v46, v47
	v_add_f32_e32 v32, v32, v33
	v_add_f32_e32 v32, v38, v32
	v_add_f32_e32 v32, v39, v32
	v_add_f32_e32 v32, v201, v32
	ds_bpermute_b32 v33, v200, v32
	v_and_b32_e32 v39, 0xffff0000, v37
	v_lshlrev_b32_e32 v38, 16, v37
	v_pk_add_f32 v[38:39], v[46:47], v[38:39] neg_lo:[0,1] neg_hi:[0,1]
	v_cvt_pk_bf16_f32 v44, v48, v49
	s_waitcnt lgkmcnt(0)
	v_add_f32_e32 v32, v32, v33
	ds_bpermute_b32 v33, v199, v32
	v_cvt_pk_bf16_f32 v45, v38, v39
	global_store_dwordx4 v[144:145], v[34:37], off offset:256
	global_store_dwordx4 v[146:147], v[42:45], off
	s_and_saveexec_b64 s[26:27], vcc
	s_cbranch_execz .LBB0_2509
	s_waitcnt lgkmcnt(0)
	v_add_f32_e32 v32, v32, v33
	global_atomic_add_f32 v[40:41], v32, off
.LBB0_2509:
	s_or_b64 exec, exec, s[26:27]
	s_waitcnt vmcnt(13)
	v_lshlrev_b32_e32 v32, 16, v92
	s_waitcnt lgkmcnt(0)
	v_and_b32_e32 v33, 0xffff0000, v92
	s_waitcnt vmcnt(11)
	v_lshlrev_b32_e32 v34, 16, v88
	v_and_b32_e32 v35, 0xffff0000, v88
	v_pk_add_f32 v[32:33], v[32:33], v[34:35]
	v_lshlrev_b32_e32 v34, 16, v93
	v_and_b32_e32 v35, 0xffff0000, v93
	v_lshlrev_b32_e32 v36, 16, v89
	v_and_b32_e32 v37, 0xffff0000, v89
	v_pk_add_f32 v[34:35], v[34:35], v[36:37]
	v_pk_add_f32 v[38:39], v[28:29], v[32:33]
	v_pk_add_f32 v[36:37], v[30:31], v[34:35]
	v_lshlrev_b32_e32 v28, 16, v94
	v_and_b32_e32 v29, 0xffff0000, v94
	v_lshlrev_b32_e32 v30, 16, v90
	v_and_b32_e32 v31, 0xffff0000, v90
	v_pk_add_f32 v[28:29], v[28:29], v[30:31]
	v_lshlrev_b32_e32 v30, 16, v95
	v_and_b32_e32 v31, 0xffff0000, v95
	v_lshlrev_b32_e32 v32, 16, v91
	v_and_b32_e32 v33, 0xffff0000, v91
	v_pk_add_f32 v[30:31], v[30:31], v[32:33]
	v_pk_add_f32 v[24:25], v[24:25], v[28:29]
	v_cvt_pk_bf16_f32 v28, v38, v39
	v_pk_add_f32 v[26:27], v[26:27], v[30:31]
	v_and_b32_e32 v31, 0xffff0000, v28
	v_lshlrev_b32_e32 v30, 16, v28
	v_pk_add_f32 v[30:31], v[38:39], v[30:31] neg_lo:[0,1] neg_hi:[0,1]
	v_cvt_pk_bf16_f32 v29, v36, v37
	v_cvt_pk_bf16_f32 v32, v30, v31
	v_and_b32_e32 v31, 0xffff0000, v29
	v_lshlrev_b32_e32 v30, 16, v29
	v_pk_add_f32 v[30:31], v[36:37], v[30:31] neg_lo:[0,1] neg_hi:[0,1]
	v_pk_mul_f32 v[40:41], v[26:27], v[26:27]
	v_cvt_pk_bf16_f32 v33, v30, v31
	v_cvt_pk_bf16_f32 v30, v24, v25
	v_and_b32_e32 v35, 0xffff0000, v30
	v_lshlrev_b32_e32 v34, 16, v30
	v_pk_add_f32 v[34:35], v[24:25], v[34:35] neg_lo:[0,1] neg_hi:[0,1]
	v_pk_mul_f32 v[24:25], v[24:25], v[24:25]
	v_pk_fma_f32 v[36:37], v[36:37], v[36:37], v[40:41]
	v_pk_fma_f32 v[24:25], v[38:39], v[38:39], v[24:25]
	v_cvt_pk_bf16_f32 v34, v34, v35
	v_add_f32_e32 v24, v24, v25
	v_add_f32_e32 v24, v36, v24
	v_add_f32_e32 v35, v37, v24
	v_mov_b32_e32 v201, v35
	v_cvt_pk_bf16_f32 v31, v26, v27
	v_and_b32_e32 v25, 0xffff0000, v31
	v_lshlrev_b32_e32 v24, 16, v31
	v_pk_add_f32 v[24:25], v[26:27], v[24:25] neg_lo:[0,1] neg_hi:[0,1]
	s_waitcnt lgkmcnt(0)
	v_cvt_pk_bf16_f32 v35, v24, v25
	v_lshl_add_u64 v[24:25], v[140:141], 2, s[12:13]
	global_store_dwordx4 v[136:137], v[28:31], off
	global_store_dwordx4 v[142:143], v[32:35], off
.LBB0_2511:
	v_lshlrev_b32_e32 v26, 16, v84
	s_waitcnt lgkmcnt(0)
	v_and_b32_e32 v27, 0xffff0000, v84
	s_waitcnt vmcnt(11)
	v_lshlrev_b32_e32 v28, 16, v80
	v_and_b32_e32 v29, 0xffff0000, v80
	v_pk_add_f32 v[26:27], v[26:27], v[28:29]
	v_lshlrev_b32_e32 v28, 16, v85
	v_and_b32_e32 v29, 0xffff0000, v85
	v_lshlrev_b32_e32 v30, 16, v81
	v_and_b32_e32 v31, 0xffff0000, v81
	v_pk_add_f32 v[28:29], v[28:29], v[30:31]
	v_lshlrev_b32_e32 v30, 16, v83
	v_pk_add_f32 v[22:23], v[22:23], v[28:29]
	v_pk_add_f32 v[28:29], v[20:21], v[26:27]
	v_lshlrev_b32_e32 v20, 16, v86
	v_and_b32_e32 v21, 0xffff0000, v86
	v_lshlrev_b32_e32 v26, 16, v82
	v_and_b32_e32 v27, 0xffff0000, v82
	v_pk_add_f32 v[20:21], v[20:21], v[26:27]
	v_lshlrev_b32_e32 v26, 16, v87
	v_and_b32_e32 v27, 0xffff0000, v87
	v_and_b32_e32 v31, 0xffff0000, v83
	v_pk_add_f32 v[26:27], v[26:27], v[30:31]
	v_pk_add_f32 v[16:17], v[16:17], v[20:21]
	v_pk_add_f32 v[30:31], v[18:19], v[26:27]
	v_cvt_pk_bf16_f32 v18, v28, v29
	v_and_b32_e32 v21, 0xffff0000, v18
	v_lshlrev_b32_e32 v20, 16, v18
	v_pk_add_f32 v[20:21], v[28:29], v[20:21] neg_lo:[0,1] neg_hi:[0,1]
	v_cvt_pk_bf16_f32 v19, v22, v23
	v_cvt_pk_bf16_f32 v26, v20, v21
	v_and_b32_e32 v21, 0xffff0000, v19
	v_lshlrev_b32_e32 v20, 16, v19
	v_pk_add_f32 v[20:21], v[22:23], v[20:21] neg_lo:[0,1] neg_hi:[0,1]
	v_pk_mul_f32 v[34:35], v[30:31], v[30:31]
	v_cvt_pk_bf16_f32 v27, v20, v21
	v_cvt_pk_bf16_f32 v20, v16, v17
	v_and_b32_e32 v33, 0xffff0000, v20
	v_lshlrev_b32_e32 v32, 16, v20
	v_pk_add_f32 v[32:33], v[16:17], v[32:33] neg_lo:[0,1] neg_hi:[0,1]
	v_pk_mul_f32 v[16:17], v[16:17], v[16:17]
	v_pk_fma_f32 v[22:23], v[22:23], v[22:23], v[34:35]
	v_pk_fma_f32 v[16:17], v[28:29], v[28:29], v[16:17]
	v_cvt_pk_bf16_f32 v21, v30, v31
	v_add_f32_e32 v16, v16, v17
	v_add_f32_e32 v16, v22, v16
	v_add_f32_e32 v16, v23, v16
	v_add_f32_e32 v16, v201, v16
	ds_bpermute_b32 v17, v200, v16
	v_and_b32_e32 v23, 0xffff0000, v21
	v_lshlrev_b32_e32 v22, 16, v21
	v_pk_add_f32 v[22:23], v[30:31], v[22:23] neg_lo:[0,1] neg_hi:[0,1]
	v_cvt_pk_bf16_f32 v28, v32, v33
	s_waitcnt lgkmcnt(0)
	v_add_f32_e32 v16, v16, v17
	ds_bpermute_b32 v17, v199, v16
	v_cvt_pk_bf16_f32 v29, v22, v23
	global_store_dwordx4 v[136:137], v[18:21], off offset:256
	global_store_dwordx4 v[138:139], v[26:29], off
	s_and_saveexec_b64 s[26:27], vcc
	s_cbranch_execz .LBB0_2513
	s_waitcnt lgkmcnt(0)
	v_add_f32_e32 v16, v16, v17
	global_atomic_add_f32 v[24:25], v16, off
.LBB0_2513:
	s_or_b64 exec, exec, s[26:27]
	s_waitcnt vmcnt(12)
	v_lshlrev_b32_e32 v16, 16, v72
	s_waitcnt lgkmcnt(0)
	v_and_b32_e32 v17, 0xffff0000, v72
	s_waitcnt vmcnt(10)
	v_lshlrev_b32_e32 v18, 16, v68
	v_and_b32_e32 v19, 0xffff0000, v68
	v_pk_add_f32 v[16:17], v[16:17], v[18:19]
	v_lshlrev_b32_e32 v18, 16, v73
	v_and_b32_e32 v19, 0xffff0000, v73
	v_lshlrev_b32_e32 v20, 16, v69
	v_and_b32_e32 v21, 0xffff0000, v69
	v_pk_add_f32 v[18:19], v[18:19], v[20:21]
	v_pk_add_f32 v[22:23], v[12:13], v[16:17]
	v_pk_add_f32 v[20:21], v[14:15], v[18:19]
	v_lshlrev_b32_e32 v12, 16, v74
	v_and_b32_e32 v13, 0xffff0000, v74
	v_lshlrev_b32_e32 v14, 16, v70
	v_and_b32_e32 v15, 0xffff0000, v70
	v_pk_add_f32 v[12:13], v[12:13], v[14:15]
	v_lshlrev_b32_e32 v14, 16, v75
	v_and_b32_e32 v15, 0xffff0000, v75
	v_lshlrev_b32_e32 v16, 16, v71
	v_and_b32_e32 v17, 0xffff0000, v71
	v_pk_add_f32 v[14:15], v[14:15], v[16:17]
	v_pk_add_f32 v[8:9], v[8:9], v[12:13]
	v_cvt_pk_bf16_f32 v12, v22, v23
	v_pk_add_f32 v[10:11], v[10:11], v[14:15]
	v_and_b32_e32 v15, 0xffff0000, v12
	v_lshlrev_b32_e32 v14, 16, v12
	v_pk_add_f32 v[14:15], v[22:23], v[14:15] neg_lo:[0,1] neg_hi:[0,1]
	v_cvt_pk_bf16_f32 v13, v20, v21
	v_cvt_pk_bf16_f32 v16, v14, v15
	v_and_b32_e32 v15, 0xffff0000, v13
	v_lshlrev_b32_e32 v14, 16, v13
	v_pk_add_f32 v[14:15], v[20:21], v[14:15] neg_lo:[0,1] neg_hi:[0,1]
	v_pk_mul_f32 v[24:25], v[10:11], v[10:11]
	v_cvt_pk_bf16_f32 v17, v14, v15
	v_cvt_pk_bf16_f32 v14, v8, v9
	v_and_b32_e32 v19, 0xffff0000, v14
	v_lshlrev_b32_e32 v18, 16, v14
	v_pk_add_f32 v[18:19], v[8:9], v[18:19] neg_lo:[0,1] neg_hi:[0,1]
	v_pk_mul_f32 v[8:9], v[8:9], v[8:9]
	v_pk_fma_f32 v[20:21], v[20:21], v[20:21], v[24:25]
	v_pk_fma_f32 v[8:9], v[22:23], v[22:23], v[8:9]
	v_cvt_pk_bf16_f32 v18, v18, v19
	v_add_f32_e32 v8, v8, v9
	v_add_f32_e32 v8, v20, v8
	v_add_f32_e32 v19, v21, v8
	v_mov_b32_e32 v201, v19
	v_cvt_pk_bf16_f32 v15, v10, v11
	v_and_b32_e32 v9, 0xffff0000, v15
	v_lshlrev_b32_e32 v8, 16, v15
	v_pk_add_f32 v[8:9], v[10:11], v[8:9] neg_lo:[0,1] neg_hi:[0,1]
	s_waitcnt lgkmcnt(0)
	v_cvt_pk_bf16_f32 v19, v8, v9
	v_lshl_add_u64 v[8:9], v[132:133], 2, s[12:13]
	global_store_dwordx4 v[128:129], v[12:15], off
	global_store_dwordx4 v[134:135], v[16:19], off
.LBB0_2515:
	v_lshlrev_b32_e32 v10, 16, v64
	s_waitcnt lgkmcnt(0)
	v_and_b32_e32 v11, 0xffff0000, v64
	s_waitcnt vmcnt(10)
	v_lshlrev_b32_e32 v12, 16, v76
	v_and_b32_e32 v13, 0xffff0000, v76
	v_pk_add_f32 v[10:11], v[10:11], v[12:13]
	v_lshlrev_b32_e32 v12, 16, v65
	v_and_b32_e32 v13, 0xffff0000, v65
	v_lshlrev_b32_e32 v14, 16, v77
	v_and_b32_e32 v15, 0xffff0000, v77
	v_pk_add_f32 v[12:13], v[12:13], v[14:15]
	v_lshlrev_b32_e32 v14, 16, v79
	v_pk_add_f32 v[6:7], v[6:7], v[12:13]
	v_pk_add_f32 v[12:13], v[4:5], v[10:11]
	v_lshlrev_b32_e32 v4, 16, v66
	v_and_b32_e32 v5, 0xffff0000, v66
	v_lshlrev_b32_e32 v10, 16, v78
	v_and_b32_e32 v11, 0xffff0000, v78
	v_pk_add_f32 v[4:5], v[4:5], v[10:11]
	v_lshlrev_b32_e32 v10, 16, v67
	v_and_b32_e32 v11, 0xffff0000, v67
	v_and_b32_e32 v15, 0xffff0000, v79
	v_pk_add_f32 v[10:11], v[10:11], v[14:15]
	v_pk_add_f32 v[0:1], v[0:1], v[4:5]
	v_pk_add_f32 v[14:15], v[2:3], v[10:11]
	v_cvt_pk_bf16_f32 v2, v12, v13
	v_and_b32_e32 v5, 0xffff0000, v2
	v_lshlrev_b32_e32 v4, 16, v2
	v_pk_add_f32 v[4:5], v[12:13], v[4:5] neg_lo:[0,1] neg_hi:[0,1]
	v_cvt_pk_bf16_f32 v3, v6, v7
	v_cvt_pk_bf16_f32 v10, v4, v5
	v_and_b32_e32 v5, 0xffff0000, v3
	v_lshlrev_b32_e32 v4, 16, v3
	v_pk_add_f32 v[4:5], v[6:7], v[4:5] neg_lo:[0,1] neg_hi:[0,1]
	v_pk_mul_f32 v[18:19], v[14:15], v[14:15]
	v_cvt_pk_bf16_f32 v11, v4, v5
	v_cvt_pk_bf16_f32 v4, v0, v1
	v_and_b32_e32 v17, 0xffff0000, v4
	v_lshlrev_b32_e32 v16, 16, v4
	v_pk_add_f32 v[16:17], v[0:1], v[16:17] neg_lo:[0,1] neg_hi:[0,1]
	v_pk_mul_f32 v[0:1], v[0:1], v[0:1]
	v_pk_fma_f32 v[6:7], v[6:7], v[6:7], v[18:19]
	v_pk_fma_f32 v[0:1], v[12:13], v[12:13], v[0:1]
	v_cvt_pk_bf16_f32 v5, v14, v15
	v_add_f32_e32 v0, v0, v1
	v_add_f32_e32 v0, v6, v0
	v_add_f32_e32 v0, v7, v0
	v_add_f32_e32 v0, v201, v0
	ds_bpermute_b32 v1, v200, v0
	v_and_b32_e32 v7, 0xffff0000, v5
	v_lshlrev_b32_e32 v6, 16, v5
	v_pk_add_f32 v[6:7], v[14:15], v[6:7] neg_lo:[0,1] neg_hi:[0,1]
	v_cvt_pk_bf16_f32 v12, v16, v17
	s_waitcnt lgkmcnt(0)
	v_add_f32_e32 v0, v0, v1
	ds_bpermute_b32 v1, v199, v0
	v_cvt_pk_bf16_f32 v13, v6, v7
	global_store_dwordx4 v[128:129], v[2:5], off offset:256
	global_store_dwordx4 v[130:131], v[10:13], off
	s_and_saveexec_b64 s[26:27], vcc
	s_cbranch_execz .LBB0_2480
	s_waitcnt lgkmcnt(0)
	v_add_f32_e32 v0, v0, v1
	global_atomic_add_f32 v[8:9], v0, off
	s_branch .LBB0_2480

.LBB0_3618:
	s_add_u32 s20, s18, 0x100
	s_addc_u32 s21, s19, 0
	s_add_i32 s45, 0, 0x10000
	ds_read_b128 v[128:131], v202
	ds_read_b128 v[132:135], v202 offset:1024
	ds_read_b128 v[136:139], v202 offset:2048
	ds_read_b128 v[140:143], v202 offset:3072
	s_cmp_eq_u32 s44, 40
	s_cselect_b32 s25, s5, s21
	s_cselect_b32 s24, s4, s20
	s_cselect_b32 s23, s7, s43
	s_cselect_b32 s22, s6, s33
	s_add_i32 m0, s30, 0xc000
	ds_read_b128 v[144:147], v198
	ds_read_b128 v[148:151], v198 offset:1024
	ds_read_b128 v[152:155], v198 offset:2048
	ds_read_b128 v[156:159], v198 offset:3072
	ds_read_b128 v[160:163], v198 offset:4096
	ds_read_b128 v[164:167], v198 offset:5120
	ds_read_b128 v[168:171], v198 offset:6144
	ds_read_b128 v[172:175], v198 offset:7168
	global_load_lds_dwordx4 v214, s[18:19]
	s_add_i32 m0, s30, 0xe000
	s_nop 0
	global_load_lds_dwordx4 v212, s[18:19]
	s_waitcnt lgkmcnt(8)
	s_barrier
	s_waitcnt lgkmcnt(0)
	v_mfma_f32_16x16x32_bf16 v[124:127], v[128:131], v[144:147], v[124:127]
	v_mfma_f32_16x16x32_bf16 v[120:123], v[136:139], v[144:147], v[120:123]
	v_mfma_f32_16x16x32_bf16 v[108:111], v[128:131], v[152:155], v[108:111]
	v_mfma_f32_16x16x32_bf16 v[104:107], v[136:139], v[152:155], v[104:107]
	v_mfma_f32_16x16x32_bf16 v[92:95], v[128:131], v[160:163], v[92:95]
	v_mfma_f32_16x16x32_bf16 v[88:91], v[136:139], v[160:163], v[88:91]
	v_mfma_f32_16x16x32_bf16 v[76:79], v[128:131], v[168:171], v[76:79]
	v_mfma_f32_16x16x32_bf16 v[72:75], v[136:139], v[168:171], v[72:75]
	v_mfma_f32_16x16x32_bf16 v[124:127], v[132:135], v[148:151], v[124:127]
	v_mfma_f32_16x16x32_bf16 v[120:123], v[140:143], v[148:151], v[120:123]
	v_mfma_f32_16x16x32_bf16 v[108:111], v[132:135], v[156:159], v[108:111]
	v_mfma_f32_16x16x32_bf16 v[104:107], v[140:143], v[156:159], v[104:107]
	v_mfma_f32_16x16x32_bf16 v[92:95], v[132:135], v[164:167], v[92:95]
	v_mfma_f32_16x16x32_bf16 v[88:91], v[140:143], v[164:167], v[88:91]
	v_mfma_f32_16x16x32_bf16 v[76:79], v[132:135], v[172:175], v[76:79]
	v_mfma_f32_16x16x32_bf16 v[72:75], v[140:143], v[172:175], v[72:75]
	s_barrier
	s_add_i32 s46, 0, 0x14000
	s_add_i32 s18, s45, s29
	s_mov_b32 m0, s18
	ds_read_b128 v[176:179], v203
	ds_read_b128 v[180:183], v203 offset:1024
	ds_read_b128 v[184:187], v203 offset:2048
	ds_read_b128 v[188:191], v203 offset:3072
	global_load_lds_dwordx4 v192, s[22:23]
	s_add_i32 m0, s18, 0x2000
	s_nop 0
	global_load_lds_dwordx4 v210, s[22:23]
	s_barrier
	s_waitcnt lgkmcnt(0)
	v_mfma_f32_16x16x32_bf16 v[116:119], v[176:179], v[144:147], v[116:119]
	v_mfma_f32_16x16x32_bf16 v[112:115], v[184:187], v[144:147], v[112:115]
	v_mfma_f32_16x16x32_bf16 v[100:103], v[176:179], v[152:155], v[100:103]
	v_mfma_f32_16x16x32_bf16 v[96:99], v[184:187], v[152:155], v[96:99]
	v_mfma_f32_16x16x32_bf16 v[84:87], v[176:179], v[160:163], v[84:87]
	v_mfma_f32_16x16x32_bf16 v[80:83], v[184:187], v[160:163], v[80:83]
	v_mfma_f32_16x16x32_bf16 v[68:71], v[176:179], v[168:171], v[68:71]
	v_mfma_f32_16x16x32_bf16 v[64:67], v[184:187], v[168:171], v[64:67]
	v_mfma_f32_16x16x32_bf16 v[116:119], v[180:183], v[148:151], v[116:119]
	v_mfma_f32_16x16x32_bf16 v[112:115], v[188:191], v[148:151], v[112:115]
	v_mfma_f32_16x16x32_bf16 v[100:103], v[180:183], v[156:159], v[100:103]
	v_mfma_f32_16x16x32_bf16 v[96:99], v[188:191], v[156:159], v[96:99]
	v_mfma_f32_16x16x32_bf16 v[84:87], v[180:183], v[164:167], v[84:87]
	v_mfma_f32_16x16x32_bf16 v[80:83], v[188:191], v[164:167], v[80:83]
	v_mfma_f32_16x16x32_bf16 v[68:71], v[180:183], v[172:175], v[68:71]
	v_mfma_f32_16x16x32_bf16 v[64:67], v[188:191], v[172:175], v[64:67]
	s_mov_b32 m0, s30
	s_add_u32 vcc_lo, s24, 0x80
	s_addc_u32 vcc_hi, s25, 0
	s_barrier
	ds_read_b128 v[144:147], v198 offset:16384
	ds_read_b128 v[148:151], v198 offset:17408
	ds_read_b128 v[152:155], v198 offset:18432
	ds_read_b128 v[156:159], v198 offset:19456
	ds_read_b128 v[160:163], v198 offset:20480
	ds_read_b128 v[164:167], v198 offset:21504
	ds_read_b128 v[168:171], v198 offset:22528
	ds_read_b128 v[172:175], v198 offset:23552
	global_load_lds_dwordx4 v206, s[24:25]
	s_mov_b32 m0, s31
	s_nop 0
	global_load_lds_dwordx4 v208, s[24:25]
	s_barrier
	s_waitcnt lgkmcnt(0)
	v_mfma_f32_16x16x32_bf16 v[60:63], v[128:131], v[144:147], v[60:63]
	v_mfma_f32_16x16x32_bf16 v[56:59], v[136:139], v[144:147], v[56:59]
	v_mfma_f32_16x16x32_bf16 v[44:47], v[128:131], v[152:155], v[44:47]
	v_mfma_f32_16x16x32_bf16 v[40:43], v[136:139], v[152:155], v[40:43]
	v_mfma_f32_16x16x32_bf16 v[28:31], v[128:131], v[160:163], v[28:31]
	v_mfma_f32_16x16x32_bf16 v[24:27], v[136:139], v[160:163], v[24:27]
	v_mfma_f32_16x16x32_bf16 v[12:15], v[128:131], v[168:171], v[12:15]
	v_mfma_f32_16x16x32_bf16 v[8:11], v[136:139], v[168:171], v[8:11]
	v_mfma_f32_16x16x32_bf16 v[60:63], v[132:135], v[148:151], v[60:63]
	v_mfma_f32_16x16x32_bf16 v[56:59], v[140:143], v[148:151], v[56:59]
	v_mfma_f32_16x16x32_bf16 v[44:47], v[132:135], v[156:159], v[44:47]
	v_mfma_f32_16x16x32_bf16 v[40:43], v[140:143], v[156:159], v[40:43]
	v_mfma_f32_16x16x32_bf16 v[28:31], v[132:135], v[164:167], v[28:31]
	v_mfma_f32_16x16x32_bf16 v[24:27], v[140:143], v[164:167], v[24:27]
	v_mfma_f32_16x16x32_bf16 v[12:15], v[132:135], v[172:175], v[12:15]
	v_mfma_f32_16x16x32_bf16 v[8:11], v[140:143], v[172:175], v[8:11]
	s_barrier
	s_add_u32 s18, s22, 0xb0000
	s_addc_u32 s19, s23, 0
	s_add_i32 s45, s46, s29
	s_mov_b32 m0, s45
	s_nop 0
	global_load_lds_dwordx4 v192, s[18:19]
	s_add_i32 m0, s45, 0x2000
	s_nop 0
	global_load_lds_dwordx4 v210, s[18:19]
	s_waitcnt vmcnt(6)
	s_barrier
	v_mfma_f32_16x16x32_bf16 v[52:55], v[176:179], v[144:147], v[52:55]
	v_mfma_f32_16x16x32_bf16 v[48:51], v[184:187], v[144:147], v[48:51]
	v_mfma_f32_16x16x32_bf16 v[36:39], v[176:179], v[152:155], v[36:39]
	v_mfma_f32_16x16x32_bf16 v[32:35], v[184:187], v[152:155], v[32:35]
	v_mfma_f32_16x16x32_bf16 v[20:23], v[176:179], v[160:163], v[20:23]
	v_mfma_f32_16x16x32_bf16 v[16:19], v[184:187], v[160:163], v[16:19]
	v_mfma_f32_16x16x32_bf16 v[4:7], v[176:179], v[168:171], v[4:7]
	v_mfma_f32_16x16x32_bf16 v[0:3], v[184:187], v[168:171], v[0:3]
	v_mfma_f32_16x16x32_bf16 v[52:55], v[180:183], v[148:151], v[52:55]
	v_mfma_f32_16x16x32_bf16 v[48:51], v[188:191], v[148:151], v[48:51]
	v_mfma_f32_16x16x32_bf16 v[36:39], v[180:183], v[156:159], v[36:39]
	v_mfma_f32_16x16x32_bf16 v[32:35], v[188:191], v[156:159], v[32:35]
	v_mfma_f32_16x16x32_bf16 v[20:23], v[180:183], v[164:167], v[20:23]
	v_mfma_f32_16x16x32_bf16 v[16:19], v[188:191], v[164:167], v[16:19]
	v_mfma_f32_16x16x32_bf16 v[4:7], v[180:183], v[172:175], v[4:7]
	v_mfma_f32_16x16x32_bf16 v[0:3], v[188:191], v[172:175], v[0:3]
	s_add_i32 s45, 0, 0x18000
	s_barrier
	ds_read_b128 v[128:131], v204
	ds_read_b128 v[132:135], v204 offset:1024
	ds_read_b128 v[136:139], v204 offset:2048
	ds_read_b128 v[140:143], v204 offset:3072
	s_add_u32 s18, s24, 0xb0000
	s_addc_u32 s19, s25, 0
	s_mov_b32 m0, s34
	ds_read_b128 v[144:147], v198 offset:32768
	ds_read_b128 v[148:151], v198 offset:33792
	ds_read_b128 v[152:155], v198 offset:34816
	ds_read_b128 v[156:159], v198 offset:35840
	ds_read_b128 v[160:163], v198 offset:36864
	ds_read_b128 v[164:167], v198 offset:37888
	ds_read_b128 v[168:171], v198 offset:38912
	ds_read_b128 v[172:175], v198 offset:39936
	global_load_lds_dwordx4 v206, s[18:19]
	s_mov_b32 m0, s35
	s_nop 0
	global_load_lds_dwordx4 v208, s[18:19]
	s_waitcnt lgkmcnt(8)
	s_barrier
	s_waitcnt lgkmcnt(0)
	v_mfma_f32_16x16x32_bf16 v[124:127], v[128:131], v[144:147], v[124:127]
	v_mfma_f32_16x16x32_bf16 v[120:123], v[136:139], v[144:147], v[120:123]
	v_mfma_f32_16x16x32_bf16 v[108:111], v[128:131], v[152:155], v[108:111]
	v_mfma_f32_16x16x32_bf16 v[104:107], v[136:139], v[152:155], v[104:107]
	v_mfma_f32_16x16x32_bf16 v[92:95], v[128:131], v[160:163], v[92:95]
	v_mfma_f32_16x16x32_bf16 v[88:91], v[136:139], v[160:163], v[88:91]
	v_mfma_f32_16x16x32_bf16 v[76:79], v[128:131], v[168:171], v[76:79]
	v_mfma_f32_16x16x32_bf16 v[72:75], v[136:139], v[168:171], v[72:75]
	v_mfma_f32_16x16x32_bf16 v[124:127], v[132:135], v[148:151], v[124:127]
	v_mfma_f32_16x16x32_bf16 v[120:123], v[140:143], v[148:151], v[120:123]
	v_mfma_f32_16x16x32_bf16 v[108:111], v[132:135], v[156:159], v[108:111]
	v_mfma_f32_16x16x32_bf16 v[104:107], v[140:143], v[156:159], v[104:107]
	v_mfma_f32_16x16x32_bf16 v[92:95], v[132:135], v[164:167], v[92:95]
	v_mfma_f32_16x16x32_bf16 v[88:91], v[140:143], v[164:167], v[88:91]
	v_mfma_f32_16x16x32_bf16 v[76:79], v[132:135], v[172:175], v[76:79]
	v_mfma_f32_16x16x32_bf16 v[72:75], v[140:143], v[172:175], v[72:75]
	s_barrier
	s_add_i32 s24, 0, 0x1c000
	s_add_i32 s18, s45, s29
	s_add_u32 s100, s22, 0x80
	s_addc_u32 s101, s23, 0
	s_mov_b32 m0, s18
	ds_read_b128 v[176:179], v205
	ds_read_b128 v[180:183], v205 offset:1024
	ds_read_b128 v[184:187], v205 offset:2048
	ds_read_b128 v[188:191], v205 offset:3072
	global_load_lds_dwordx4 v192, s[100:101]
	s_add_i32 m0, s18, 0x2000
	s_nop 0
	global_load_lds_dwordx4 v210, s[100:101]
	s_barrier
	s_waitcnt lgkmcnt(0)
	v_mfma_f32_16x16x32_bf16 v[116:119], v[176:179], v[144:147], v[116:119]
	v_mfma_f32_16x16x32_bf16 v[112:115], v[184:187], v[144:147], v[112:115]
	v_mfma_f32_16x16x32_bf16 v[100:103], v[176:179], v[152:155], v[100:103]
	v_mfma_f32_16x16x32_bf16 v[96:99], v[184:187], v[152:155], v[96:99]
	v_mfma_f32_16x16x32_bf16 v[84:87], v[176:179], v[160:163], v[84:87]
	v_mfma_f32_16x16x32_bf16 v[80:83], v[184:187], v[160:163], v[80:83]
	v_mfma_f32_16x16x32_bf16 v[68:71], v[176:179], v[168:171], v[68:71]
	v_mfma_f32_16x16x32_bf16 v[64:67], v[184:187], v[168:171], v[64:67]
	v_mfma_f32_16x16x32_bf16 v[116:119], v[180:183], v[148:151], v[116:119]
	v_mfma_f32_16x16x32_bf16 v[112:115], v[188:191], v[148:151], v[112:115]
	v_mfma_f32_16x16x32_bf16 v[100:103], v[180:183], v[156:159], v[100:103]
	v_mfma_f32_16x16x32_bf16 v[96:99], v[188:191], v[156:159], v[96:99]
	v_mfma_f32_16x16x32_bf16 v[84:87], v[180:183], v[164:167], v[84:87]
	v_mfma_f32_16x16x32_bf16 v[80:83], v[188:191], v[164:167], v[80:83]
	v_mfma_f32_16x16x32_bf16 v[68:71], v[180:183], v[172:175], v[68:71]
	v_mfma_f32_16x16x32_bf16 v[64:67], v[188:191], v[172:175], v[64:67]
	s_mov_b32 m0, s36
	s_barrier
	ds_read_b128 v[144:147], v198 offset:49152
	ds_read_b128 v[148:151], v198 offset:50176
	ds_read_b128 v[152:155], v198 offset:51200
	ds_read_b128 v[156:159], v198 offset:52224
	ds_read_b128 v[160:163], v198 offset:53248
	ds_read_b128 v[164:167], v198 offset:54272
	ds_read_b128 v[168:171], v198 offset:55296
	ds_read_b128 v[172:175], v198 offset:56320
	global_load_lds_dwordx4 v206, vcc
	s_mov_b32 m0, s37
	s_nop 0
	global_load_lds_dwordx4 v208, vcc
	s_barrier
	s_waitcnt lgkmcnt(0)
	v_mfma_f32_16x16x32_bf16 v[60:63], v[128:131], v[144:147], v[60:63]
	v_mfma_f32_16x16x32_bf16 v[56:59], v[136:139], v[144:147], v[56:59]
	v_mfma_f32_16x16x32_bf16 v[44:47], v[128:131], v[152:155], v[44:47]
	v_mfma_f32_16x16x32_bf16 v[40:43], v[136:139], v[152:155], v[40:43]
	v_mfma_f32_16x16x32_bf16 v[28:31], v[128:131], v[160:163], v[28:31]
	v_mfma_f32_16x16x32_bf16 v[24:27], v[136:139], v[160:163], v[24:27]
	v_mfma_f32_16x16x32_bf16 v[12:15], v[128:131], v[168:171], v[12:15]
	v_mfma_f32_16x16x32_bf16 v[8:11], v[136:139], v[168:171], v[8:11]
	v_mfma_f32_16x16x32_bf16 v[60:63], v[132:135], v[148:151], v[60:63]
	v_mfma_f32_16x16x32_bf16 v[56:59], v[140:143], v[148:151], v[56:59]
	v_mfma_f32_16x16x32_bf16 v[44:47], v[132:135], v[156:159], v[44:47]
	v_mfma_f32_16x16x32_bf16 v[40:43], v[140:143], v[156:159], v[40:43]
	v_mfma_f32_16x16x32_bf16 v[28:31], v[132:135], v[164:167], v[28:31]
	v_mfma_f32_16x16x32_bf16 v[24:27], v[140:143], v[164:167], v[24:27]
	v_mfma_f32_16x16x32_bf16 v[12:15], v[132:135], v[172:175], v[12:15]
	v_mfma_f32_16x16x32_bf16 v[8:11], v[140:143], v[172:175], v[8:11]
	s_barrier
	s_add_u32 s18, s22, 0xb0080
	s_addc_u32 s19, s23, 0
	s_add_i32 s22, s24, s29
	s_mov_b32 m0, s22
	s_nop 0
	global_load_lds_dwordx4 v192, s[18:19]
	s_add_i32 m0, s22, 0x2000
	s_nop 0
	global_load_lds_dwordx4 v210, s[18:19]
	s_waitcnt vmcnt(6)
	s_barrier
	v_mfma_f32_16x16x32_bf16 v[52:55], v[176:179], v[144:147], v[52:55]
	v_mfma_f32_16x16x32_bf16 v[48:51], v[184:187], v[144:147], v[48:51]
	v_mfma_f32_16x16x32_bf16 v[36:39], v[176:179], v[152:155], v[36:39]
	v_mfma_f32_16x16x32_bf16 v[32:35], v[184:187], v[152:155], v[32:35]
	v_mfma_f32_16x16x32_bf16 v[20:23], v[176:179], v[160:163], v[20:23]
	v_mfma_f32_16x16x32_bf16 v[16:19], v[184:187], v[160:163], v[16:19]
	v_mfma_f32_16x16x32_bf16 v[4:7], v[176:179], v[168:171], v[4:7]
	v_mfma_f32_16x16x32_bf16 v[0:3], v[184:187], v[168:171], v[0:3]
	v_mfma_f32_16x16x32_bf16 v[52:55], v[180:183], v[148:151], v[52:55]
	v_mfma_f32_16x16x32_bf16 v[48:51], v[188:191], v[148:151], v[48:51]
	v_mfma_f32_16x16x32_bf16 v[36:39], v[180:183], v[156:159], v[36:39]
	v_mfma_f32_16x16x32_bf16 v[32:35], v[188:191], v[156:159], v[32:35]
	v_mfma_f32_16x16x32_bf16 v[20:23], v[180:183], v[164:167], v[20:23]
	v_mfma_f32_16x16x32_bf16 v[16:19], v[188:191], v[164:167], v[16:19]
	v_mfma_f32_16x16x32_bf16 v[4:7], v[180:183], v[172:175], v[4:7]
	v_mfma_f32_16x16x32_bf16 v[0:3], v[188:191], v[172:175], v[0:3]
	s_add_i32 s44, s44, 2
	s_add_u32 s33, s33, 0x100
	s_addc_u32 s43, s43, 0
	s_cmp_gt_u32 s44, 41
	s_mov_b64 s[18:19], s[20:21]
	s_barrier
	s_cbranch_scc0 .LBB0_3618
	v_mov_b32_e32 v128, v252
	s_lshl_b32 s19, s42, 8
	v_readfirstlane_b32 s18, v128
	s_ashr_i32 s20, s18, 2
	s_andn2_b32 s20, s20, 63
	s_lshr_b32 s18, s18, 1
	s_add_i32 s20, s20, s19
	s_and_b32 s18, s18, 0x60
	s_lshl_b32 s19, s41, 8
	v_and_or_b32 v218, v128, 15, s20
	v_lshrrev_b32_e32 v128, 1, v128
	s_or_b32 s18, s18, s19
	v_and_b32_e32 v129, 64, v195
	v_and_or_b32 v216, v128, 24, s18
	v_xor_b32_e32 v128, 16, v195
	v_add_u32_e32 v129, 64, v129
	v_cmp_lt_i32_e32 vcc, v128, v129
	v_ashrrev_i32_e32 v219, 31, v218
	v_ashrrev_i32_e32 v217, 31, v216
	v_cndmask_b32_e32 v128, v195, v128, vcc
	v_lshlrev_b32_e32 v200, 2, v128
	v_xor_b32_e32 v128, 32, v195
	v_cmp_lt_i32_e32 vcc, v128, v129
	v_or_b32_e32 v220, 0x80, v216
	v_ashrrev_i32_e32 v221, 31, v220
	v_cndmask_b32_e32 v128, v195, v128, vcc
	v_lshlrev_b32_e32 v199, 2, v128
	v_lshlrev_b64 v[128:129], 10, v[218:219]
	v_lshl_add_u64 v[130:131], v[128:129], 0, v[216:217]
	v_lshlrev_b64 v[130:131], 1, v[130:131]
	v_lshl_add_u64 v[246:247], s[10:11], 0, v[130:131]
	v_lshl_add_u64 v[250:251], s[12:13], 0, v[130:131]
	global_load_dwordx4 v[188:191], v[246:247], off
	global_load_dwordx4 v[180:183], v[246:247], off offset:256
	global_load_dwordx4 v[184:187], v[250:251], off
	v_or_b32_e32 v242, 16, v218
	v_lshl_add_u64 v[128:129], v[128:129], 0, v[220:221]
	v_ashrrev_i32_e32 v243, 31, v242
	v_lshl_add_u64 v[248:249], v[128:129], 1, s[12:13]
	v_lshlrev_b64 v[128:129], 10, v[242:243]
	v_or_b32_e32 v234, 32, v218
	v_lshl_add_u64 v[130:131], v[128:129], 0, v[216:217]
	v_lshl_add_u64 v[128:129], v[128:129], 0, v[220:221]
	v_ashrrev_i32_e32 v235, 31, v234
	v_lshlrev_b64 v[130:131], 1, v[130:131]
	v_lshl_add_u64 v[240:241], v[128:129], 1, s[12:13]
	v_lshlrev_b64 v[128:129], 10, v[234:235]
	v_or_b32_e32 v226, 48, v218
	v_lshl_add_u64 v[238:239], s[10:11], 0, v[130:131]
	v_lshl_add_u64 v[244:245], s[12:13], 0, v[130:131]
	v_lshl_add_u64 v[130:131], v[128:129], 0, v[216:217]
	v_lshl_add_u64 v[128:129], v[128:129], 0, v[220:221]
	v_ashrrev_i32_e32 v227, 31, v226
	v_lshlrev_b64 v[130:131], 1, v[130:131]
	v_lshl_add_u64 v[232:233], v[128:129], 1, s[12:13]
	v_lshlrev_b64 v[128:129], 10, v[226:227]
	v_lshl_add_u64 v[228:229], s[10:11], 0, v[130:131]
	v_lshl_add_u64 v[236:237], s[12:13], 0, v[130:131]
	v_lshl_add_u64 v[130:131], v[128:129], 0, v[216:217]
	v_lshlrev_b64 v[130:131], 1, v[130:131]
	v_lshl_add_u64 v[132:133], v[128:129], 0, v[220:221]
	v_lshl_add_u64 v[222:223], s[10:11], 0, v[130:131]
	v_lshl_add_u64 v[230:231], s[12:13], 0, v[130:131]
	v_lshl_add_u64 v[224:225], v[132:133], 1, s[12:13]
	global_load_dwordx4 v[176:179], v[248:249], off
	global_load_dwordx4 v[172:175], v[238:239], off
	global_load_dwordx4 v[164:167], v[238:239], off offset:256
	global_load_dwordx4 v[168:171], v[244:245], off
	global_load_dwordx4 v[160:163], v[240:241], off
	global_load_dwordx4 v[156:159], v[228:229], off
	global_load_dwordx4 v[132:135], v[224:225], off
	global_load_dwordx4 v[152:155], v[236:237], off
	global_load_dwordx4 v[144:147], v[232:233], off
	global_load_dwordx4 v[148:151], v[228:229], off offset:256
	global_load_dwordx4 v[136:139], v[230:231], off
	global_load_dwordx4 v[140:143], v[222:223], off
	global_load_dwordx4 v[128:131], v[222:223], off offset:256
	v_cmp_gt_u32_e32 vcc, 16, v195
	s_waitcnt vmcnt(0)
	v_lshlrev_b32_e32 v202, 16, v188
	v_and_b32_e32 v203, 0xffff0000, v188
	v_lshlrev_b32_e32 v204, 16, v184
	v_and_b32_e32 v205, 0xffff0000, v184
	v_lshlrev_b32_e32 v188, 16, v189
	v_and_b32_e32 v189, 0xffff0000, v189
	v_lshlrev_b32_e32 v184, 16, v185
	v_and_b32_e32 v185, 0xffff0000, v185
	v_pk_add_f32 v[202:203], v[202:203], v[204:205]
	v_pk_add_f32 v[184:185], v[188:189], v[184:185]
	v_pk_fma_f32 v[188:189], v[124:125], 0.5, v[202:203] op_sel_hi:[1,0,1]
	v_pk_fma_f32 v[184:185], v[126:127], 0.5, v[184:185] op_sel_hi:[1,0,1]
	v_lshlrev_b32_e32 v124, 16, v190
	v_and_b32_e32 v125, 0xffff0000, v190
	v_lshlrev_b32_e32 v126, 16, v186
	v_and_b32_e32 v127, 0xffff0000, v186
	v_pk_add_f32 v[124:125], v[124:125], v[126:127]
	v_lshlrev_b32_e32 v126, 16, v191
	v_and_b32_e32 v127, 0xffff0000, v191
	v_lshlrev_b32_e32 v186, 16, v187
	v_and_b32_e32 v187, 0xffff0000, v187
	v_pk_add_f32 v[126:127], v[126:127], v[186:187]
	v_pk_fma_f32 v[190:191], v[120:121], 0.5, v[124:125] op_sel_hi:[1,0,1]
	v_cvt_pk_bf16_f32 v120, v188, v189
	v_pk_fma_f32 v[186:187], v[122:123], 0.5, v[126:127] op_sel_hi:[1,0,1]
	v_and_b32_e32 v123, 0xffff0000, v120
	v_lshlrev_b32_e32 v122, 16, v120
	v_pk_add_f32 v[122:123], v[188:189], v[122:123] neg_lo:[0,1] neg_hi:[0,1]
	v_cvt_pk_bf16_f32 v121, v184, v185
	v_cvt_pk_bf16_f32 v124, v122, v123
	v_and_b32_e32 v123, 0xffff0000, v121
	v_lshlrev_b32_e32 v122, 16, v121
	v_pk_add_f32 v[122:123], v[184:185], v[122:123] neg_lo:[0,1] neg_hi:[0,1]
	s_nop 0
	v_cvt_pk_bf16_f32 v125, v122, v123
	v_cvt_pk_bf16_f32 v122, v190, v191
	v_cvt_pk_bf16_f32 v123, v186, v187
	v_and_b32_e32 v127, 0xffff0000, v122
	v_lshlrev_b32_e32 v126, 16, v122
	v_and_b32_e32 v203, 0xffff0000, v123
	v_lshlrev_b32_e32 v202, 16, v123
	v_pk_add_f32 v[126:127], v[190:191], v[126:127] neg_lo:[0,1] neg_hi:[0,1]
	v_pk_add_f32 v[202:203], v[186:187], v[202:203] neg_lo:[0,1] neg_hi:[0,1]
	v_cvt_pk_bf16_f32 v126, v126, v127
	v_cvt_pk_bf16_f32 v127, v202, v203
	global_store_dwordx4 v[246:247], v[120:123], off
	global_store_dwordx4 v[250:251], v[124:127], off
	s_nop 0
	v_pk_mul_f32 v[122:123], v[190:191], v[190:191]
	v_pk_mul_f32 v[120:121], v[186:187], v[186:187]
	v_pk_fma_f32 v[122:123], v[188:189], v[188:189], v[122:123]
	v_pk_fma_f32 v[120:121], v[184:185], v[184:185], v[120:121]
	v_add_f32_e32 v122, v122, v123
	v_add_f32_e32 v120, v120, v122
	v_add_f32_e32 v120, v121, v120
	v_mov_b32_e32 v201, v120
	s_waitcnt lgkmcnt(0)
	v_lshl_add_u64 v[120:121], v[218:219], 2, s[16:17]
.LBB0_3621:
	v_lshlrev_b32_e32 v122, 16, v180
	s_waitcnt lgkmcnt(0)
	v_and_b32_e32 v123, 0xffff0000, v180
	v_lshlrev_b32_e32 v124, 16, v176
	v_and_b32_e32 v125, 0xffff0000, v176
	v_pk_add_f32 v[122:123], v[122:123], v[124:125]
	v_lshlrev_b32_e32 v124, 16, v181
	v_and_b32_e32 v125, 0xffff0000, v181
	v_lshlrev_b32_e32 v126, 16, v177
	v_and_b32_e32 v127, 0xffff0000, v177
	v_pk_add_f32 v[124:125], v[124:125], v[126:127]
	v_lshlrev_b32_e32 v126, 16, v179
	v_pk_fma_f32 v[118:119], v[118:119], 0.5, v[124:125] op_sel_hi:[1,0,1]
	v_pk_fma_f32 v[124:125], v[116:117], 0.5, v[122:123] op_sel_hi:[1,0,1]
	v_lshlrev_b32_e32 v116, 16, v182
	v_and_b32_e32 v117, 0xffff0000, v182
	v_lshlrev_b32_e32 v122, 16, v178
	v_and_b32_e32 v123, 0xffff0000, v178
	v_pk_add_f32 v[116:117], v[116:117], v[122:123]
	v_lshlrev_b32_e32 v122, 16, v183
	v_and_b32_e32 v123, 0xffff0000, v183
	v_and_b32_e32 v127, 0xffff0000, v179
	v_pk_add_f32 v[122:123], v[122:123], v[126:127]
	v_pk_fma_f32 v[112:113], v[112:113], 0.5, v[116:117] op_sel_hi:[1,0,1]
	v_pk_fma_f32 v[126:127], v[114:115], 0.5, v[122:123] op_sel_hi:[1,0,1]
	v_cvt_pk_bf16_f32 v114, v124, v125
	v_and_b32_e32 v117, 0xffff0000, v114
	v_lshlrev_b32_e32 v116, 16, v114
	v_pk_add_f32 v[116:117], v[124:125], v[116:117] neg_lo:[0,1] neg_hi:[0,1]
	v_cvt_pk_bf16_f32 v115, v118, v119
	v_cvt_pk_bf16_f32 v122, v116, v117
	v_and_b32_e32 v117, 0xffff0000, v115
	v_lshlrev_b32_e32 v116, 16, v115
	v_pk_add_f32 v[116:117], v[118:119], v[116:117] neg_lo:[0,1] neg_hi:[0,1]
	v_pk_mul_f32 v[178:179], v[126:127], v[126:127]
	v_cvt_pk_bf16_f32 v123, v116, v117
	v_cvt_pk_bf16_f32 v116, v112, v113
	v_and_b32_e32 v177, 0xffff0000, v116
	v_lshlrev_b32_e32 v176, 16, v116
	v_pk_add_f32 v[176:177], v[112:113], v[176:177] neg_lo:[0,1] neg_hi:[0,1]
	v_pk_mul_f32 v[112:113], v[112:113], v[112:113]
	v_pk_fma_f32 v[118:119], v[118:119], v[118:119], v[178:179]
	v_pk_fma_f32 v[112:113], v[124:125], v[124:125], v[112:113]
	v_cvt_pk_bf16_f32 v117, v126, v127
	v_add_f32_e32 v112, v112, v113
	v_add_f32_e32 v112, v118, v112
	v_add_f32_e32 v112, v119, v112
	v_add_f32_e32 v112, v201, v112
	ds_bpermute_b32 v113, v200, v112
	v_and_b32_e32 v119, 0xffff0000, v117
	v_lshlrev_b32_e32 v118, 16, v117
	v_pk_add_f32 v[118:119], v[126:127], v[118:119] neg_lo:[0,1] neg_hi:[0,1]
	v_cvt_pk_bf16_f32 v124, v176, v177
	s_waitcnt lgkmcnt(0)
	v_add_f32_e32 v112, v112, v113
	ds_bpermute_b32 v113, v199, v112
	v_cvt_pk_bf16_f32 v125, v118, v119
	global_store_dwordx4 v[246:247], v[114:117], off offset:256
	global_store_dwordx4 v[248:249], v[122:125], off
	s_and_saveexec_b64 s[18:19], vcc
	s_cbranch_execz .LBB0_3623
	s_waitcnt lgkmcnt(0)
	v_add_f32_e32 v112, v112, v113
	global_atomic_add_f32 v[120:121], v112, off
.LBB0_3623:
	s_or_b64 exec, exec, s[18:19]
	v_lshlrev_b32_e32 v112, 16, v172
	s_waitcnt lgkmcnt(0)
	v_and_b32_e32 v113, 0xffff0000, v172
	v_lshlrev_b32_e32 v114, 16, v168
	v_and_b32_e32 v115, 0xffff0000, v168
	v_pk_add_f32 v[112:113], v[112:113], v[114:115]
	v_lshlrev_b32_e32 v114, 16, v173
	v_and_b32_e32 v115, 0xffff0000, v173
	v_lshlrev_b32_e32 v116, 16, v169
	v_and_b32_e32 v117, 0xffff0000, v169
	v_pk_add_f32 v[114:115], v[114:115], v[116:117]
	v_pk_fma_f32 v[118:119], v[108:109], 0.5, v[112:113] op_sel_hi:[1,0,1]
	v_pk_fma_f32 v[116:117], v[110:111], 0.5, v[114:115] op_sel_hi:[1,0,1]
	v_lshlrev_b32_e32 v108, 16, v174
	v_and_b32_e32 v109, 0xffff0000, v174
	v_lshlrev_b32_e32 v110, 16, v170
	v_and_b32_e32 v111, 0xffff0000, v170
	v_pk_add_f32 v[108:109], v[108:109], v[110:111]
	v_lshlrev_b32_e32 v110, 16, v175
	v_and_b32_e32 v111, 0xffff0000, v175
	v_lshlrev_b32_e32 v112, 16, v171
	v_and_b32_e32 v113, 0xffff0000, v171
	v_pk_add_f32 v[110:111], v[110:111], v[112:113]
	v_pk_fma_f32 v[104:105], v[104:105], 0.5, v[108:109] op_sel_hi:[1,0,1]
	v_cvt_pk_bf16_f32 v108, v118, v119
	v_pk_fma_f32 v[106:107], v[106:107], 0.5, v[110:111] op_sel_hi:[1,0,1]
	v_and_b32_e32 v111, 0xffff0000, v108
	v_lshlrev_b32_e32 v110, 16, v108
	v_pk_add_f32 v[110:111], v[118:119], v[110:111] neg_lo:[0,1] neg_hi:[0,1]
	v_cvt_pk_bf16_f32 v109, v116, v117
	v_cvt_pk_bf16_f32 v112, v110, v111
	v_and_b32_e32 v111, 0xffff0000, v109
	v_lshlrev_b32_e32 v110, 16, v109
	v_pk_add_f32 v[110:111], v[116:117], v[110:111] neg_lo:[0,1] neg_hi:[0,1]
	v_pk_mul_f32 v[120:121], v[106:107], v[106:107]
	v_cvt_pk_bf16_f32 v113, v110, v111
	v_cvt_pk_bf16_f32 v110, v104, v105
	v_and_b32_e32 v115, 0xffff0000, v110
	v_lshlrev_b32_e32 v114, 16, v110
	v_pk_add_f32 v[114:115], v[104:105], v[114:115] neg_lo:[0,1] neg_hi:[0,1]
	v_pk_mul_f32 v[104:105], v[104:105], v[104:105]
	v_pk_fma_f32 v[116:117], v[116:117], v[116:117], v[120:121]
	v_pk_fma_f32 v[104:105], v[118:119], v[118:119], v[104:105]
	v_cvt_pk_bf16_f32 v114, v114, v115
	v_add_f32_e32 v104, v104, v105
	v_add_f32_e32 v104, v116, v104
	v_add_f32_e32 v115, v117, v104
	v_mov_b32_e32 v201, v115
	v_cvt_pk_bf16_f32 v111, v106, v107
	v_and_b32_e32 v105, 0xffff0000, v111
	v_lshlrev_b32_e32 v104, 16, v111
	v_pk_add_f32 v[104:105], v[106:107], v[104:105] neg_lo:[0,1] neg_hi:[0,1]
	s_waitcnt lgkmcnt(0)
	v_cvt_pk_bf16_f32 v115, v104, v105
	v_lshl_add_u64 v[104:105], v[242:243], 2, s[16:17]
	global_store_dwordx4 v[238:239], v[108:111], off
	global_store_dwordx4 v[244:245], v[112:115], off
.LBB0_3625:
	v_lshlrev_b32_e32 v106, 16, v164
	s_waitcnt lgkmcnt(0)
	v_and_b32_e32 v107, 0xffff0000, v164
	v_lshlrev_b32_e32 v108, 16, v160
	v_and_b32_e32 v109, 0xffff0000, v160
	v_pk_add_f32 v[106:107], v[106:107], v[108:109]
	v_lshlrev_b32_e32 v108, 16, v165
	v_and_b32_e32 v109, 0xffff0000, v165
	v_lshlrev_b32_e32 v110, 16, v161
	v_and_b32_e32 v111, 0xffff0000, v161
	v_pk_add_f32 v[108:109], v[108:109], v[110:111]
	v_lshlrev_b32_e32 v110, 16, v163
	v_pk_fma_f32 v[102:103], v[102:103], 0.5, v[108:109] op_sel_hi:[1,0,1]
	v_pk_fma_f32 v[108:109], v[100:101], 0.5, v[106:107] op_sel_hi:[1,0,1]
	v_lshlrev_b32_e32 v100, 16, v166
	v_and_b32_e32 v101, 0xffff0000, v166
	v_lshlrev_b32_e32 v106, 16, v162
	v_and_b32_e32 v107, 0xffff0000, v162
	v_pk_add_f32 v[100:101], v[100:101], v[106:107]
	v_lshlrev_b32_e32 v106, 16, v167
	v_and_b32_e32 v107, 0xffff0000, v167
	v_and_b32_e32 v111, 0xffff0000, v163
	v_pk_add_f32 v[106:107], v[106:107], v[110:111]
	v_pk_fma_f32 v[96:97], v[96:97], 0.5, v[100:101] op_sel_hi:[1,0,1]
	v_pk_fma_f32 v[110:111], v[98:99], 0.5, v[106:107] op_sel_hi:[1,0,1]
	v_cvt_pk_bf16_f32 v98, v108, v109
	v_and_b32_e32 v101, 0xffff0000, v98
	v_lshlrev_b32_e32 v100, 16, v98
	v_pk_add_f32 v[100:101], v[108:109], v[100:101] neg_lo:[0,1] neg_hi:[0,1]
	v_cvt_pk_bf16_f32 v99, v102, v103
	v_cvt_pk_bf16_f32 v106, v100, v101
	v_and_b32_e32 v101, 0xffff0000, v99
	v_lshlrev_b32_e32 v100, 16, v99
	v_pk_add_f32 v[100:101], v[102:103], v[100:101] neg_lo:[0,1] neg_hi:[0,1]
	v_pk_mul_f32 v[114:115], v[110:111], v[110:111]
	v_cvt_pk_bf16_f32 v107, v100, v101
	v_cvt_pk_bf16_f32 v100, v96, v97
	v_and_b32_e32 v113, 0xffff0000, v100
	v_lshlrev_b32_e32 v112, 16, v100
	v_pk_add_f32 v[112:113], v[96:97], v[112:113] neg_lo:[0,1] neg_hi:[0,1]
	v_pk_mul_f32 v[96:97], v[96:97], v[96:97]
	v_pk_fma_f32 v[102:103], v[102:103], v[102:103], v[114:115]
	v_pk_fma_f32 v[96:97], v[108:109], v[108:109], v[96:97]
	v_cvt_pk_bf16_f32 v101, v110, v111
	v_add_f32_e32 v96, v96, v97
	v_add_f32_e32 v96, v102, v96
	v_add_f32_e32 v96, v103, v96
	v_add_f32_e32 v96, v201, v96
	ds_bpermute_b32 v97, v200, v96
	v_and_b32_e32 v103, 0xffff0000, v101
	v_lshlrev_b32_e32 v102, 16, v101
	v_pk_add_f32 v[102:103], v[110:111], v[102:103] neg_lo:[0,1] neg_hi:[0,1]
	v_cvt_pk_bf16_f32 v108, v112, v113
	s_waitcnt lgkmcnt(0)
	v_add_f32_e32 v96, v96, v97
	ds_bpermute_b32 v97, v199, v96
	v_cvt_pk_bf16_f32 v109, v102, v103
	global_store_dwordx4 v[238:239], v[98:101], off offset:256
	global_store_dwordx4 v[240:241], v[106:109], off
	s_and_saveexec_b64 s[18:19], vcc
	s_cbranch_execz .LBB0_3627
	s_waitcnt lgkmcnt(0)
	v_add_f32_e32 v96, v96, v97
	global_atomic_add_f32 v[104:105], v96, off
.LBB0_3627:
	s_or_b64 exec, exec, s[18:19]
	v_lshlrev_b32_e32 v96, 16, v156
	s_waitcnt lgkmcnt(0)
	v_and_b32_e32 v97, 0xffff0000, v156
	v_lshlrev_b32_e32 v98, 16, v152
	v_and_b32_e32 v99, 0xffff0000, v152
	v_pk_add_f32 v[96:97], v[96:97], v[98:99]
	v_lshlrev_b32_e32 v98, 16, v157
	v_and_b32_e32 v99, 0xffff0000, v157
	v_lshlrev_b32_e32 v100, 16, v153
	v_and_b32_e32 v101, 0xffff0000, v153
	v_pk_add_f32 v[98:99], v[98:99], v[100:101]
	v_pk_fma_f32 v[102:103], v[92:93], 0.5, v[96:97] op_sel_hi:[1,0,1]
	v_pk_fma_f32 v[100:101], v[94:95], 0.5, v[98:99] op_sel_hi:[1,0,1]
	v_lshlrev_b32_e32 v92, 16, v158
	v_and_b32_e32 v93, 0xffff0000, v158
	v_lshlrev_b32_e32 v94, 16, v154
	v_and_b32_e32 v95, 0xffff0000, v154
	v_pk_add_f32 v[92:93], v[92:93], v[94:95]
	v_lshlrev_b32_e32 v94, 16, v159
	v_and_b32_e32 v95, 0xffff0000, v159
	v_lshlrev_b32_e32 v96, 16, v155
	v_and_b32_e32 v97, 0xffff0000, v155
	v_pk_add_f32 v[94:95], v[94:95], v[96:97]
	v_pk_fma_f32 v[88:89], v[88:89], 0.5, v[92:93] op_sel_hi:[1,0,1]
	v_cvt_pk_bf16_f32 v92, v102, v103
	v_pk_fma_f32 v[90:91], v[90:91], 0.5, v[94:95] op_sel_hi:[1,0,1]
	v_and_b32_e32 v95, 0xffff0000, v92
	v_lshlrev_b32_e32 v94, 16, v92
	v_pk_add_f32 v[94:95], v[102:103], v[94:95] neg_lo:[0,1] neg_hi:[0,1]
	v_cvt_pk_bf16_f32 v93, v100, v101
	v_cvt_pk_bf16_f32 v96, v94, v95
	v_and_b32_e32 v95, 0xffff0000, v93
	v_lshlrev_b32_e32 v94, 16, v93
	v_pk_add_f32 v[94:95], v[100:101], v[94:95] neg_lo:[0,1] neg_hi:[0,1]
	v_pk_mul_f32 v[104:105], v[90:91], v[90:91]
	v_cvt_pk_bf16_f32 v97, v94, v95
	v_cvt_pk_bf16_f32 v94, v88, v89
	v_and_b32_e32 v99, 0xffff0000, v94
	v_lshlrev_b32_e32 v98, 16, v94
	v_pk_add_f32 v[98:99], v[88:89], v[98:99] neg_lo:[0,1] neg_hi:[0,1]
	v_pk_mul_f32 v[88:89], v[88:89], v[88:89]
	v_pk_fma_f32 v[100:101], v[100:101], v[100:101], v[104:105]
	v_pk_fma_f32 v[88:89], v[102:103], v[102:103], v[88:89]
	v_cvt_pk_bf16_f32 v98, v98, v99
	v_add_f32_e32 v88, v88, v89
	v_add_f32_e32 v88, v100, v88
	v_add_f32_e32 v99, v101, v88
	v_mov_b32_e32 v201, v99
	v_cvt_pk_bf16_f32 v95, v90, v91
	v_and_b32_e32 v89, 0xffff0000, v95
	v_lshlrev_b32_e32 v88, 16, v95
	v_pk_add_f32 v[88:89], v[90:91], v[88:89] neg_lo:[0,1] neg_hi:[0,1]
	s_waitcnt lgkmcnt(0)
	v_cvt_pk_bf16_f32 v99, v88, v89
	v_lshl_add_u64 v[88:89], v[234:235], 2, s[16:17]
	global_store_dwordx4 v[228:229], v[92:95], off
	global_store_dwordx4 v[236:237], v[96:99], off
.LBB0_3629:
	v_lshlrev_b32_e32 v90, 16, v148
	s_waitcnt lgkmcnt(0)
	v_and_b32_e32 v91, 0xffff0000, v148
	v_lshlrev_b32_e32 v92, 16, v144
	v_and_b32_e32 v93, 0xffff0000, v144
	v_pk_add_f32 v[90:91], v[90:91], v[92:93]
	v_lshlrev_b32_e32 v92, 16, v149
	v_and_b32_e32 v93, 0xffff0000, v149
	v_lshlrev_b32_e32 v94, 16, v145
	v_and_b32_e32 v95, 0xffff0000, v145
	v_pk_add_f32 v[92:93], v[92:93], v[94:95]
	v_lshlrev_b32_e32 v94, 16, v147
	v_pk_fma_f32 v[86:87], v[86:87], 0.5, v[92:93] op_sel_hi:[1,0,1]
	v_pk_fma_f32 v[92:93], v[84:85], 0.5, v[90:91] op_sel_hi:[1,0,1]
	v_lshlrev_b32_e32 v84, 16, v150
	v_and_b32_e32 v85, 0xffff0000, v150
	v_lshlrev_b32_e32 v90, 16, v146
	v_and_b32_e32 v91, 0xffff0000, v146
	v_pk_add_f32 v[84:85], v[84:85], v[90:91]
	v_lshlrev_b32_e32 v90, 16, v151
	v_and_b32_e32 v91, 0xffff0000, v151
	v_and_b32_e32 v95, 0xffff0000, v147
	v_pk_add_f32 v[90:91], v[90:91], v[94:95]
	v_pk_fma_f32 v[80:81], v[80:81], 0.5, v[84:85] op_sel_hi:[1,0,1]
	v_pk_fma_f32 v[94:95], v[82:83], 0.5, v[90:91] op_sel_hi:[1,0,1]
	v_cvt_pk_bf16_f32 v82, v92, v93
	v_and_b32_e32 v85, 0xffff0000, v82
	v_lshlrev_b32_e32 v84, 16, v82
	v_pk_add_f32 v[84:85], v[92:93], v[84:85] neg_lo:[0,1] neg_hi:[0,1]
	v_cvt_pk_bf16_f32 v83, v86, v87
	v_cvt_pk_bf16_f32 v90, v84, v85
	v_and_b32_e32 v85, 0xffff0000, v83
	v_lshlrev_b32_e32 v84, 16, v83
	v_pk_add_f32 v[84:85], v[86:87], v[84:85] neg_lo:[0,1] neg_hi:[0,1]
	v_pk_mul_f32 v[98:99], v[94:95], v[94:95]
	v_cvt_pk_bf16_f32 v91, v84, v85
	v_cvt_pk_bf16_f32 v84, v80, v81
	v_and_b32_e32 v97, 0xffff0000, v84
	v_lshlrev_b32_e32 v96, 16, v84
	v_pk_add_f32 v[96:97], v[80:81], v[96:97] neg_lo:[0,1] neg_hi:[0,1]
	v_pk_mul_f32 v[80:81], v[80:81], v[80:81]
	v_pk_fma_f32 v[86:87], v[86:87], v[86:87], v[98:99]
	v_pk_fma_f32 v[80:81], v[92:93], v[92:93], v[80:81]
	v_cvt_pk_bf16_f32 v85, v94, v95
	v_add_f32_e32 v80, v80, v81
	v_add_f32_e32 v80, v86, v80
	v_add_f32_e32 v80, v87, v80
	v_add_f32_e32 v80, v201, v80
	ds_bpermute_b32 v81, v200, v80
	v_and_b32_e32 v87, 0xffff0000, v85
	v_lshlrev_b32_e32 v86, 16, v85
	v_pk_add_f32 v[86:87], v[94:95], v[86:87] neg_lo:[0,1] neg_hi:[0,1]
	v_cvt_pk_bf16_f32 v92, v96, v97
	s_waitcnt lgkmcnt(0)
	v_add_f32_e32 v80, v80, v81
	ds_bpermute_b32 v81, v199, v80
	v_cvt_pk_bf16_f32 v93, v86, v87
	global_store_dwordx4 v[228:229], v[82:85], off offset:256
	global_store_dwordx4 v[232:233], v[90:93], off
	s_and_saveexec_b64 s[18:19], vcc
	s_cbranch_execz .LBB0_3631
	s_waitcnt lgkmcnt(0)
	v_add_f32_e32 v80, v80, v81
	global_atomic_add_f32 v[88:89], v80, off
.LBB0_3631:
	s_or_b64 exec, exec, s[18:19]
	v_lshlrev_b32_e32 v80, 16, v140
	s_waitcnt lgkmcnt(0)
	v_and_b32_e32 v81, 0xffff0000, v140
	v_lshlrev_b32_e32 v82, 16, v136
	v_and_b32_e32 v83, 0xffff0000, v136
	v_pk_add_f32 v[80:81], v[80:81], v[82:83]
	v_lshlrev_b32_e32 v82, 16, v141
	v_and_b32_e32 v83, 0xffff0000, v141
	v_lshlrev_b32_e32 v84, 16, v137
	v_and_b32_e32 v85, 0xffff0000, v137
	v_pk_add_f32 v[82:83], v[82:83], v[84:85]
	v_pk_fma_f32 v[86:87], v[76:77], 0.5, v[80:81] op_sel_hi:[1,0,1]
	v_pk_fma_f32 v[84:85], v[78:79], 0.5, v[82:83] op_sel_hi:[1,0,1]
	v_lshlrev_b32_e32 v76, 16, v142
	v_and_b32_e32 v77, 0xffff0000, v142
	v_lshlrev_b32_e32 v78, 16, v138
	v_and_b32_e32 v79, 0xffff0000, v138
	v_pk_add_f32 v[76:77], v[76:77], v[78:79]
	v_lshlrev_b32_e32 v78, 16, v143
	v_and_b32_e32 v79, 0xffff0000, v143
	v_lshlrev_b32_e32 v80, 16, v139
	v_and_b32_e32 v81, 0xffff0000, v139
	v_pk_add_f32 v[78:79], v[78:79], v[80:81]
	v_pk_fma_f32 v[72:73], v[72:73], 0.5, v[76:77] op_sel_hi:[1,0,1]
	v_cvt_pk_bf16_f32 v76, v86, v87
	v_pk_fma_f32 v[74:75], v[74:75], 0.5, v[78:79] op_sel_hi:[1,0,1]
	v_and_b32_e32 v79, 0xffff0000, v76
	v_lshlrev_b32_e32 v78, 16, v76
	v_pk_add_f32 v[78:79], v[86:87], v[78:79] neg_lo:[0,1] neg_hi:[0,1]
	v_cvt_pk_bf16_f32 v77, v84, v85
	v_cvt_pk_bf16_f32 v80, v78, v79
	v_and_b32_e32 v79, 0xffff0000, v77
	v_lshlrev_b32_e32 v78, 16, v77
	v_pk_add_f32 v[78:79], v[84:85], v[78:79] neg_lo:[0,1] neg_hi:[0,1]
	v_pk_mul_f32 v[88:89], v[74:75], v[74:75]
	v_cvt_pk_bf16_f32 v81, v78, v79
	v_cvt_pk_bf16_f32 v78, v72, v73
	v_and_b32_e32 v83, 0xffff0000, v78
	v_lshlrev_b32_e32 v82, 16, v78
	v_pk_add_f32 v[82:83], v[72:73], v[82:83] neg_lo:[0,1] neg_hi:[0,1]
	v_pk_mul_f32 v[72:73], v[72:73], v[72:73]
	v_pk_fma_f32 v[84:85], v[84:85], v[84:85], v[88:89]
	v_pk_fma_f32 v[72:73], v[86:87], v[86:87], v[72:73]
	v_cvt_pk_bf16_f32 v82, v82, v83
	v_add_f32_e32 v72, v72, v73
	v_add_f32_e32 v72, v84, v72
	v_add_f32_e32 v83, v85, v72
	v_mov_b32_e32 v201, v83
	v_cvt_pk_bf16_f32 v79, v74, v75
	v_and_b32_e32 v73, 0xffff0000, v79
	v_lshlrev_b32_e32 v72, 16, v79
	v_pk_add_f32 v[72:73], v[74:75], v[72:73] neg_lo:[0,1] neg_hi:[0,1]
	s_waitcnt lgkmcnt(0)
	v_cvt_pk_bf16_f32 v83, v72, v73
	v_lshl_add_u64 v[72:73], v[226:227], 2, s[16:17]
	global_store_dwordx4 v[222:223], v[76:79], off
	global_store_dwordx4 v[230:231], v[80:83], off
.LBB0_3633:
	v_lshlrev_b32_e32 v74, 16, v128
	s_waitcnt lgkmcnt(0)
	v_and_b32_e32 v75, 0xffff0000, v128
	v_lshlrev_b32_e32 v76, 16, v132
	v_and_b32_e32 v77, 0xffff0000, v132
	v_pk_add_f32 v[74:75], v[74:75], v[76:77]
	v_lshlrev_b32_e32 v76, 16, v129
	v_and_b32_e32 v77, 0xffff0000, v129
	v_lshlrev_b32_e32 v78, 16, v133
	v_and_b32_e32 v79, 0xffff0000, v133
	v_pk_add_f32 v[76:77], v[76:77], v[78:79]
	v_lshlrev_b32_e32 v78, 16, v135
	v_pk_fma_f32 v[70:71], v[70:71], 0.5, v[76:77] op_sel_hi:[1,0,1]
	v_pk_fma_f32 v[76:77], v[68:69], 0.5, v[74:75] op_sel_hi:[1,0,1]
	v_lshlrev_b32_e32 v68, 16, v130
	v_and_b32_e32 v69, 0xffff0000, v130
	v_lshlrev_b32_e32 v74, 16, v134
	v_and_b32_e32 v75, 0xffff0000, v134
	v_pk_add_f32 v[68:69], v[68:69], v[74:75]
	v_lshlrev_b32_e32 v74, 16, v131
	v_and_b32_e32 v75, 0xffff0000, v131
	v_and_b32_e32 v79, 0xffff0000, v135
	v_pk_add_f32 v[74:75], v[74:75], v[78:79]
	v_pk_fma_f32 v[64:65], v[64:65], 0.5, v[68:69] op_sel_hi:[1,0,1]
	v_pk_fma_f32 v[78:79], v[66:67], 0.5, v[74:75] op_sel_hi:[1,0,1]
	v_cvt_pk_bf16_f32 v66, v76, v77
	v_and_b32_e32 v69, 0xffff0000, v66
	v_lshlrev_b32_e32 v68, 16, v66
	v_pk_add_f32 v[68:69], v[76:77], v[68:69] neg_lo:[0,1] neg_hi:[0,1]
	v_cvt_pk_bf16_f32 v67, v70, v71
	v_cvt_pk_bf16_f32 v74, v68, v69
	v_and_b32_e32 v69, 0xffff0000, v67
	v_lshlrev_b32_e32 v68, 16, v67
	v_pk_add_f32 v[68:69], v[70:71], v[68:69] neg_lo:[0,1] neg_hi:[0,1]
	v_pk_mul_f32 v[82:83], v[78:79], v[78:79]
	v_cvt_pk_bf16_f32 v75, v68, v69
	v_cvt_pk_bf16_f32 v68, v64, v65
	v_and_b32_e32 v81, 0xffff0000, v68
	v_lshlrev_b32_e32 v80, 16, v68
	v_pk_add_f32 v[80:81], v[64:65], v[80:81] neg_lo:[0,1] neg_hi:[0,1]
	v_pk_mul_f32 v[64:65], v[64:65], v[64:65]
	v_pk_fma_f32 v[70:71], v[70:71], v[70:71], v[82:83]
	v_pk_fma_f32 v[64:65], v[76:77], v[76:77], v[64:65]
	v_cvt_pk_bf16_f32 v69, v78, v79
	v_add_f32_e32 v64, v64, v65
	v_add_f32_e32 v64, v70, v64
	v_add_f32_e32 v64, v71, v64
	v_add_f32_e32 v64, v201, v64
	ds_bpermute_b32 v65, v200, v64
	v_and_b32_e32 v71, 0xffff0000, v69
	v_lshlrev_b32_e32 v70, 16, v69
	v_pk_add_f32 v[70:71], v[78:79], v[70:71] neg_lo:[0,1] neg_hi:[0,1]
	v_cvt_pk_bf16_f32 v76, v80, v81
	s_waitcnt lgkmcnt(0)
	v_add_f32_e32 v64, v64, v65
	ds_bpermute_b32 v65, v199, v64
	v_cvt_pk_bf16_f32 v77, v70, v71
	global_store_dwordx4 v[222:223], v[66:69], off offset:256
	global_store_dwordx4 v[224:225], v[74:77], off
	s_and_saveexec_b64 s[18:19], vcc
	s_cbranch_execz .LBB0_3635
	s_waitcnt lgkmcnt(0)
	v_add_f32_e32 v64, v64, v65
	global_atomic_add_f32 v[72:73], v64, off
.LBB0_3635:
	s_or_b64 exec, exec, s[18:19]
	v_add_u32_e32 v156, 0x80, v218
	v_ashrrev_i32_e32 v157, 31, v156
	s_waitcnt lgkmcnt(0)
	v_lshlrev_b64 v[64:65], 10, v[156:157]
	v_lshl_add_u64 v[66:67], v[64:65], 0, v[216:217]
	v_lshlrev_b64 v[66:67], 1, v[66:67]
	v_lshl_add_u64 v[152:153], s[10:11], 0, v[66:67]
	v_lshl_add_u64 v[158:159], s[12:13], 0, v[66:67]
	global_load_dwordx4 v[124:127], v[152:153], off
	global_load_dwordx4 v[116:119], v[152:153], off offset:256
	global_load_dwordx4 v[120:123], v[158:159], off
	v_add_u32_e32 v148, 0x90, v218
	v_lshl_add_u64 v[64:65], v[64:65], 0, v[220:221]
	v_ashrrev_i32_e32 v149, 31, v148
	v_lshl_add_u64 v[154:155], v[64:65], 1, s[12:13]
	v_lshlrev_b64 v[64:65], 10, v[148:149]
	v_add_u32_e32 v140, 0xa0, v218
	v_lshl_add_u64 v[66:67], v[64:65], 0, v[216:217]
	v_lshl_add_u64 v[64:65], v[64:65], 0, v[220:221]
	v_ashrrev_i32_e32 v141, 31, v140
	v_lshlrev_b64 v[66:67], 1, v[66:67]
	v_lshl_add_u64 v[146:147], v[64:65], 1, s[12:13]
	v_lshlrev_b64 v[64:65], 10, v[140:141]
	v_add_u32_e32 v132, 0xb0, v218
	v_lshl_add_u64 v[144:145], s[10:11], 0, v[66:67]
	v_lshl_add_u64 v[150:151], s[12:13], 0, v[66:67]
	v_lshl_add_u64 v[66:67], v[64:65], 0, v[216:217]
	v_lshl_add_u64 v[64:65], v[64:65], 0, v[220:221]
	v_ashrrev_i32_e32 v133, 31, v132
	v_lshlrev_b64 v[66:67], 1, v[66:67]
	v_lshl_add_u64 v[138:139], v[64:65], 1, s[12:13]
	v_lshlrev_b64 v[64:65], 10, v[132:133]
	v_lshl_add_u64 v[136:137], s[10:11], 0, v[66:67]
	v_lshl_add_u64 v[142:143], s[12:13], 0, v[66:67]
	v_lshl_add_u64 v[66:67], v[64:65], 0, v[216:217]
	v_lshlrev_b64 v[66:67], 1, v[66:67]
	v_lshl_add_u64 v[76:77], v[64:65], 0, v[220:221]
	v_lshl_add_u64 v[128:129], s[10:11], 0, v[66:67]
	v_lshl_add_u64 v[134:135], s[12:13], 0, v[66:67]
	v_lshl_add_u64 v[130:131], v[76:77], 1, s[12:13]
	global_load_dwordx4 v[112:115], v[154:155], off
	global_load_dwordx4 v[108:111], v[144:145], off
	global_load_dwordx4 v[100:103], v[144:145], off offset:256
	global_load_dwordx4 v[104:107], v[150:151], off
	global_load_dwordx4 v[96:99], v[146:147], off
	global_load_dwordx4 v[92:95], v[136:137], off
	global_load_dwordx4 v[84:87], v[136:137], off offset:256
	global_load_dwordx4 v[88:91], v[142:143], off
	global_load_dwordx4 v[80:83], v[138:139], off
	global_load_dwordx4 v[72:75], v[128:129], off
	global_load_dwordx4 v[64:67], v[128:129], off offset:256
	global_load_dwordx4 v[68:71], v[134:135], off
	global_load_dwordx4 v[76:79], v[130:131], off
	s_waitcnt vmcnt(15)
	v_lshlrev_b32_e32 v160, 16, v124
	v_and_b32_e32 v161, 0xffff0000, v124
	s_waitcnt vmcnt(13)
	v_lshlrev_b32_e32 v162, 16, v120
	v_and_b32_e32 v163, 0xffff0000, v120
	v_lshlrev_b32_e32 v124, 16, v125
	v_and_b32_e32 v125, 0xffff0000, v125
	v_lshlrev_b32_e32 v120, 16, v121
	v_and_b32_e32 v121, 0xffff0000, v121
	v_pk_add_f32 v[160:161], v[160:161], v[162:163]
	v_pk_add_f32 v[120:121], v[124:125], v[120:121]
	v_pk_fma_f32 v[124:125], v[60:61], 0.5, v[160:161] op_sel_hi:[1,0,1]
	v_pk_fma_f32 v[120:121], v[62:63], 0.5, v[120:121] op_sel_hi:[1,0,1]
	v_lshlrev_b32_e32 v60, 16, v126
	v_and_b32_e32 v61, 0xffff0000, v126
	v_lshlrev_b32_e32 v62, 16, v122
	v_and_b32_e32 v63, 0xffff0000, v122
	v_pk_add_f32 v[60:61], v[60:61], v[62:63]
	v_lshlrev_b32_e32 v62, 16, v127
	v_and_b32_e32 v63, 0xffff0000, v127
	v_lshlrev_b32_e32 v122, 16, v123
	v_and_b32_e32 v123, 0xffff0000, v123
	v_pk_add_f32 v[62:63], v[62:63], v[122:123]
	v_pk_fma_f32 v[126:127], v[56:57], 0.5, v[60:61] op_sel_hi:[1,0,1]
	v_cvt_pk_bf16_f32 v56, v124, v125
	v_pk_fma_f32 v[122:123], v[58:59], 0.5, v[62:63] op_sel_hi:[1,0,1]
	v_and_b32_e32 v59, 0xffff0000, v56
	v_lshlrev_b32_e32 v58, 16, v56
	v_pk_add_f32 v[58:59], v[124:125], v[58:59] neg_lo:[0,1] neg_hi:[0,1]
	v_cvt_pk_bf16_f32 v57, v120, v121
	v_cvt_pk_bf16_f32 v60, v58, v59
	v_and_b32_e32 v59, 0xffff0000, v57
	v_lshlrev_b32_e32 v58, 16, v57
	v_pk_add_f32 v[58:59], v[120:121], v[58:59] neg_lo:[0,1] neg_hi:[0,1]
	s_nop 0
	v_cvt_pk_bf16_f32 v61, v58, v59
	v_cvt_pk_bf16_f32 v58, v126, v127
	v_cvt_pk_bf16_f32 v59, v122, v123
	v_and_b32_e32 v63, 0xffff0000, v58
	v_lshlrev_b32_e32 v62, 16, v58
	v_and_b32_e32 v161, 0xffff0000, v59
	v_lshlrev_b32_e32 v160, 16, v59
	v_pk_add_f32 v[62:63], v[126:127], v[62:63] neg_lo:[0,1] neg_hi:[0,1]
	v_pk_add_f32 v[160:161], v[122:123], v[160:161] neg_lo:[0,1] neg_hi:[0,1]
	v_cvt_pk_bf16_f32 v62, v62, v63
	v_cvt_pk_bf16_f32 v63, v160, v161
	global_store_dwordx4 v[152:153], v[56:59], off
	global_store_dwordx4 v[158:159], v[60:63], off
	s_nop 0
	v_pk_mul_f32 v[58:59], v[126:127], v[126:127]
	v_pk_mul_f32 v[56:57], v[122:123], v[122:123]
	v_pk_fma_f32 v[58:59], v[124:125], v[124:125], v[58:59]
	v_pk_fma_f32 v[56:57], v[120:121], v[120:121], v[56:57]
	v_add_f32_e32 v58, v58, v59
	v_add_f32_e32 v56, v56, v58
	v_add_f32_e32 v56, v57, v56
	v_mov_b32_e32 v201, v56
	s_waitcnt lgkmcnt(0)
	v_lshl_add_u64 v[56:57], v[156:157], 2, s[16:17]
.LBB0_3637:
	v_lshlrev_b32_e32 v58, 16, v116
	s_waitcnt lgkmcnt(0)
	v_and_b32_e32 v59, 0xffff0000, v116
	s_waitcnt vmcnt(13)
	v_lshlrev_b32_e32 v60, 16, v112
	v_and_b32_e32 v61, 0xffff0000, v112
	v_pk_add_f32 v[58:59], v[58:59], v[60:61]
	v_lshlrev_b32_e32 v60, 16, v117
	v_and_b32_e32 v61, 0xffff0000, v117
	v_lshlrev_b32_e32 v62, 16, v113
	v_and_b32_e32 v63, 0xffff0000, v113
	v_pk_add_f32 v[60:61], v[60:61], v[62:63]
	v_lshlrev_b32_e32 v62, 16, v115
	v_pk_fma_f32 v[54:55], v[54:55], 0.5, v[60:61] op_sel_hi:[1,0,1]
	v_pk_fma_f32 v[60:61], v[52:53], 0.5, v[58:59] op_sel_hi:[1,0,1]
	v_lshlrev_b32_e32 v52, 16, v118
	v_and_b32_e32 v53, 0xffff0000, v118
	v_lshlrev_b32_e32 v58, 16, v114
	v_and_b32_e32 v59, 0xffff0000, v114
	v_pk_add_f32 v[52:53], v[52:53], v[58:59]
	v_lshlrev_b32_e32 v58, 16, v119
	v_and_b32_e32 v59, 0xffff0000, v119
	v_and_b32_e32 v63, 0xffff0000, v115
	v_pk_add_f32 v[58:59], v[58:59], v[62:63]
	v_pk_fma_f32 v[48:49], v[48:49], 0.5, v[52:53] op_sel_hi:[1,0,1]
	v_pk_fma_f32 v[62:63], v[50:51], 0.5, v[58:59] op_sel_hi:[1,0,1]
	v_cvt_pk_bf16_f32 v50, v60, v61
	v_and_b32_e32 v53, 0xffff0000, v50
	v_lshlrev_b32_e32 v52, 16, v50
	v_pk_add_f32 v[52:53], v[60:61], v[52:53] neg_lo:[0,1] neg_hi:[0,1]
	v_cvt_pk_bf16_f32 v51, v54, v55
	v_cvt_pk_bf16_f32 v58, v52, v53
	v_and_b32_e32 v53, 0xffff0000, v51
	v_lshlrev_b32_e32 v52, 16, v51
	v_pk_add_f32 v[52:53], v[54:55], v[52:53] neg_lo:[0,1] neg_hi:[0,1]
	v_pk_mul_f32 v[114:115], v[62:63], v[62:63]
	v_cvt_pk_bf16_f32 v59, v52, v53
	v_cvt_pk_bf16_f32 v52, v48, v49
	v_and_b32_e32 v113, 0xffff0000, v52
	v_lshlrev_b32_e32 v112, 16, v52
	v_pk_add_f32 v[112:113], v[48:49], v[112:113] neg_lo:[0,1] neg_hi:[0,1]
	v_pk_mul_f32 v[48:49], v[48:49], v[48:49]
	v_pk_fma_f32 v[54:55], v[54:55], v[54:55], v[114:115]
	v_pk_fma_f32 v[48:49], v[60:61], v[60:61], v[48:49]
	v_cvt_pk_bf16_f32 v53, v62, v63
	v_add_f32_e32 v48, v48, v49
	v_add_f32_e32 v48, v54, v48
	v_add_f32_e32 v48, v55, v48
	v_add_f32_e32 v48, v201, v48
	ds_bpermute_b32 v49, v200, v48
	v_and_b32_e32 v55, 0xffff0000, v53
	v_lshlrev_b32_e32 v54, 16, v53
	v_pk_add_f32 v[54:55], v[62:63], v[54:55] neg_lo:[0,1] neg_hi:[0,1]
	v_cvt_pk_bf16_f32 v60, v112, v113
	s_waitcnt lgkmcnt(0)
	v_add_f32_e32 v48, v48, v49
	ds_bpermute_b32 v49, v199, v48
	v_cvt_pk_bf16_f32 v61, v54, v55
	global_store_dwordx4 v[152:153], v[50:53], off offset:256
	global_store_dwordx4 v[154:155], v[58:61], off
	s_and_saveexec_b64 s[18:19], vcc
	s_cbranch_execz .LBB0_3639
	s_waitcnt lgkmcnt(0)
	v_add_f32_e32 v48, v48, v49
	global_atomic_add_f32 v[56:57], v48, off
.LBB0_3639:
	s_or_b64 exec, exec, s[18:19]
	s_waitcnt vmcnt(14)
	v_lshlrev_b32_e32 v48, 16, v108
	s_waitcnt lgkmcnt(0)
	v_and_b32_e32 v49, 0xffff0000, v108
	s_waitcnt vmcnt(12)
	v_lshlrev_b32_e32 v50, 16, v104
	v_and_b32_e32 v51, 0xffff0000, v104
	v_pk_add_f32 v[48:49], v[48:49], v[50:51]
	v_lshlrev_b32_e32 v50, 16, v109
	v_and_b32_e32 v51, 0xffff0000, v109
	v_lshlrev_b32_e32 v52, 16, v105
	v_and_b32_e32 v53, 0xffff0000, v105
	v_pk_add_f32 v[50:51], v[50:51], v[52:53]
	v_pk_fma_f32 v[54:55], v[44:45], 0.5, v[48:49] op_sel_hi:[1,0,1]
	v_pk_fma_f32 v[52:53], v[46:47], 0.5, v[50:51] op_sel_hi:[1,0,1]
	v_lshlrev_b32_e32 v44, 16, v110
	v_and_b32_e32 v45, 0xffff0000, v110
	v_lshlrev_b32_e32 v46, 16, v106
	v_and_b32_e32 v47, 0xffff0000, v106
	v_pk_add_f32 v[44:45], v[44:45], v[46:47]
	v_lshlrev_b32_e32 v46, 16, v111
	v_and_b32_e32 v47, 0xffff0000, v111
	v_lshlrev_b32_e32 v48, 16, v107
	v_and_b32_e32 v49, 0xffff0000, v107
	v_pk_add_f32 v[46:47], v[46:47], v[48:49]
	v_pk_fma_f32 v[40:41], v[40:41], 0.5, v[44:45] op_sel_hi:[1,0,1]
	v_cvt_pk_bf16_f32 v44, v54, v55
	v_pk_fma_f32 v[42:43], v[42:43], 0.5, v[46:47] op_sel_hi:[1,0,1]
	v_and_b32_e32 v47, 0xffff0000, v44
	v_lshlrev_b32_e32 v46, 16, v44
	v_pk_add_f32 v[46:47], v[54:55], v[46:47] neg_lo:[0,1] neg_hi:[0,1]
	v_cvt_pk_bf16_f32 v45, v52, v53
	v_cvt_pk_bf16_f32 v48, v46, v47
	v_and_b32_e32 v47, 0xffff0000, v45
	v_lshlrev_b32_e32 v46, 16, v45
	v_pk_add_f32 v[46:47], v[52:53], v[46:47] neg_lo:[0,1] neg_hi:[0,1]
	v_pk_mul_f32 v[56:57], v[42:43], v[42:43]
	v_cvt_pk_bf16_f32 v49, v46, v47
	v_cvt_pk_bf16_f32 v46, v40, v41
	v_and_b32_e32 v51, 0xffff0000, v46
	v_lshlrev_b32_e32 v50, 16, v46
	v_pk_add_f32 v[50:51], v[40:41], v[50:51] neg_lo:[0,1] neg_hi:[0,1]
	v_pk_mul_f32 v[40:41], v[40:41], v[40:41]
	v_pk_fma_f32 v[52:53], v[52:53], v[52:53], v[56:57]
	v_pk_fma_f32 v[40:41], v[54:55], v[54:55], v[40:41]
	v_cvt_pk_bf16_f32 v50, v50, v51
	v_add_f32_e32 v40, v40, v41
	v_add_f32_e32 v40, v52, v40
	v_add_f32_e32 v51, v53, v40
	v_mov_b32_e32 v201, v51
	v_cvt_pk_bf16_f32 v47, v42, v43
	v_and_b32_e32 v41, 0xffff0000, v47
	v_lshlrev_b32_e32 v40, 16, v47
	v_pk_add_f32 v[40:41], v[42:43], v[40:41] neg_lo:[0,1] neg_hi:[0,1]
	s_waitcnt lgkmcnt(0)
	v_cvt_pk_bf16_f32 v51, v40, v41
	v_lshl_add_u64 v[40:41], v[148:149], 2, s[16:17]
	global_store_dwordx4 v[144:145], v[44:47], off
	global_store_dwordx4 v[150:151], v[48:51], off
.LBB0_3641:
	v_lshlrev_b32_e32 v42, 16, v100
	s_waitcnt lgkmcnt(0)
	v_and_b32_e32 v43, 0xffff0000, v100
	s_waitcnt vmcnt(12)
	v_lshlrev_b32_e32 v44, 16, v96
	v_and_b32_e32 v45, 0xffff0000, v96
	v_pk_add_f32 v[42:43], v[42:43], v[44:45]
	v_lshlrev_b32_e32 v44, 16, v101
	v_and_b32_e32 v45, 0xffff0000, v101
	v_lshlrev_b32_e32 v46, 16, v97
	v_and_b32_e32 v47, 0xffff0000, v97
	v_pk_add_f32 v[44:45], v[44:45], v[46:47]
	v_lshlrev_b32_e32 v46, 16, v99
	v_pk_fma_f32 v[38:39], v[38:39], 0.5, v[44:45] op_sel_hi:[1,0,1]
	v_pk_fma_f32 v[44:45], v[36:37], 0.5, v[42:43] op_sel_hi:[1,0,1]
	v_lshlrev_b32_e32 v36, 16, v102
	v_and_b32_e32 v37, 0xffff0000, v102
	v_lshlrev_b32_e32 v42, 16, v98
	v_and_b32_e32 v43, 0xffff0000, v98
	v_pk_add_f32 v[36:37], v[36:37], v[42:43]
	v_lshlrev_b32_e32 v42, 16, v103
	v_and_b32_e32 v43, 0xffff0000, v103
	v_and_b32_e32 v47, 0xffff0000, v99
	v_pk_add_f32 v[42:43], v[42:43], v[46:47]
	v_pk_fma_f32 v[32:33], v[32:33], 0.5, v[36:37] op_sel_hi:[1,0,1]
	v_pk_fma_f32 v[46:47], v[34:35], 0.5, v[42:43] op_sel_hi:[1,0,1]
	v_cvt_pk_bf16_f32 v34, v44, v45
	v_and_b32_e32 v37, 0xffff0000, v34
	v_lshlrev_b32_e32 v36, 16, v34
	v_pk_add_f32 v[36:37], v[44:45], v[36:37] neg_lo:[0,1] neg_hi:[0,1]
	v_cvt_pk_bf16_f32 v35, v38, v39
	v_cvt_pk_bf16_f32 v42, v36, v37
	v_and_b32_e32 v37, 0xffff0000, v35
	v_lshlrev_b32_e32 v36, 16, v35
	v_pk_add_f32 v[36:37], v[38:39], v[36:37] neg_lo:[0,1] neg_hi:[0,1]
	v_pk_mul_f32 v[50:51], v[46:47], v[46:47]
	v_cvt_pk_bf16_f32 v43, v36, v37
	v_cvt_pk_bf16_f32 v36, v32, v33
	v_and_b32_e32 v49, 0xffff0000, v36
	v_lshlrev_b32_e32 v48, 16, v36
	v_pk_add_f32 v[48:49], v[32:33], v[48:49] neg_lo:[0,1] neg_hi:[0,1]
	v_pk_mul_f32 v[32:33], v[32:33], v[32:33]
	v_pk_fma_f32 v[38:39], v[38:39], v[38:39], v[50:51]
	v_pk_fma_f32 v[32:33], v[44:45], v[44:45], v[32:33]
	v_cvt_pk_bf16_f32 v37, v46, v47
	v_add_f32_e32 v32, v32, v33
	v_add_f32_e32 v32, v38, v32
	v_add_f32_e32 v32, v39, v32
	v_add_f32_e32 v32, v201, v32
	ds_bpermute_b32 v33, v200, v32
	v_and_b32_e32 v39, 0xffff0000, v37
	v_lshlrev_b32_e32 v38, 16, v37
	v_pk_add_f32 v[38:39], v[46:47], v[38:39] neg_lo:[0,1] neg_hi:[0,1]
	v_cvt_pk_bf16_f32 v44, v48, v49
	s_waitcnt lgkmcnt(0)
	v_add_f32_e32 v32, v32, v33
	ds_bpermute_b32 v33, v199, v32
	v_cvt_pk_bf16_f32 v45, v38, v39
	global_store_dwordx4 v[144:145], v[34:37], off offset:256
	global_store_dwordx4 v[146:147], v[42:45], off
	s_and_saveexec_b64 s[18:19], vcc
	s_cbranch_execz .LBB0_3643
	s_waitcnt lgkmcnt(0)
	v_add_f32_e32 v32, v32, v33
	global_atomic_add_f32 v[40:41], v32, off
.LBB0_3643:
	s_or_b64 exec, exec, s[18:19]
	s_waitcnt vmcnt(13)
	v_lshlrev_b32_e32 v32, 16, v92
	s_waitcnt lgkmcnt(0)
	v_and_b32_e32 v33, 0xffff0000, v92
	s_waitcnt vmcnt(11)
	v_lshlrev_b32_e32 v34, 16, v88
	v_and_b32_e32 v35, 0xffff0000, v88
	v_pk_add_f32 v[32:33], v[32:33], v[34:35]
	v_lshlrev_b32_e32 v34, 16, v93
	v_and_b32_e32 v35, 0xffff0000, v93
	v_lshlrev_b32_e32 v36, 16, v89
	v_and_b32_e32 v37, 0xffff0000, v89
	v_pk_add_f32 v[34:35], v[34:35], v[36:37]
	v_pk_fma_f32 v[38:39], v[28:29], 0.5, v[32:33] op_sel_hi:[1,0,1]
	v_pk_fma_f32 v[36:37], v[30:31], 0.5, v[34:35] op_sel_hi:[1,0,1]
	v_lshlrev_b32_e32 v28, 16, v94
	v_and_b32_e32 v29, 0xffff0000, v94
	v_lshlrev_b32_e32 v30, 16, v90
	v_and_b32_e32 v31, 0xffff0000, v90
	v_pk_add_f32 v[28:29], v[28:29], v[30:31]
	v_lshlrev_b32_e32 v30, 16, v95
	v_and_b32_e32 v31, 0xffff0000, v95
	v_lshlrev_b32_e32 v32, 16, v91
	v_and_b32_e32 v33, 0xffff0000, v91
	v_pk_add_f32 v[30:31], v[30:31], v[32:33]
	v_pk_fma_f32 v[24:25], v[24:25], 0.5, v[28:29] op_sel_hi:[1,0,1]
	v_cvt_pk_bf16_f32 v28, v38, v39
	v_pk_fma_f32 v[26:27], v[26:27], 0.5, v[30:31] op_sel_hi:[1,0,1]
	v_and_b32_e32 v31, 0xffff0000, v28
	v_lshlrev_b32_e32 v30, 16, v28
	v_pk_add_f32 v[30:31], v[38:39], v[30:31] neg_lo:[0,1] neg_hi:[0,1]
	v_cvt_pk_bf16_f32 v29, v36, v37
	v_cvt_pk_bf16_f32 v32, v30, v31
	v_and_b32_e32 v31, 0xffff0000, v29
	v_lshlrev_b32_e32 v30, 16, v29
	v_pk_add_f32 v[30:31], v[36:37], v[30:31] neg_lo:[0,1] neg_hi:[0,1]
	v_pk_mul_f32 v[40:41], v[26:27], v[26:27]
	v_cvt_pk_bf16_f32 v33, v30, v31
	v_cvt_pk_bf16_f32 v30, v24, v25
	v_and_b32_e32 v35, 0xffff0000, v30
	v_lshlrev_b32_e32 v34, 16, v30
	v_pk_add_f32 v[34:35], v[24:25], v[34:35] neg_lo:[0,1] neg_hi:[0,1]
	v_pk_mul_f32 v[24:25], v[24:25], v[24:25]
	v_pk_fma_f32 v[36:37], v[36:37], v[36:37], v[40:41]
	v_pk_fma_f32 v[24:25], v[38:39], v[38:39], v[24:25]
	v_cvt_pk_bf16_f32 v34, v34, v35
	v_add_f32_e32 v24, v24, v25
	v_add_f32_e32 v24, v36, v24
	v_add_f32_e32 v35, v37, v24
	v_mov_b32_e32 v201, v35
	v_cvt_pk_bf16_f32 v31, v26, v27
	v_and_b32_e32 v25, 0xffff0000, v31
	v_lshlrev_b32_e32 v24, 16, v31
	v_pk_add_f32 v[24:25], v[26:27], v[24:25] neg_lo:[0,1] neg_hi:[0,1]
	s_waitcnt lgkmcnt(0)
	v_cvt_pk_bf16_f32 v35, v24, v25
	v_lshl_add_u64 v[24:25], v[140:141], 2, s[16:17]
	global_store_dwordx4 v[136:137], v[28:31], off
	global_store_dwordx4 v[142:143], v[32:35], off
.LBB0_3645:
	v_lshlrev_b32_e32 v26, 16, v84
	s_waitcnt lgkmcnt(0)
	v_and_b32_e32 v27, 0xffff0000, v84
	s_waitcnt vmcnt(11)
	v_lshlrev_b32_e32 v28, 16, v80
	v_and_b32_e32 v29, 0xffff0000, v80
	v_pk_add_f32 v[26:27], v[26:27], v[28:29]
	v_lshlrev_b32_e32 v28, 16, v85
	v_and_b32_e32 v29, 0xffff0000, v85
	v_lshlrev_b32_e32 v30, 16, v81
	v_and_b32_e32 v31, 0xffff0000, v81
	v_pk_add_f32 v[28:29], v[28:29], v[30:31]
	v_lshlrev_b32_e32 v30, 16, v83
	v_pk_fma_f32 v[22:23], v[22:23], 0.5, v[28:29] op_sel_hi:[1,0,1]
	v_pk_fma_f32 v[28:29], v[20:21], 0.5, v[26:27] op_sel_hi:[1,0,1]
	v_lshlrev_b32_e32 v20, 16, v86
	v_and_b32_e32 v21, 0xffff0000, v86
	v_lshlrev_b32_e32 v26, 16, v82
	v_and_b32_e32 v27, 0xffff0000, v82
	v_pk_add_f32 v[20:21], v[20:21], v[26:27]
	v_lshlrev_b32_e32 v26, 16, v87
	v_and_b32_e32 v27, 0xffff0000, v87
	v_and_b32_e32 v31, 0xffff0000, v83
	v_pk_add_f32 v[26:27], v[26:27], v[30:31]
	v_pk_fma_f32 v[16:17], v[16:17], 0.5, v[20:21] op_sel_hi:[1,0,1]
	v_pk_fma_f32 v[30:31], v[18:19], 0.5, v[26:27] op_sel_hi:[1,0,1]
	v_cvt_pk_bf16_f32 v18, v28, v29
	v_and_b32_e32 v21, 0xffff0000, v18
	v_lshlrev_b32_e32 v20, 16, v18
	v_pk_add_f32 v[20:21], v[28:29], v[20:21] neg_lo:[0,1] neg_hi:[0,1]
	v_cvt_pk_bf16_f32 v19, v22, v23
	v_cvt_pk_bf16_f32 v26, v20, v21
	v_and_b32_e32 v21, 0xffff0000, v19
	v_lshlrev_b32_e32 v20, 16, v19
	v_pk_add_f32 v[20:21], v[22:23], v[20:21] neg_lo:[0,1] neg_hi:[0,1]
	v_pk_mul_f32 v[34:35], v[30:31], v[30:31]
	v_cvt_pk_bf16_f32 v27, v20, v21
	v_cvt_pk_bf16_f32 v20, v16, v17
	v_and_b32_e32 v33, 0xffff0000, v20
	v_lshlrev_b32_e32 v32, 16, v20
	v_pk_add_f32 v[32:33], v[16:17], v[32:33] neg_lo:[0,1] neg_hi:[0,1]
	v_pk_mul_f32 v[16:17], v[16:17], v[16:17]
	v_pk_fma_f32 v[22:23], v[22:23], v[22:23], v[34:35]
	v_pk_fma_f32 v[16:17], v[28:29], v[28:29], v[16:17]
	v_cvt_pk_bf16_f32 v21, v30, v31
	v_add_f32_e32 v16, v16, v17
	v_add_f32_e32 v16, v22, v16
	v_add_f32_e32 v16, v23, v16
	v_add_f32_e32 v16, v201, v16
	ds_bpermute_b32 v17, v200, v16
	v_and_b32_e32 v23, 0xffff0000, v21
	v_lshlrev_b32_e32 v22, 16, v21
	v_pk_add_f32 v[22:23], v[30:31], v[22:23] neg_lo:[0,1] neg_hi:[0,1]
	v_cvt_pk_bf16_f32 v28, v32, v33
	s_waitcnt lgkmcnt(0)
	v_add_f32_e32 v16, v16, v17
	ds_bpermute_b32 v17, v199, v16
	v_cvt_pk_bf16_f32 v29, v22, v23
	global_store_dwordx4 v[136:137], v[18:21], off offset:256
	global_store_dwordx4 v[138:139], v[26:29], off
	s_and_saveexec_b64 s[18:19], vcc
	s_cbranch_execz .LBB0_3647
	s_waitcnt lgkmcnt(0)
	v_add_f32_e32 v16, v16, v17
	global_atomic_add_f32 v[24:25], v16, off
.LBB0_3647:
	s_or_b64 exec, exec, s[18:19]
	s_waitcnt vmcnt(12)
	v_lshlrev_b32_e32 v16, 16, v72
	s_waitcnt lgkmcnt(0)
	v_and_b32_e32 v17, 0xffff0000, v72
	s_waitcnt vmcnt(10)
	v_lshlrev_b32_e32 v18, 16, v68
	v_and_b32_e32 v19, 0xffff0000, v68
	v_pk_add_f32 v[16:17], v[16:17], v[18:19]
	v_lshlrev_b32_e32 v18, 16, v73
	v_and_b32_e32 v19, 0xffff0000, v73
	v_lshlrev_b32_e32 v20, 16, v69
	v_and_b32_e32 v21, 0xffff0000, v69
	v_pk_add_f32 v[18:19], v[18:19], v[20:21]
	v_pk_fma_f32 v[22:23], v[12:13], 0.5, v[16:17] op_sel_hi:[1,0,1]
	v_pk_fma_f32 v[20:21], v[14:15], 0.5, v[18:19] op_sel_hi:[1,0,1]
	v_lshlrev_b32_e32 v12, 16, v74
	v_and_b32_e32 v13, 0xffff0000, v74
	v_lshlrev_b32_e32 v14, 16, v70
	v_and_b32_e32 v15, 0xffff0000, v70
	v_pk_add_f32 v[12:13], v[12:13], v[14:15]
	v_lshlrev_b32_e32 v14, 16, v75
	v_and_b32_e32 v15, 0xffff0000, v75
	v_lshlrev_b32_e32 v16, 16, v71
	v_and_b32_e32 v17, 0xffff0000, v71
	v_pk_add_f32 v[14:15], v[14:15], v[16:17]
	v_pk_fma_f32 v[8:9], v[8:9], 0.5, v[12:13] op_sel_hi:[1,0,1]
	v_cvt_pk_bf16_f32 v12, v22, v23
	v_pk_fma_f32 v[10:11], v[10:11], 0.5, v[14:15] op_sel_hi:[1,0,1]
	v_and_b32_e32 v15, 0xffff0000, v12
	v_lshlrev_b32_e32 v14, 16, v12
	v_pk_add_f32 v[14:15], v[22:23], v[14:15] neg_lo:[0,1] neg_hi:[0,1]
	v_cvt_pk_bf16_f32 v13, v20, v21
	v_cvt_pk_bf16_f32 v16, v14, v15
	v_and_b32_e32 v15, 0xffff0000, v13
	v_lshlrev_b32_e32 v14, 16, v13
	v_pk_add_f32 v[14:15], v[20:21], v[14:15] neg_lo:[0,1] neg_hi:[0,1]
	v_pk_mul_f32 v[24:25], v[10:11], v[10:11]
	v_cvt_pk_bf16_f32 v17, v14, v15
	v_cvt_pk_bf16_f32 v14, v8, v9
	v_and_b32_e32 v19, 0xffff0000, v14
	v_lshlrev_b32_e32 v18, 16, v14
	v_pk_add_f32 v[18:19], v[8:9], v[18:19] neg_lo:[0,1] neg_hi:[0,1]
	v_pk_mul_f32 v[8:9], v[8:9], v[8:9]
	v_pk_fma_f32 v[20:21], v[20:21], v[20:21], v[24:25]
	v_pk_fma_f32 v[8:9], v[22:23], v[22:23], v[8:9]
	v_cvt_pk_bf16_f32 v18, v18, v19
	v_add_f32_e32 v8, v8, v9
	v_add_f32_e32 v8, v20, v8
	v_add_f32_e32 v19, v21, v8
	v_mov_b32_e32 v201, v19
	v_cvt_pk_bf16_f32 v15, v10, v11
	v_and_b32_e32 v9, 0xffff0000, v15
	v_lshlrev_b32_e32 v8, 16, v15
	v_pk_add_f32 v[8:9], v[10:11], v[8:9] neg_lo:[0,1] neg_hi:[0,1]
	s_waitcnt lgkmcnt(0)
	v_cvt_pk_bf16_f32 v19, v8, v9
	v_lshl_add_u64 v[8:9], v[132:133], 2, s[16:17]
	global_store_dwordx4 v[128:129], v[12:15], off
	global_store_dwordx4 v[134:135], v[16:19], off
.LBB0_3649:
	v_lshlrev_b32_e32 v10, 16, v64
	s_waitcnt lgkmcnt(0)
	v_and_b32_e32 v11, 0xffff0000, v64
	s_waitcnt vmcnt(10)
	v_lshlrev_b32_e32 v12, 16, v76
	v_and_b32_e32 v13, 0xffff0000, v76
	v_pk_add_f32 v[10:11], v[10:11], v[12:13]
	v_lshlrev_b32_e32 v12, 16, v65
	v_and_b32_e32 v13, 0xffff0000, v65
	v_lshlrev_b32_e32 v14, 16, v77
	v_and_b32_e32 v15, 0xffff0000, v77
	v_pk_add_f32 v[12:13], v[12:13], v[14:15]
	v_lshlrev_b32_e32 v14, 16, v79
	v_pk_fma_f32 v[6:7], v[6:7], 0.5, v[12:13] op_sel_hi:[1,0,1]
	v_pk_fma_f32 v[12:13], v[4:5], 0.5, v[10:11] op_sel_hi:[1,0,1]
	v_lshlrev_b32_e32 v4, 16, v66
	v_and_b32_e32 v5, 0xffff0000, v66
	v_lshlrev_b32_e32 v10, 16, v78
	v_and_b32_e32 v11, 0xffff0000, v78
	v_pk_add_f32 v[4:5], v[4:5], v[10:11]
	v_lshlrev_b32_e32 v10, 16, v67
	v_and_b32_e32 v11, 0xffff0000, v67
	v_and_b32_e32 v15, 0xffff0000, v79
	v_pk_add_f32 v[10:11], v[10:11], v[14:15]
	v_pk_fma_f32 v[0:1], v[0:1], 0.5, v[4:5] op_sel_hi:[1,0,1]
	v_pk_fma_f32 v[14:15], v[2:3], 0.5, v[10:11] op_sel_hi:[1,0,1]
	v_cvt_pk_bf16_f32 v2, v12, v13
	v_and_b32_e32 v5, 0xffff0000, v2
	v_lshlrev_b32_e32 v4, 16, v2
	v_pk_add_f32 v[4:5], v[12:13], v[4:5] neg_lo:[0,1] neg_hi:[0,1]
	v_cvt_pk_bf16_f32 v3, v6, v7
	v_cvt_pk_bf16_f32 v10, v4, v5
	v_and_b32_e32 v5, 0xffff0000, v3
	v_lshlrev_b32_e32 v4, 16, v3
	v_pk_add_f32 v[4:5], v[6:7], v[4:5] neg_lo:[0,1] neg_hi:[0,1]
	v_pk_mul_f32 v[18:19], v[14:15], v[14:15]
	v_cvt_pk_bf16_f32 v11, v4, v5
	v_cvt_pk_bf16_f32 v4, v0, v1
	v_and_b32_e32 v17, 0xffff0000, v4
	v_lshlrev_b32_e32 v16, 16, v4
	v_pk_add_f32 v[16:17], v[0:1], v[16:17] neg_lo:[0,1] neg_hi:[0,1]
	v_pk_mul_f32 v[0:1], v[0:1], v[0:1]
	v_pk_fma_f32 v[6:7], v[6:7], v[6:7], v[18:19]
	v_pk_fma_f32 v[0:1], v[12:13], v[12:13], v[0:1]
	v_cvt_pk_bf16_f32 v5, v14, v15
	v_add_f32_e32 v0, v0, v1
	v_add_f32_e32 v0, v6, v0
	v_add_f32_e32 v0, v7, v0
	v_add_f32_e32 v0, v201, v0
	ds_bpermute_b32 v1, v200, v0
	v_and_b32_e32 v7, 0xffff0000, v5
	v_lshlrev_b32_e32 v6, 16, v5
	v_pk_add_f32 v[6:7], v[14:15], v[6:7] neg_lo:[0,1] neg_hi:[0,1]
	v_cvt_pk_bf16_f32 v12, v16, v17
	s_waitcnt lgkmcnt(0)
	v_add_f32_e32 v0, v0, v1
	ds_bpermute_b32 v1, v199, v0
	v_cvt_pk_bf16_f32 v13, v6, v7
	global_store_dwordx4 v[128:129], v[2:5], off offset:256
	global_store_dwordx4 v[130:131], v[10:13], off
	s_and_saveexec_b64 s[18:19], vcc
	s_cbranch_execz .LBB0_3610
	s_waitcnt lgkmcnt(0)
	v_add_f32_e32 v0, v0, v1
	global_atomic_add_f32 v[8:9], v0, off
	s_branch .LBB0_3610
